# on top of no-setprio + peeled K-loops: LDS-DMA loads in SGPR-base form (no VALU address adds in the loading half), LDS read-address adds hoisted
# speedup vs baseline: 1.0149x; 1.0050x over previous
; #define PG8_STAGE(bufoff, gbase, voff) do { _Pragma("unroll") for (int _i = 0; _i < 2; ++_i) \
;         __builtin_amdgcn_global_load_lds((const unsigned*)((const char*)(gbase) + (voff)[_i]), (LAS unsigned*)(lds + (bufoff) + ldsw + _i * 8192), 16, 0, 0); } while (0)
; #define PG8_LDA(dst, b, h) do { _Pragma("unroll") for (int m = 0; m < 4; ++m) _Pragma("unroll") for (int k = 0; k < 2; ++k) dst[m][k] = *(const LAS bf16x8*)(lds + PG8_SA(b, h) + aoff + m * 2048 + k * 1024); } while (0)
; #define PG8_LDB(dst, b, h) do { _Pragma("unroll") for (int n = 0; n < 2; ++n) _Pragma("unroll") for (int k = 0; k < 2; ++k) dst[n][k] = *(const LAS bf16x8*)(lds + PG8_SB(b, h) + boff + n * 2048 + k * 1024); } while (0)
; #define PG8_WAIT_V(n) asm volatile("s_waitcnt vmcnt(" #n ")" ::: "memory")
; #define PG8_WAIT_L(n) asm volatile("s_waitcnt lgkmcnt(" #n ")" ::: "memory")
; #define PG8_BAR __builtin_amdgcn_s_barrier()
; __device__ __forceinline__ void gemm_phase(LAS unsigned char* lds, const Params& p, const bf16_t* gA, const bf16_t* gBt, const int gM, const int gN, const int gK, const int epi, const int perm, bf16_t* const Hp, const int goff, const float coef) {
;     ...
;         const bool has_next = S.next(ui + 1, nxt);
;         const char* nA = has_next ? (const char*)gA + (size_t)nxt.pm * tstep + (nxt.ks > 0 ? nxt.ks * ksl : 0) : cA; const char* nB = has_next ? (const char*)gBt + (size_t)nxt.pn * tstep + (nxt.ks > 0 ? nxt.ks * ksl : 0) : cB;
;         const int nt = cur.ks >= 0 ? ntf / 4 : ntf;
;         for (int t = 0; t < nt; t += 2) {
;             const bool last = (t == nt - 2);
;             const char* a1 = cA + (size_t)(t + 1) * kstep;
;             const char* a2 = last ? nA : cA + (size_t)(t + 2) * kstep; const char* b2 = last ? nB : cB + (size_t)(t + 2) * kstep;
;             const char* a3 = a2 + kstep; const char* b3 = b2 + kstep;
;             PG8_LDB(B0, 0, 0); PG8_LDB(B1, 0, 1); PG8_SCHED; PG8_LDA(At, 0, 0); PG8_STAGE(PG8_SA(1, 1), a1 + hstep, voffA);
;             PG8_WAIT_V(8); PG8_WAIT_L(0); PG8_BAR; PG8_MMA(0, 0, At, B0); PG8_MMA(0, 1, At, B1); PG8_BAR; PG8_SCHED;
;             PG8_LDA(At, 0, 1); PG8_STAGE(PG8_SB(0, 0), b2, voffB); PG8_STAGE(PG8_SB(0, 1), b2 + hstep, voffB); PG8_STAGE(PG8_SA(0, 0), a2, voffA);
;             PG8_WAIT_V(8); PG8_WAIT_L(0); PG8_BAR; PG8_MMA(1, 0, At, B0); PG8_MMA(1, 1, At, B1); PG8_BAR; PG8_SCHED;
.LBB0_169:
	s_ashr_i32 s25, s24, 31
	s_lshl_b64 s[30:31], s[24:25], 20
	s_add_u32 s25, s3, s30
	s_addc_u32 s27, s10, s31
	s_lshl_b64 s[30:31], s[0:1], 10
	s_cmp_gt_i32 s0, 0
	s_cselect_b32 s52, s30, 0
	s_cselect_b32 s51, s31, 0
	s_add_u32 s30, s25, s52
	s_addc_u32 s31, s27, s51
	s_and_b64 s[34:35], s[28:29], exec
	s_cselect_b32 s25, s31, s45
	s_cselect_b32 s50, s30, s44
	s_ashr_i32 s27, s26, 31
	s_lshl_b64 s[34:35], s[26:27], 20
	s_add_u32 s27, s74, s34
	s_addc_u32 s35, s75, s35
	s_add_u32 s34, s27, s52
	s_addc_u32 s35, s35, s51
	s_and_b64 s[52:53], s[28:29], exec
	s_cselect_b32 s27, s35, s47
	s_cselect_b32 s51, s34, s46
	s_cmp_gt_i32 s49, -1
	s_cselect_b32 s52, 8, 32
	s_add_i32 s53, s52, -2
	s_add_u32 s44, s44, 0x80080
	s_addc_u32 s45, s45, 0
	s_add_u32 s54, s46, 0x100
	s_mov_b32 s48, 0
	s_addc_u32 s55, s47, 0
	v_add_u32_e32 v222, 0x18000, v146
	v_add_u32_e32 v223, 0x1c000, v146
	ds_read_b128 v[158:161], v155
	ds_read_b128 v[162:165], v155 offset:1024
	ds_read_b128 v[166:169], v155 offset:2048
	ds_read_b128 v[170:173], v155 offset:3072
	ds_read_b128 v[174:177], v156
	ds_read_b128 v[178:181], v156 offset:1024
	ds_read_b128 v[182:185], v156 offset:2048
	ds_read_b128 v[186:189], v156 offset:3072
	s_add_i32 s56, s48, 2
	s_add_u32 s46, s44, 0xfff80080
	s_addc_u32 s47, s45, -1
	s_cmp_eq_u32 s53, s48
	s_cselect_b32 s48, s50, s46
	s_cselect_b32 s49, s25, s47
	s_cselect_b32 s47, s27, s55
	s_cselect_b32 s46, s51, s54
	s_add_i32 m0, s14, 0xc000
	ds_read_b128 v[190:193], v157
	ds_read_b128 v[194:197], v157 offset:1024
	ds_read_b128 v[198:201], v157 offset:2048
	ds_read_b128 v[202:205], v157 offset:3072
	ds_read_b128 v[206:209], v157 offset:4096
	ds_read_b128 v[210:213], v157 offset:5120
	ds_read_b128 v[214:217], v157 offset:6144
	ds_read_b128 v[218:221], v157 offset:7168
	global_load_lds_dwordx4 v136, s[44:45]
	s_add_i32 m0, s14, 0xe000
	s_nop 0
	global_load_lds_dwordx4 v138, s[44:45]
	s_waitcnt vmcnt(8)
	s_waitcnt lgkmcnt(0)
	s_barrier
	s_waitcnt lgkmcnt(0)
	v_mfma_f32_16x16x32_bf16 v[124:127], v[158:161], v[190:193], 0
	v_mfma_f32_16x16x32_bf16 v[120:123], v[166:169], v[190:193], 0
	v_mfma_f32_16x16x32_bf16 v[108:111], v[158:161], v[198:201], 0
	v_mfma_f32_16x16x32_bf16 v[104:107], v[166:169], v[198:201], 0
	v_mfma_f32_16x16x32_bf16 v[92:95], v[158:161], v[206:209], 0
	v_mfma_f32_16x16x32_bf16 v[88:91], v[166:169], v[206:209], 0
	v_mfma_f32_16x16x32_bf16 v[76:79], v[158:161], v[214:217], 0
	v_mfma_f32_16x16x32_bf16 v[72:75], v[166:169], v[214:217], 0
	v_mfma_f32_16x16x32_bf16 v[124:127], v[162:165], v[194:197], v[124:127]
	v_mfma_f32_16x16x32_bf16 v[120:123], v[170:173], v[194:197], v[120:123]
	v_mfma_f32_16x16x32_bf16 v[108:111], v[162:165], v[202:205], v[108:111]
	v_mfma_f32_16x16x32_bf16 v[104:107], v[170:173], v[202:205], v[104:107]
	v_mfma_f32_16x16x32_bf16 v[92:95], v[162:165], v[210:213], v[92:95]
	v_mfma_f32_16x16x32_bf16 v[88:91], v[170:173], v[210:213], v[88:91]
	v_mfma_f32_16x16x32_bf16 v[76:79], v[162:165], v[218:221], v[76:79]
	v_mfma_f32_16x16x32_bf16 v[72:75], v[170:173], v[218:221], v[72:75]
	v_mfma_f32_16x16x32_bf16 v[116:119], v[174:177], v[190:193], 0
	v_mfma_f32_16x16x32_bf16 v[112:115], v[182:185], v[190:193], 0
	v_mfma_f32_16x16x32_bf16 v[100:103], v[174:177], v[198:201], 0
	v_mfma_f32_16x16x32_bf16 v[96:99], v[182:185], v[198:201], 0
	v_mfma_f32_16x16x32_bf16 v[84:87], v[174:177], v[206:209], 0
	v_mfma_f32_16x16x32_bf16 v[80:83], v[182:185], v[206:209], 0
	v_mfma_f32_16x16x32_bf16 v[68:71], v[174:177], v[214:217], 0
	v_mfma_f32_16x16x32_bf16 v[64:67], v[182:185], v[214:217], 0
	v_mfma_f32_16x16x32_bf16 v[116:119], v[178:181], v[194:197], v[116:119]
	v_mfma_f32_16x16x32_bf16 v[112:115], v[186:189], v[194:197], v[112:115]
	v_mfma_f32_16x16x32_bf16 v[100:103], v[178:181], v[202:205], v[100:103]
	v_mfma_f32_16x16x32_bf16 v[96:99], v[186:189], v[202:205], v[96:99]
	v_mfma_f32_16x16x32_bf16 v[84:87], v[178:181], v[210:213], v[84:87]
	v_mfma_f32_16x16x32_bf16 v[80:83], v[186:189], v[210:213], v[80:83]
	v_mfma_f32_16x16x32_bf16 v[68:71], v[178:181], v[218:221], v[68:71]
	v_mfma_f32_16x16x32_bf16 v[64:67], v[186:189], v[218:221], v[64:67]
	s_barrier
	s_add_i32 s57, s23, s11
	s_mov_b32 m0, s57
	ds_read_b128 v[190:193], v157 offset:16384
	ds_read_b128 v[194:197], v157 offset:17408
	ds_read_b128 v[198:201], v157 offset:18432
	ds_read_b128 v[202:205], v157 offset:19456
	ds_read_b128 v[206:209], v157 offset:20480
	ds_read_b128 v[210:213], v157 offset:21504
	ds_read_b128 v[214:217], v157 offset:22528
	ds_read_b128 v[218:221], v157 offset:23552
	global_load_lds_dwordx4 v130, s[46:47]
	s_add_i32 m0, s57, 0x2000
	s_add_u32 s58, s46, 0x80000
	s_addc_u32 s59, s47, 0
	s_add_i32 s57, s33, s11
	global_load_lds_dwordx4 v134, s[46:47]
	s_mov_b32 m0, s57
	s_nop 0
	global_load_lds_dwordx4 v130, s[58:59]
	s_add_i32 m0, s57, 0x2000
	s_nop 0
	global_load_lds_dwordx4 v134, s[58:59]
	s_mov_b32 m0, s14
	s_nop 0
	global_load_lds_dwordx4 v128, s[48:49]
	s_mov_b32 m0, s15
	s_nop 0
	global_load_lds_dwordx4 v132, s[48:49]
	s_waitcnt vmcnt(8)
	s_waitcnt lgkmcnt(0)
	s_barrier
; #define PG8_STAGE(bufoff, gbase, voff) do { _Pragma("unroll") for (int _i = 0; _i < 2; ++_i) \
;         __builtin_amdgcn_global_load_lds((const unsigned*)((const char*)(gbase) + (voff)[_i]), (LAS unsigned*)(lds + (bufoff) + ldsw + _i * 8192), 16, 0, 0); } while (0)
; #define PG8_LDA(dst, b, h) do { _Pragma("unroll") for (int m = 0; m < 4; ++m) _Pragma("unroll") for (int k = 0; k < 2; ++k) dst[m][k] = *(const LAS bf16x8*)(lds + PG8_SA(b, h) + aoff + m * 2048 + k * 1024); } while (0)
; #define PG8_LDB(dst, b, h) do { _Pragma("unroll") for (int n = 0; n < 2; ++n) _Pragma("unroll") for (int k = 0; k < 2; ++k) dst[n][k] = *(const LAS bf16x8*)(lds + PG8_SB(b, h) + boff + n * 2048 + k * 1024); } while (0)
; #define PG8_MMA(ai, bj, At, Bt) do { __builtin_amdgcn_s_setprio(1); _Pragma("unroll") for (int m = 0; m < 4; ++m) _Pragma("unroll") for (int n = 0; n < 2; ++n) _Pragma("unroll") for (int k = 0; k < 2; ++k) \
;         acc[ai][bj][m][n] = __builtin_amdgcn_mfma_f32_16x16x32_bf16(Bt[n][k], At[m][k], acc[ai][bj][m][n], 0, 0, 0); __builtin_amdgcn_s_setprio(0); } while (0)
; #define PG8_WAIT_V(n) asm volatile("s_waitcnt vmcnt(" #n ")" ::: "memory")
; #define PG8_WAIT_L(n) asm volatile("s_waitcnt lgkmcnt(" #n ")" ::: "memory")
; #define PG8_BAR __builtin_amdgcn_s_barrier()
; #define PG8_SCHED __builtin_amdgcn_sched_barrier(0)
; __device__ __forceinline__ void gemm_phase(LAS unsigned char* lds, const Params& p, const bf16_t* gA, const bf16_t* gBt, const int gM, const int gN, const int gK, const int epi, const int perm, bf16_t* const Hp, const int goff, const float coef) {
;     ...
;             PG8_WAIT_V(8); PG8_WAIT_L(0); PG8_BAR; PG8_MMA(1, 0, At, B0); PG8_MMA(1, 1, At, B1); PG8_BAR; PG8_SCHED;
;             PG8_LDB(B0, 1, 0); PG8_LDB(B1, 1, 1); PG8_SCHED; PG8_LDA(At, 1, 0); PG8_STAGE(PG8_SA(0, 1), a2 + hstep, voffA);
;             PG8_WAIT_V(8); PG8_WAIT_L(0); PG8_BAR; PG8_MMA(0, 0, At, B0); PG8_MMA(0, 1, At, B1); PG8_BAR; PG8_SCHED;
	s_waitcnt lgkmcnt(0)
	v_mfma_f32_16x16x32_bf16 v[60:63], v[158:161], v[190:193], 0
	v_mfma_f32_16x16x32_bf16 v[56:59], v[166:169], v[190:193], 0
	v_mfma_f32_16x16x32_bf16 v[44:47], v[158:161], v[198:201], 0
	v_mfma_f32_16x16x32_bf16 v[40:43], v[166:169], v[198:201], 0
	v_mfma_f32_16x16x32_bf16 v[28:31], v[158:161], v[206:209], 0
	v_mfma_f32_16x16x32_bf16 v[24:27], v[166:169], v[206:209], 0
	v_mfma_f32_16x16x32_bf16 v[12:15], v[158:161], v[214:217], 0
	v_mfma_f32_16x16x32_bf16 v[8:11], v[166:169], v[214:217], 0
	v_mfma_f32_16x16x32_bf16 v[60:63], v[162:165], v[194:197], v[60:63]
	v_mfma_f32_16x16x32_bf16 v[56:59], v[170:173], v[194:197], v[56:59]
	v_mfma_f32_16x16x32_bf16 v[44:47], v[162:165], v[202:205], v[44:47]
	v_mfma_f32_16x16x32_bf16 v[40:43], v[170:173], v[202:205], v[40:43]
	v_mfma_f32_16x16x32_bf16 v[28:31], v[162:165], v[210:213], v[28:31]
	v_mfma_f32_16x16x32_bf16 v[24:27], v[170:173], v[210:213], v[24:27]
	v_mfma_f32_16x16x32_bf16 v[12:15], v[162:165], v[218:221], v[12:15]
	v_mfma_f32_16x16x32_bf16 v[8:11], v[170:173], v[218:221], v[8:11]
	v_mfma_f32_16x16x32_bf16 v[52:55], v[174:177], v[190:193], 0
	v_mfma_f32_16x16x32_bf16 v[48:51], v[182:185], v[190:193], 0
	v_mfma_f32_16x16x32_bf16 v[36:39], v[174:177], v[198:201], 0
	v_mfma_f32_16x16x32_bf16 v[32:35], v[182:185], v[198:201], 0
	v_mfma_f32_16x16x32_bf16 v[20:23], v[174:177], v[206:209], 0
	v_mfma_f32_16x16x32_bf16 v[16:19], v[182:185], v[206:209], 0
	v_mfma_f32_16x16x32_bf16 v[4:7], v[174:177], v[214:217], 0
	v_mfma_f32_16x16x32_bf16 v[0:3], v[182:185], v[214:217], 0
	v_mfma_f32_16x16x32_bf16 v[52:55], v[178:181], v[194:197], v[52:55]
	v_mfma_f32_16x16x32_bf16 v[48:51], v[186:189], v[194:197], v[48:51]
	v_mfma_f32_16x16x32_bf16 v[36:39], v[178:181], v[202:205], v[36:39]
	v_mfma_f32_16x16x32_bf16 v[32:35], v[186:189], v[202:205], v[32:35]
	v_mfma_f32_16x16x32_bf16 v[20:23], v[178:181], v[210:213], v[20:23]
	v_mfma_f32_16x16x32_bf16 v[16:19], v[186:189], v[210:213], v[16:19]
	v_mfma_f32_16x16x32_bf16 v[4:7], v[178:181], v[218:221], v[4:7]
	v_mfma_f32_16x16x32_bf16 v[0:3], v[186:189], v[218:221], v[0:3]
	s_barrier
	s_add_i32 s57, 0, 0x18000
	s_add_i32 s58, 0, 0x1c000
	ds_read_b128 v[158:161], v222
	ds_read_b128 v[162:165], v222 offset:1024
	ds_read_b128 v[166:169], v222 offset:2048
	ds_read_b128 v[170:173], v222 offset:3072
	ds_read_b128 v[174:177], v223
	ds_read_b128 v[178:181], v223 offset:1024
	ds_read_b128 v[182:185], v223 offset:2048
	ds_read_b128 v[186:189], v223 offset:3072
	s_add_u32 s48, s48, 0x80000
	s_addc_u32 s49, s49, 0
	s_mov_b32 m0, s16
	ds_read_b128 v[190:193], v157 offset:32768
	ds_read_b128 v[194:197], v157 offset:33792
	ds_read_b128 v[198:201], v157 offset:34816
	ds_read_b128 v[202:205], v157 offset:35840
	ds_read_b128 v[206:209], v157 offset:36864
	ds_read_b128 v[210:213], v157 offset:37888
	ds_read_b128 v[214:217], v157 offset:38912
	ds_read_b128 v[218:221], v157 offset:39936
	global_load_lds_dwordx4 v128, s[48:49]
	s_mov_b32 m0, s17
	s_nop 0
	global_load_lds_dwordx4 v132, s[48:49]
	s_waitcnt vmcnt(8)
	s_waitcnt lgkmcnt(0)
	s_barrier
	s_waitcnt lgkmcnt(0)
	v_mfma_f32_16x16x32_bf16 v[124:127], v[158:161], v[190:193], v[124:127]
	v_mfma_f32_16x16x32_bf16 v[120:123], v[166:169], v[190:193], v[120:123]
	v_mfma_f32_16x16x32_bf16 v[108:111], v[158:161], v[198:201], v[108:111]
	v_mfma_f32_16x16x32_bf16 v[104:107], v[166:169], v[198:201], v[104:107]
	v_mfma_f32_16x16x32_bf16 v[92:95], v[158:161], v[206:209], v[92:95]
	v_mfma_f32_16x16x32_bf16 v[88:91], v[166:169], v[206:209], v[88:91]
	v_mfma_f32_16x16x32_bf16 v[76:79], v[158:161], v[214:217], v[76:79]
	v_mfma_f32_16x16x32_bf16 v[72:75], v[166:169], v[214:217], v[72:75]
	v_mfma_f32_16x16x32_bf16 v[124:127], v[162:165], v[194:197], v[124:127]
	v_mfma_f32_16x16x32_bf16 v[120:123], v[170:173], v[194:197], v[120:123]
	v_mfma_f32_16x16x32_bf16 v[108:111], v[162:165], v[202:205], v[108:111]
	v_mfma_f32_16x16x32_bf16 v[104:107], v[170:173], v[202:205], v[104:107]
	v_mfma_f32_16x16x32_bf16 v[92:95], v[162:165], v[210:213], v[92:95]
	v_mfma_f32_16x16x32_bf16 v[88:91], v[170:173], v[210:213], v[88:91]
	v_mfma_f32_16x16x32_bf16 v[76:79], v[162:165], v[218:221], v[76:79]
	v_mfma_f32_16x16x32_bf16 v[72:75], v[170:173], v[218:221], v[72:75]
	v_mfma_f32_16x16x32_bf16 v[116:119], v[174:177], v[190:193], v[116:119]
	v_mfma_f32_16x16x32_bf16 v[112:115], v[182:185], v[190:193], v[112:115]
	v_mfma_f32_16x16x32_bf16 v[100:103], v[174:177], v[198:201], v[100:103]
	v_mfma_f32_16x16x32_bf16 v[96:99], v[182:185], v[198:201], v[96:99]
	v_mfma_f32_16x16x32_bf16 v[84:87], v[174:177], v[206:209], v[84:87]
	v_mfma_f32_16x16x32_bf16 v[80:83], v[182:185], v[206:209], v[80:83]
	v_mfma_f32_16x16x32_bf16 v[68:71], v[174:177], v[214:217], v[68:71]
	v_mfma_f32_16x16x32_bf16 v[64:67], v[182:185], v[214:217], v[64:67]
	v_mfma_f32_16x16x32_bf16 v[116:119], v[178:181], v[194:197], v[116:119]
	v_mfma_f32_16x16x32_bf16 v[112:115], v[186:189], v[194:197], v[112:115]
	v_mfma_f32_16x16x32_bf16 v[100:103], v[178:181], v[202:205], v[100:103]
	v_mfma_f32_16x16x32_bf16 v[96:99], v[186:189], v[202:205], v[96:99]
	v_mfma_f32_16x16x32_bf16 v[84:87], v[178:181], v[210:213], v[84:87]
	v_mfma_f32_16x16x32_bf16 v[80:83], v[186:189], v[210:213], v[80:83]
	v_mfma_f32_16x16x32_bf16 v[68:71], v[178:181], v[218:221], v[68:71]
	v_mfma_f32_16x16x32_bf16 v[64:67], v[186:189], v[218:221], v[64:67]
	s_barrier
; #define PG8_STAGE(bufoff, gbase, voff) do { _Pragma("unroll") for (int _i = 0; _i < 2; ++_i) \
;         __builtin_amdgcn_global_load_lds((const unsigned*)((const char*)(gbase) + (voff)[_i]), (LAS unsigned*)(lds + (bufoff) + ldsw + _i * 8192), 16, 0, 0); } while (0)
; #define PG8_LDA(dst, b, h) do { _Pragma("unroll") for (int m = 0; m < 4; ++m) _Pragma("unroll") for (int k = 0; k < 2; ++k) dst[m][k] = *(const LAS bf16x8*)(lds + PG8_SA(b, h) + aoff + m * 2048 + k * 1024); } while (0)
; #define PG8_LDB(dst, b, h) do { _Pragma("unroll") for (int n = 0; n < 2; ++n) _Pragma("unroll") for (int k = 0; k < 2; ++k) dst[n][k] = *(const LAS bf16x8*)(lds + PG8_SB(b, h) + boff + n * 2048 + k * 1024); } while (0)
; #define PG8_MMA(ai, bj, At, Bt) do { __builtin_amdgcn_s_setprio(1); _Pragma("unroll") for (int m = 0; m < 4; ++m) _Pragma("unroll") for (int n = 0; n < 2; ++n) _Pragma("unroll") for (int k = 0; k < 2; ++k) \
;         acc[ai][bj][m][n] = __builtin_amdgcn_mfma_f32_16x16x32_bf16(Bt[n][k], At[m][k], acc[ai][bj][m][n], 0, 0, 0); __builtin_amdgcn_s_setprio(0); } while (0)
; __device__ __forceinline__ void gemm_phase(LAS unsigned char* lds, const Params& p, const bf16_t* gA, const bf16_t* gBt, const int gM, const int gN, const int gK, const int epi, const int perm, bf16_t* const Hp, const int goff, const float coef) {
;     ...
;             PG8_LDB(B0, 0, 0); PG8_LDB(B1, 0, 1); PG8_SCHED; PG8_LDA(At, 0, 0); PG8_STAGE(PG8_SA(1, 1), a1 + hstep, voffA);
;             PG8_WAIT_V(8); PG8_WAIT_L(0); PG8_BAR; PG8_MMA(0, 0, At, B0); PG8_MMA(0, 1, At, B1); PG8_BAR; PG8_SCHED;
;             PG8_LDA(At, 0, 1); PG8_STAGE(PG8_SB(0, 0), b2, voffB); PG8_STAGE(PG8_SB(0, 1), b2 + hstep, voffB); PG8_STAGE(PG8_SA(0, 0), a2, voffA);
;             PG8_WAIT_V(8); PG8_WAIT_L(0); PG8_BAR; PG8_MMA(1, 0, At, B0); PG8_MMA(1, 1, At, B1); PG8_BAR; PG8_SCHED;
;             PG8_LDB(B0, 1, 0); PG8_LDB(B1, 1, 1); PG8_SCHED; PG8_LDA(At, 1, 0); PG8_STAGE(PG8_SA(0, 1), a2 + hstep, voffA);
;             PG8_WAIT_V(8); PG8_WAIT_L(0); PG8_BAR; PG8_MMA(0, 0, At, B0); PG8_MMA(0, 1, At, B1); PG8_BAR; PG8_SCHED;
;             PG8_LDA(At, 1, 1); PG8_STAGE(PG8_SB(1, 0), b3, voffB); PG8_STAGE(PG8_SB(1, 1), b3 + hstep, voffB); PG8_STAGE(PG8_SA(1, 0), a3, voffA);
;             PG8_WAIT_V(8); PG8_WAIT_L(0); PG8_BAR; PG8_MMA(1, 0, At, B0); PG8_MMA(1, 1, At, B1); PG8_BAR; PG8_SCHED;
	s_mov_b64 s[98:99], s[48:49]
	s_add_i32 s48, s57, s11
	s_mov_b32 m0, s48
	ds_read_b128 v[190:193], v157 offset:49152
	ds_read_b128 v[194:197], v157 offset:50176
	ds_read_b128 v[198:201], v157 offset:51200
	ds_read_b128 v[202:205], v157 offset:52224
	ds_read_b128 v[206:209], v157 offset:53248
	ds_read_b128 v[210:213], v157 offset:54272
	ds_read_b128 v[214:217], v157 offset:55296
	ds_read_b128 v[218:221], v157 offset:56320
	s_add_u32 s100, s46, 0x80
	s_addc_u32 s101, s47, 0
	global_load_lds_dwordx4 v130, s[100:101]
	s_add_i32 m0, s48, 0x2000
	s_add_u32 s46, s46, 0x80080
	s_addc_u32 s47, s47, 0
	s_add_i32 s48, s58, s11
	global_load_lds_dwordx4 v134, s[100:101]
	s_mov_b32 m0, s48
	s_nop 0
	global_load_lds_dwordx4 v130, s[46:47]
	s_add_i32 m0, s48, 0x2000
	s_nop 0
	global_load_lds_dwordx4 v134, s[46:47]
	s_mov_b32 m0, s19
	s_nop 0
	s_add_u32 s100, s98, 0xfff80080
	s_addc_u32 s101, s99, -1
	global_load_lds_dwordx4 v128, s[100:101]
	s_mov_b32 m0, s20
	s_nop 0
	global_load_lds_dwordx4 v132, s[100:101]
	s_waitcnt vmcnt(8)
	s_waitcnt lgkmcnt(0)
	s_barrier
	s_waitcnt lgkmcnt(0)
	v_mfma_f32_16x16x32_bf16 v[60:63], v[158:161], v[190:193], v[60:63]
	v_mfma_f32_16x16x32_bf16 v[56:59], v[166:169], v[190:193], v[56:59]
	v_mfma_f32_16x16x32_bf16 v[44:47], v[158:161], v[198:201], v[44:47]
	v_mfma_f32_16x16x32_bf16 v[40:43], v[166:169], v[198:201], v[40:43]
	v_mfma_f32_16x16x32_bf16 v[28:31], v[158:161], v[206:209], v[28:31]
	v_mfma_f32_16x16x32_bf16 v[24:27], v[166:169], v[206:209], v[24:27]
	v_mfma_f32_16x16x32_bf16 v[12:15], v[158:161], v[214:217], v[12:15]
	v_mfma_f32_16x16x32_bf16 v[8:11], v[166:169], v[214:217], v[8:11]
	v_mfma_f32_16x16x32_bf16 v[60:63], v[162:165], v[194:197], v[60:63]
	v_mfma_f32_16x16x32_bf16 v[56:59], v[170:173], v[194:197], v[56:59]
	v_mfma_f32_16x16x32_bf16 v[44:47], v[162:165], v[202:205], v[44:47]
	v_mfma_f32_16x16x32_bf16 v[40:43], v[170:173], v[202:205], v[40:43]
	v_mfma_f32_16x16x32_bf16 v[28:31], v[162:165], v[210:213], v[28:31]
	v_mfma_f32_16x16x32_bf16 v[24:27], v[170:173], v[210:213], v[24:27]
	v_mfma_f32_16x16x32_bf16 v[12:15], v[162:165], v[218:221], v[12:15]
	v_mfma_f32_16x16x32_bf16 v[8:11], v[170:173], v[218:221], v[8:11]
	v_mfma_f32_16x16x32_bf16 v[52:55], v[174:177], v[190:193], v[52:55]
	v_mfma_f32_16x16x32_bf16 v[48:51], v[182:185], v[190:193], v[48:51]
	v_mfma_f32_16x16x32_bf16 v[36:39], v[174:177], v[198:201], v[36:39]
	v_mfma_f32_16x16x32_bf16 v[32:35], v[182:185], v[198:201], v[32:35]
	v_mfma_f32_16x16x32_bf16 v[20:23], v[174:177], v[206:209], v[20:23]
	v_mfma_f32_16x16x32_bf16 v[16:19], v[182:185], v[206:209], v[16:19]
	v_mfma_f32_16x16x32_bf16 v[4:7], v[174:177], v[214:217], v[4:7]
	v_mfma_f32_16x16x32_bf16 v[0:3], v[182:185], v[214:217], v[0:3]
	v_mfma_f32_16x16x32_bf16 v[52:55], v[178:181], v[194:197], v[52:55]
	v_mfma_f32_16x16x32_bf16 v[48:51], v[186:189], v[194:197], v[48:51]
	v_mfma_f32_16x16x32_bf16 v[36:39], v[178:181], v[202:205], v[36:39]
	v_mfma_f32_16x16x32_bf16 v[32:35], v[186:189], v[202:205], v[32:35]
	v_mfma_f32_16x16x32_bf16 v[20:23], v[178:181], v[210:213], v[20:23]
	v_mfma_f32_16x16x32_bf16 v[16:19], v[186:189], v[210:213], v[16:19]
	v_mfma_f32_16x16x32_bf16 v[4:7], v[178:181], v[218:221], v[4:7]
	v_mfma_f32_16x16x32_bf16 v[0:3], v[186:189], v[218:221], v[0:3]
	s_barrier
	s_add_u32 s44, s44, 0x100
	s_addc_u32 s45, s45, 0
	s_add_u32 s54, s54, 0x100
	s_addc_u32 s55, s55, 0
	s_cmp_ge_u32 s56, s52
	s_mov_b32 s48, s56
	s_cbranch_scc1 .Lpeel_exit_0
.LBB0_170:
	ds_read_b128 v[158:161], v155
	ds_read_b128 v[162:165], v155 offset:1024
	ds_read_b128 v[166:169], v155 offset:2048
	ds_read_b128 v[170:173], v155 offset:3072
	ds_read_b128 v[174:177], v156
	ds_read_b128 v[178:181], v156 offset:1024
	ds_read_b128 v[182:185], v156 offset:2048
	ds_read_b128 v[186:189], v156 offset:3072
	s_add_i32 s56, s48, 2
	s_add_u32 s46, s44, 0xfff80080
	s_addc_u32 s47, s45, -1
	s_cmp_eq_u32 s53, s48
	s_cselect_b32 s48, s50, s46
	s_cselect_b32 s49, s25, s47
	s_cselect_b32 s47, s27, s55
	s_cselect_b32 s46, s51, s54
	s_add_i32 m0, s14, 0xc000
	ds_read_b128 v[190:193], v157
	ds_read_b128 v[194:197], v157 offset:1024
	ds_read_b128 v[198:201], v157 offset:2048
	ds_read_b128 v[202:205], v157 offset:3072
	ds_read_b128 v[206:209], v157 offset:4096
	ds_read_b128 v[210:213], v157 offset:5120
	ds_read_b128 v[214:217], v157 offset:6144
	ds_read_b128 v[218:221], v157 offset:7168
	global_load_lds_dwordx4 v136, s[44:45]
	s_add_i32 m0, s14, 0xe000
	s_nop 0
	global_load_lds_dwordx4 v138, s[44:45]
	s_waitcnt vmcnt(8)
	s_waitcnt lgkmcnt(0)
	s_barrier
; #define PG8_STAGE(bufoff, gbase, voff) do { _Pragma("unroll") for (int _i = 0; _i < 2; ++_i) \
;         __builtin_amdgcn_global_load_lds((const unsigned*)((const char*)(gbase) + (voff)[_i]), (LAS unsigned*)(lds + (bufoff) + ldsw + _i * 8192), 16, 0, 0); } while (0)
; #define PG8_LDA(dst, b, h) do { _Pragma("unroll") for (int m = 0; m < 4; ++m) _Pragma("unroll") for (int k = 0; k < 2; ++k) dst[m][k] = *(const LAS bf16x8*)(lds + PG8_SA(b, h) + aoff + m * 2048 + k * 1024); } while (0)
; #define PG8_LDB(dst, b, h) do { _Pragma("unroll") for (int n = 0; n < 2; ++n) _Pragma("unroll") for (int k = 0; k < 2; ++k) dst[n][k] = *(const LAS bf16x8*)(lds + PG8_SB(b, h) + boff + n * 2048 + k * 1024); } while (0)
; #define PG8_BAR __builtin_amdgcn_s_barrier()
; __device__ __forceinline__ void gemm_phase(LAS unsigned char* lds, const Params& p, const bf16_t* gA, const bf16_t* gBt, const int gM, const int gN, const int gK, const int epi, const int perm, bf16_t* const Hp, const int goff, const float coef) {
;     ...
;         for (int t = 0; t < nt; t += 2) {
;             const bool last = (t == nt - 2);
;             const char* a1 = cA + (size_t)(t + 1) * kstep;
;             const char* a2 = last ? nA : cA + (size_t)(t + 2) * kstep; const char* b2 = last ? nB : cB + (size_t)(t + 2) * kstep;
;             const char* a3 = a2 + kstep; const char* b3 = b2 + kstep;
;             PG8_LDB(B0, 0, 0); PG8_LDB(B1, 0, 1); PG8_SCHED; PG8_LDA(At, 0, 0); PG8_STAGE(PG8_SA(1, 1), a1 + hstep, voffA);
;             PG8_WAIT_V(8); PG8_WAIT_L(0); PG8_BAR; PG8_MMA(0, 0, At, B0); PG8_MMA(0, 1, At, B1); PG8_BAR; PG8_SCHED;
;             PG8_LDA(At, 0, 1); PG8_STAGE(PG8_SB(0, 0), b2, voffB); PG8_STAGE(PG8_SB(0, 1), b2 + hstep, voffB); PG8_STAGE(PG8_SA(0, 0), a2, voffA);
;             PG8_WAIT_V(8); PG8_WAIT_L(0); PG8_BAR; PG8_MMA(1, 0, At, B0); PG8_MMA(1, 1, At, B1); PG8_BAR; PG8_SCHED;
;             PG8_LDB(B0, 1, 0); PG8_LDB(B1, 1, 1); PG8_SCHED; PG8_LDA(At, 1, 0); PG8_STAGE(PG8_SA(0, 1), a2 + hstep, voffA);
;             PG8_WAIT_V(8); PG8_WAIT_L(0); PG8_BAR; PG8_MMA(0, 0, At, B0); PG8_MMA(0, 1, At, B1); PG8_BAR; PG8_SCHED;
;             PG8_LDA(At, 1, 1); PG8_STAGE(PG8_SB(1, 0), b3, voffB); PG8_STAGE(PG8_SB(1, 1), b3 + hstep, voffB); PG8_STAGE(PG8_SA(1, 0), a3, voffA);
;             PG8_WAIT_V(8); PG8_WAIT_L(0); PG8_BAR; PG8_MMA(1, 0, At, B0); PG8_MMA(1, 1, At, B1); PG8_BAR; PG8_SCHED;
	s_waitcnt lgkmcnt(0)
	v_mfma_f32_16x16x32_bf16 v[124:127], v[158:161], v[190:193], v[124:127]
	v_mfma_f32_16x16x32_bf16 v[120:123], v[166:169], v[190:193], v[120:123]
	v_mfma_f32_16x16x32_bf16 v[108:111], v[158:161], v[198:201], v[108:111]
	v_mfma_f32_16x16x32_bf16 v[104:107], v[166:169], v[198:201], v[104:107]
	v_mfma_f32_16x16x32_bf16 v[92:95], v[158:161], v[206:209], v[92:95]
	v_mfma_f32_16x16x32_bf16 v[88:91], v[166:169], v[206:209], v[88:91]
	v_mfma_f32_16x16x32_bf16 v[76:79], v[158:161], v[214:217], v[76:79]
	v_mfma_f32_16x16x32_bf16 v[72:75], v[166:169], v[214:217], v[72:75]
	v_mfma_f32_16x16x32_bf16 v[124:127], v[162:165], v[194:197], v[124:127]
	v_mfma_f32_16x16x32_bf16 v[120:123], v[170:173], v[194:197], v[120:123]
	v_mfma_f32_16x16x32_bf16 v[108:111], v[162:165], v[202:205], v[108:111]
	v_mfma_f32_16x16x32_bf16 v[104:107], v[170:173], v[202:205], v[104:107]
	v_mfma_f32_16x16x32_bf16 v[92:95], v[162:165], v[210:213], v[92:95]
	v_mfma_f32_16x16x32_bf16 v[88:91], v[170:173], v[210:213], v[88:91]
	v_mfma_f32_16x16x32_bf16 v[76:79], v[162:165], v[218:221], v[76:79]
	v_mfma_f32_16x16x32_bf16 v[72:75], v[170:173], v[218:221], v[72:75]
	v_mfma_f32_16x16x32_bf16 v[116:119], v[174:177], v[190:193], v[116:119]
	v_mfma_f32_16x16x32_bf16 v[112:115], v[182:185], v[190:193], v[112:115]
	v_mfma_f32_16x16x32_bf16 v[100:103], v[174:177], v[198:201], v[100:103]
	v_mfma_f32_16x16x32_bf16 v[96:99], v[182:185], v[198:201], v[96:99]
	v_mfma_f32_16x16x32_bf16 v[84:87], v[174:177], v[206:209], v[84:87]
	v_mfma_f32_16x16x32_bf16 v[80:83], v[182:185], v[206:209], v[80:83]
	v_mfma_f32_16x16x32_bf16 v[68:71], v[174:177], v[214:217], v[68:71]
	v_mfma_f32_16x16x32_bf16 v[64:67], v[182:185], v[214:217], v[64:67]
	v_mfma_f32_16x16x32_bf16 v[116:119], v[178:181], v[194:197], v[116:119]
	v_mfma_f32_16x16x32_bf16 v[112:115], v[186:189], v[194:197], v[112:115]
	v_mfma_f32_16x16x32_bf16 v[100:103], v[178:181], v[202:205], v[100:103]
	v_mfma_f32_16x16x32_bf16 v[96:99], v[186:189], v[202:205], v[96:99]
	v_mfma_f32_16x16x32_bf16 v[84:87], v[178:181], v[210:213], v[84:87]
	v_mfma_f32_16x16x32_bf16 v[80:83], v[186:189], v[210:213], v[80:83]
	v_mfma_f32_16x16x32_bf16 v[68:71], v[178:181], v[218:221], v[68:71]
	v_mfma_f32_16x16x32_bf16 v[64:67], v[186:189], v[218:221], v[64:67]
	s_barrier
	s_add_i32 s57, s23, s11
	s_mov_b32 m0, s57
	ds_read_b128 v[190:193], v157 offset:16384
	ds_read_b128 v[194:197], v157 offset:17408
	ds_read_b128 v[198:201], v157 offset:18432
	ds_read_b128 v[202:205], v157 offset:19456
	ds_read_b128 v[206:209], v157 offset:20480
	ds_read_b128 v[210:213], v157 offset:21504
	ds_read_b128 v[214:217], v157 offset:22528
	ds_read_b128 v[218:221], v157 offset:23552
	global_load_lds_dwordx4 v130, s[46:47]
	s_add_i32 m0, s57, 0x2000
	s_add_u32 s58, s46, 0x80000
	s_addc_u32 s59, s47, 0
	s_add_i32 s57, s33, s11
	global_load_lds_dwordx4 v134, s[46:47]
	s_mov_b32 m0, s57
	s_nop 0
	global_load_lds_dwordx4 v130, s[58:59]
	s_add_i32 m0, s57, 0x2000
	s_nop 0
	global_load_lds_dwordx4 v134, s[58:59]
	s_mov_b32 m0, s14
	s_nop 0
	global_load_lds_dwordx4 v128, s[48:49]
	s_mov_b32 m0, s15
	s_nop 0
	global_load_lds_dwordx4 v132, s[48:49]
	s_waitcnt vmcnt(8)
	s_waitcnt lgkmcnt(0)
	s_barrier
	s_waitcnt lgkmcnt(0)
	v_mfma_f32_16x16x32_bf16 v[60:63], v[158:161], v[190:193], v[60:63]
	v_mfma_f32_16x16x32_bf16 v[56:59], v[166:169], v[190:193], v[56:59]
	v_mfma_f32_16x16x32_bf16 v[44:47], v[158:161], v[198:201], v[44:47]
	v_mfma_f32_16x16x32_bf16 v[40:43], v[166:169], v[198:201], v[40:43]
	v_mfma_f32_16x16x32_bf16 v[28:31], v[158:161], v[206:209], v[28:31]
	v_mfma_f32_16x16x32_bf16 v[24:27], v[166:169], v[206:209], v[24:27]
	v_mfma_f32_16x16x32_bf16 v[12:15], v[158:161], v[214:217], v[12:15]
	v_mfma_f32_16x16x32_bf16 v[8:11], v[166:169], v[214:217], v[8:11]
	v_mfma_f32_16x16x32_bf16 v[60:63], v[162:165], v[194:197], v[60:63]
	v_mfma_f32_16x16x32_bf16 v[56:59], v[170:173], v[194:197], v[56:59]
	v_mfma_f32_16x16x32_bf16 v[44:47], v[162:165], v[202:205], v[44:47]
	v_mfma_f32_16x16x32_bf16 v[40:43], v[170:173], v[202:205], v[40:43]
	v_mfma_f32_16x16x32_bf16 v[28:31], v[162:165], v[210:213], v[28:31]
	v_mfma_f32_16x16x32_bf16 v[24:27], v[170:173], v[210:213], v[24:27]
	v_mfma_f32_16x16x32_bf16 v[12:15], v[162:165], v[218:221], v[12:15]
	v_mfma_f32_16x16x32_bf16 v[8:11], v[170:173], v[218:221], v[8:11]
	v_mfma_f32_16x16x32_bf16 v[52:55], v[174:177], v[190:193], v[52:55]
	v_mfma_f32_16x16x32_bf16 v[48:51], v[182:185], v[190:193], v[48:51]
	v_mfma_f32_16x16x32_bf16 v[36:39], v[174:177], v[198:201], v[36:39]
	v_mfma_f32_16x16x32_bf16 v[32:35], v[182:185], v[198:201], v[32:35]
	v_mfma_f32_16x16x32_bf16 v[20:23], v[174:177], v[206:209], v[20:23]
	v_mfma_f32_16x16x32_bf16 v[16:19], v[182:185], v[206:209], v[16:19]
	v_mfma_f32_16x16x32_bf16 v[4:7], v[174:177], v[214:217], v[4:7]
	v_mfma_f32_16x16x32_bf16 v[0:3], v[182:185], v[214:217], v[0:3]
	v_mfma_f32_16x16x32_bf16 v[52:55], v[178:181], v[194:197], v[52:55]
	v_mfma_f32_16x16x32_bf16 v[48:51], v[186:189], v[194:197], v[48:51]
	v_mfma_f32_16x16x32_bf16 v[36:39], v[178:181], v[202:205], v[36:39]
	v_mfma_f32_16x16x32_bf16 v[32:35], v[186:189], v[202:205], v[32:35]
	v_mfma_f32_16x16x32_bf16 v[20:23], v[178:181], v[210:213], v[20:23]
	v_mfma_f32_16x16x32_bf16 v[16:19], v[186:189], v[210:213], v[16:19]
	v_mfma_f32_16x16x32_bf16 v[4:7], v[178:181], v[218:221], v[4:7]
	v_mfma_f32_16x16x32_bf16 v[0:3], v[186:189], v[218:221], v[0:3]
	s_barrier
; #define PG8_STAGE(bufoff, gbase, voff) do { _Pragma("unroll") for (int _i = 0; _i < 2; ++_i) \
;         __builtin_amdgcn_global_load_lds((const unsigned*)((const char*)(gbase) + (voff)[_i]), (LAS unsigned*)(lds + (bufoff) + ldsw + _i * 8192), 16, 0, 0); } while (0)
; #define PG8_LDA(dst, b, h) do { _Pragma("unroll") for (int m = 0; m < 4; ++m) _Pragma("unroll") for (int k = 0; k < 2; ++k) dst[m][k] = *(const LAS bf16x8*)(lds + PG8_SA(b, h) + aoff + m * 2048 + k * 1024); } while (0)
; #define PG8_LDB(dst, b, h) do { _Pragma("unroll") for (int n = 0; n < 2; ++n) _Pragma("unroll") for (int k = 0; k < 2; ++k) dst[n][k] = *(const LAS bf16x8*)(lds + PG8_SB(b, h) + boff + n * 2048 + k * 1024); } while (0)
; #define PG8_MMA(ai, bj, At, Bt) do { __builtin_amdgcn_s_setprio(1); _Pragma("unroll") for (int m = 0; m < 4; ++m) _Pragma("unroll") for (int n = 0; n < 2; ++n) _Pragma("unroll") for (int k = 0; k < 2; ++k) \
;         acc[ai][bj][m][n] = __builtin_amdgcn_mfma_f32_16x16x32_bf16(Bt[n][k], At[m][k], acc[ai][bj][m][n], 0, 0, 0); __builtin_amdgcn_s_setprio(0); } while (0)
; #define PG8_WAIT_V(n) asm volatile("s_waitcnt vmcnt(" #n ")" ::: "memory")
; #define PG8_WAIT_L(n) asm volatile("s_waitcnt lgkmcnt(" #n ")" ::: "memory")
; #define PG8_BAR __builtin_amdgcn_s_barrier()
; #define PG8_SCHED __builtin_amdgcn_sched_barrier(0)
; __device__ __forceinline__ void gemm_phase(LAS unsigned char* lds, const Params& p, const bf16_t* gA, const bf16_t* gBt, const int gM, const int gN, const int gK, const int epi, const int perm, bf16_t* const Hp, const int goff, const float coef) {
;     ...
;             PG8_LDB(B0, 1, 0); PG8_LDB(B1, 1, 1); PG8_SCHED; PG8_LDA(At, 1, 0); PG8_STAGE(PG8_SA(0, 1), a2 + hstep, voffA);
;             PG8_WAIT_V(8); PG8_WAIT_L(0); PG8_BAR; PG8_MMA(0, 0, At, B0); PG8_MMA(0, 1, At, B1); PG8_BAR; PG8_SCHED;
;             PG8_LDA(At, 1, 1); PG8_STAGE(PG8_SB(1, 0), b3, voffB); PG8_STAGE(PG8_SB(1, 1), b3 + hstep, voffB); PG8_STAGE(PG8_SA(1, 0), a3, voffA);
;             PG8_WAIT_V(8); PG8_WAIT_L(0); PG8_BAR; PG8_MMA(1, 0, At, B0); PG8_MMA(1, 1, At, B1); PG8_BAR; PG8_SCHED;
	s_add_i32 s57, 0, 0x18000
	s_add_i32 s58, 0, 0x1c000
	ds_read_b128 v[158:161], v222
	ds_read_b128 v[162:165], v222 offset:1024
	ds_read_b128 v[166:169], v222 offset:2048
	ds_read_b128 v[170:173], v222 offset:3072
	ds_read_b128 v[174:177], v223
	ds_read_b128 v[178:181], v223 offset:1024
	ds_read_b128 v[182:185], v223 offset:2048
	ds_read_b128 v[186:189], v223 offset:3072
	s_add_u32 s48, s48, 0x80000
	s_addc_u32 s49, s49, 0
	s_mov_b32 m0, s16
	ds_read_b128 v[190:193], v157 offset:32768
	ds_read_b128 v[194:197], v157 offset:33792
	ds_read_b128 v[198:201], v157 offset:34816
	ds_read_b128 v[202:205], v157 offset:35840
	ds_read_b128 v[206:209], v157 offset:36864
	ds_read_b128 v[210:213], v157 offset:37888
	ds_read_b128 v[214:217], v157 offset:38912
	ds_read_b128 v[218:221], v157 offset:39936
	global_load_lds_dwordx4 v128, s[48:49]
	s_mov_b32 m0, s17
	s_nop 0
	global_load_lds_dwordx4 v132, s[48:49]
	s_waitcnt vmcnt(8)
	s_waitcnt lgkmcnt(0)
	s_barrier
	s_waitcnt lgkmcnt(0)
	v_mfma_f32_16x16x32_bf16 v[124:127], v[158:161], v[190:193], v[124:127]
	v_mfma_f32_16x16x32_bf16 v[120:123], v[166:169], v[190:193], v[120:123]
	v_mfma_f32_16x16x32_bf16 v[108:111], v[158:161], v[198:201], v[108:111]
	v_mfma_f32_16x16x32_bf16 v[104:107], v[166:169], v[198:201], v[104:107]
	v_mfma_f32_16x16x32_bf16 v[92:95], v[158:161], v[206:209], v[92:95]
	v_mfma_f32_16x16x32_bf16 v[88:91], v[166:169], v[206:209], v[88:91]
	v_mfma_f32_16x16x32_bf16 v[76:79], v[158:161], v[214:217], v[76:79]
	v_mfma_f32_16x16x32_bf16 v[72:75], v[166:169], v[214:217], v[72:75]
	v_mfma_f32_16x16x32_bf16 v[124:127], v[162:165], v[194:197], v[124:127]
	v_mfma_f32_16x16x32_bf16 v[120:123], v[170:173], v[194:197], v[120:123]
	v_mfma_f32_16x16x32_bf16 v[108:111], v[162:165], v[202:205], v[108:111]
	v_mfma_f32_16x16x32_bf16 v[104:107], v[170:173], v[202:205], v[104:107]
	v_mfma_f32_16x16x32_bf16 v[92:95], v[162:165], v[210:213], v[92:95]
	v_mfma_f32_16x16x32_bf16 v[88:91], v[170:173], v[210:213], v[88:91]
	v_mfma_f32_16x16x32_bf16 v[76:79], v[162:165], v[218:221], v[76:79]
	v_mfma_f32_16x16x32_bf16 v[72:75], v[170:173], v[218:221], v[72:75]
	v_mfma_f32_16x16x32_bf16 v[116:119], v[174:177], v[190:193], v[116:119]
	v_mfma_f32_16x16x32_bf16 v[112:115], v[182:185], v[190:193], v[112:115]
	v_mfma_f32_16x16x32_bf16 v[100:103], v[174:177], v[198:201], v[100:103]
	v_mfma_f32_16x16x32_bf16 v[96:99], v[182:185], v[198:201], v[96:99]
	v_mfma_f32_16x16x32_bf16 v[84:87], v[174:177], v[206:209], v[84:87]
	v_mfma_f32_16x16x32_bf16 v[80:83], v[182:185], v[206:209], v[80:83]
	v_mfma_f32_16x16x32_bf16 v[68:71], v[174:177], v[214:217], v[68:71]
	v_mfma_f32_16x16x32_bf16 v[64:67], v[182:185], v[214:217], v[64:67]
	v_mfma_f32_16x16x32_bf16 v[116:119], v[178:181], v[194:197], v[116:119]
	v_mfma_f32_16x16x32_bf16 v[112:115], v[186:189], v[194:197], v[112:115]
	v_mfma_f32_16x16x32_bf16 v[100:103], v[178:181], v[202:205], v[100:103]
	v_mfma_f32_16x16x32_bf16 v[96:99], v[186:189], v[202:205], v[96:99]
	v_mfma_f32_16x16x32_bf16 v[84:87], v[178:181], v[210:213], v[84:87]
	v_mfma_f32_16x16x32_bf16 v[80:83], v[186:189], v[210:213], v[80:83]
	v_mfma_f32_16x16x32_bf16 v[68:71], v[178:181], v[218:221], v[68:71]
	v_mfma_f32_16x16x32_bf16 v[64:67], v[186:189], v[218:221], v[64:67]
	s_barrier
	s_mov_b64 s[98:99], s[48:49]
	s_add_i32 s48, s57, s11
	s_mov_b32 m0, s48
	ds_read_b128 v[190:193], v157 offset:49152
	ds_read_b128 v[194:197], v157 offset:50176
	ds_read_b128 v[198:201], v157 offset:51200
	ds_read_b128 v[202:205], v157 offset:52224
	ds_read_b128 v[206:209], v157 offset:53248
	ds_read_b128 v[210:213], v157 offset:54272
	ds_read_b128 v[214:217], v157 offset:55296
	ds_read_b128 v[218:221], v157 offset:56320
	s_add_u32 s100, s46, 0x80
	s_addc_u32 s101, s47, 0
	global_load_lds_dwordx4 v130, s[100:101]
	s_add_i32 m0, s48, 0x2000
	s_add_u32 s46, s46, 0x80080
	s_addc_u32 s47, s47, 0
	s_add_i32 s48, s58, s11
	global_load_lds_dwordx4 v134, s[100:101]
	s_mov_b32 m0, s48
	s_nop 0
	global_load_lds_dwordx4 v130, s[46:47]
	s_add_i32 m0, s48, 0x2000
	s_nop 0
	global_load_lds_dwordx4 v134, s[46:47]
	s_mov_b32 m0, s19
	s_nop 0
	s_add_u32 s100, s98, 0xfff80080
	s_addc_u32 s101, s99, -1
	global_load_lds_dwordx4 v128, s[100:101]
	s_mov_b32 m0, s20
	s_nop 0
	global_load_lds_dwordx4 v132, s[100:101]
	s_waitcnt vmcnt(8)
	s_waitcnt lgkmcnt(0)
	s_barrier
	s_waitcnt lgkmcnt(0)
	v_mfma_f32_16x16x32_bf16 v[60:63], v[158:161], v[190:193], v[60:63]
	v_mfma_f32_16x16x32_bf16 v[56:59], v[166:169], v[190:193], v[56:59]
	v_mfma_f32_16x16x32_bf16 v[44:47], v[158:161], v[198:201], v[44:47]
	v_mfma_f32_16x16x32_bf16 v[40:43], v[166:169], v[198:201], v[40:43]
	v_mfma_f32_16x16x32_bf16 v[28:31], v[158:161], v[206:209], v[28:31]
	v_mfma_f32_16x16x32_bf16 v[24:27], v[166:169], v[206:209], v[24:27]
	v_mfma_f32_16x16x32_bf16 v[12:15], v[158:161], v[214:217], v[12:15]
	v_mfma_f32_16x16x32_bf16 v[8:11], v[166:169], v[214:217], v[8:11]
	v_mfma_f32_16x16x32_bf16 v[60:63], v[162:165], v[194:197], v[60:63]
	v_mfma_f32_16x16x32_bf16 v[56:59], v[170:173], v[194:197], v[56:59]
	v_mfma_f32_16x16x32_bf16 v[44:47], v[162:165], v[202:205], v[44:47]
	v_mfma_f32_16x16x32_bf16 v[40:43], v[170:173], v[202:205], v[40:43]
	v_mfma_f32_16x16x32_bf16 v[28:31], v[162:165], v[210:213], v[28:31]
	v_mfma_f32_16x16x32_bf16 v[24:27], v[170:173], v[210:213], v[24:27]
	v_mfma_f32_16x16x32_bf16 v[12:15], v[162:165], v[218:221], v[12:15]
	v_mfma_f32_16x16x32_bf16 v[8:11], v[170:173], v[218:221], v[8:11]
	v_mfma_f32_16x16x32_bf16 v[52:55], v[174:177], v[190:193], v[52:55]
	v_mfma_f32_16x16x32_bf16 v[48:51], v[182:185], v[190:193], v[48:51]
	v_mfma_f32_16x16x32_bf16 v[36:39], v[174:177], v[198:201], v[36:39]
	v_mfma_f32_16x16x32_bf16 v[32:35], v[182:185], v[198:201], v[32:35]
	v_mfma_f32_16x16x32_bf16 v[20:23], v[174:177], v[206:209], v[20:23]
	v_mfma_f32_16x16x32_bf16 v[16:19], v[182:185], v[206:209], v[16:19]
	v_mfma_f32_16x16x32_bf16 v[4:7], v[174:177], v[214:217], v[4:7]
	v_mfma_f32_16x16x32_bf16 v[0:3], v[182:185], v[214:217], v[0:3]
	v_mfma_f32_16x16x32_bf16 v[52:55], v[178:181], v[194:197], v[52:55]
	v_mfma_f32_16x16x32_bf16 v[48:51], v[186:189], v[194:197], v[48:51]
	v_mfma_f32_16x16x32_bf16 v[36:39], v[178:181], v[202:205], v[36:39]
	v_mfma_f32_16x16x32_bf16 v[32:35], v[186:189], v[202:205], v[32:35]
	v_mfma_f32_16x16x32_bf16 v[20:23], v[178:181], v[210:213], v[20:23]
	v_mfma_f32_16x16x32_bf16 v[16:19], v[186:189], v[210:213], v[16:19]
	v_mfma_f32_16x16x32_bf16 v[4:7], v[178:181], v[218:221], v[4:7]
	v_mfma_f32_16x16x32_bf16 v[0:3], v[186:189], v[218:221], v[0:3]
	s_barrier
	s_add_u32 s44, s44, 0x100
	s_addc_u32 s45, s45, 0
	s_add_u32 s54, s54, 0x100
	s_addc_u32 s55, s55, 0
	s_cmp_ge_u32 s56, s52
	s_mov_b32 s48, s56
	s_cbranch_scc0 .LBB0_170

; #define PG8_STAGE(bufoff, gbase, voff) do { _Pragma("unroll") for (int _i = 0; _i < 2; ++_i) \
;         __builtin_amdgcn_global_load_lds((const unsigned*)((const char*)(gbase) + (voff)[_i]), (LAS unsigned*)(lds + (bufoff) + ldsw + _i * 8192), 16, 0, 0); } while (0)
; #define PG8_WAIT_V(n) asm volatile("s_waitcnt vmcnt(" #n ")" ::: "memory")
; #define PG8_WAIT_L(n) asm volatile("s_waitcnt lgkmcnt(" #n ")" ::: "memory")
; #define PG8_BAR __builtin_amdgcn_s_barrier()
; __device__ __forceinline__ void gemm_phase(LAS unsigned char* lds, const Params& p, const bf16_t* gA, const bf16_t* gBt, const int gM, const int gN, const int gK, const int epi, const int perm, bf16_t* const Hp, const int goff, const float coef) {
;     ...
;         const char* nA = has_next ? (const char*)gA + (size_t)nxt.pm * tstep + (nxt.ks > 0 ? nxt.ks * ksl : 0) : cA; const char* nB = has_next ? (const char*)gBt + (size_t)nxt.pn * tstep + (nxt.ks > 0 ? nxt.ks * ksl : 0) : cB;
;         const int nt = cur.ks >= 0 ? ntf / 4 : ntf;
;         for (int t = 0; t < nt; t += 2) {
;             const bool last = (t == nt - 2);
;             const char* a1 = cA + (size_t)(t + 1) * kstep;
;             const char* a2 = last ? nA : cA + (size_t)(t + 2) * kstep; const char* b2 = last ? nB : cB + (size_t)(t + 2) * kstep;
;             const char* a3 = a2 + kstep; const char* b3 = b2 + kstep;
;             PG8_LDB(B0, 0, 0); PG8_LDB(B1, 0, 1); PG8_SCHED; PG8_LDA(At, 0, 0); PG8_STAGE(PG8_SA(1, 1), a1 + hstep, voffA);
;             PG8_WAIT_V(8); PG8_WAIT_L(0); PG8_BAR; PG8_MMA(0, 0, At, B0); PG8_MMA(0, 1, At, B1); PG8_BAR; PG8_SCHED;
;             PG8_LDA(At, 0, 1); PG8_STAGE(PG8_SB(0, 0), b2, voffB); PG8_STAGE(PG8_SB(0, 1), b2 + hstep, voffB); PG8_STAGE(PG8_SA(0, 0), a2, voffA);
;             PG8_WAIT_V(8); PG8_WAIT_L(0); PG8_BAR; PG8_MMA(1, 0, At, B0); PG8_MMA(1, 1, At, B1); PG8_BAR; PG8_SCHED;
;             PG8_LDB(B0, 1, 0); PG8_LDB(B1, 1, 1); PG8_SCHED; PG8_LDA(At, 1, 0); PG8_STAGE(PG8_SA(0, 1), a2 + hstep, voffA);
;             PG8_WAIT_V(8); PG8_WAIT_L(0); PG8_BAR; PG8_MMA(0, 0, At, B0); PG8_MMA(0, 1, At, B1); PG8_BAR; PG8_SCHED;
;             PG8_LDA(At, 1, 1); PG8_STAGE(PG8_SB(1, 0), b3, voffB); PG8_STAGE(PG8_SB(1, 1), b3 + hstep, voffB); PG8_STAGE(PG8_SA(1, 0), a3, voffA);
;             PG8_WAIT_V(8); PG8_WAIT_L(0); PG8_BAR; PG8_MMA(1, 0, At, B0); PG8_MMA(1, 1, At, B1); PG8_BAR; PG8_SCHED;
.LBB0_263:
	s_cmp_gt_i32 s6, -1
	s_cselect_b64 s[4:5], -1, 0
	s_and_b64 s[38:39], s[4:5], exec
	s_cselect_b32 s54, 22, 0x58
	s_add_i32 s55, s54, -2
	s_add_u32 s30, s30, 0x160080
	s_addc_u32 s31, s31, 0
	s_add_u32 s56, s34, 0x100
	s_addc_u32 s57, s35, 0
	s_mov_b32 s34, 0
	v_add_u32_e32 v222, 0x18000, v158
	v_add_u32_e32 v223, 0x1c000, v158
	ds_read_b128 v[146:149], v167
	ds_read_b128 v[150:153], v167 offset:1024
	ds_read_b128 v[154:157], v167 offset:2048
	ds_read_b128 v[170:173], v167 offset:3072
	ds_read_b128 v[174:177], v168
	ds_read_b128 v[178:181], v168 offset:1024
	ds_read_b128 v[182:185], v168 offset:2048
	ds_read_b128 v[186:189], v168 offset:3072
	s_add_i32 s58, s34, 2
	s_add_u32 s35, s30, 0xffea0080
	s_addc_u32 s38, s31, -1
	s_cmp_eq_u32 s55, s34
	s_cselect_b32 s34, s28, s56
	s_cselect_b32 s39, s27, s38
	s_cselect_b32 s38, s26, s35
	s_cselect_b32 s35, s29, s57
	s_add_i32 m0, s17, 0xc000
	ds_read_b128 v[190:193], v169
	ds_read_b128 v[194:197], v169 offset:1024
	ds_read_b128 v[198:201], v169 offset:2048
	ds_read_b128 v[202:205], v169 offset:3072
	ds_read_b128 v[206:209], v169 offset:4096
	ds_read_b128 v[210:213], v169 offset:5120
	ds_read_b128 v[214:217], v169 offset:6144
	ds_read_b128 v[218:221], v169 offset:7168
	global_load_lds_dwordx4 v136, s[30:31]
	s_add_i32 m0, s17, 0xe000
	s_nop 0
	global_load_lds_dwordx4 v138, s[30:31]
	s_waitcnt vmcnt(8)
	s_waitcnt lgkmcnt(0)
	s_barrier
	s_waitcnt lgkmcnt(0)
	v_mfma_f32_16x16x32_bf16 v[124:127], v[146:149], v[190:193], 0
	v_mfma_f32_16x16x32_bf16 v[120:123], v[154:157], v[190:193], 0
	v_mfma_f32_16x16x32_bf16 v[116:119], v[146:149], v[198:201], 0
	v_mfma_f32_16x16x32_bf16 v[112:115], v[154:157], v[198:201], 0
	v_mfma_f32_16x16x32_bf16 v[108:111], v[146:149], v[206:209], 0
	v_mfma_f32_16x16x32_bf16 v[104:107], v[154:157], v[206:209], 0
	v_mfma_f32_16x16x32_bf16 v[100:103], v[146:149], v[214:217], 0
	v_mfma_f32_16x16x32_bf16 v[96:99], v[154:157], v[214:217], 0
	v_mfma_f32_16x16x32_bf16 v[124:127], v[150:153], v[194:197], v[124:127]
	v_mfma_f32_16x16x32_bf16 v[120:123], v[170:173], v[194:197], v[120:123]
	v_mfma_f32_16x16x32_bf16 v[116:119], v[150:153], v[202:205], v[116:119]
	v_mfma_f32_16x16x32_bf16 v[112:115], v[170:173], v[202:205], v[112:115]
	v_mfma_f32_16x16x32_bf16 v[108:111], v[150:153], v[210:213], v[108:111]
	v_mfma_f32_16x16x32_bf16 v[104:107], v[170:173], v[210:213], v[104:107]
	v_mfma_f32_16x16x32_bf16 v[100:103], v[150:153], v[218:221], v[100:103]
	v_mfma_f32_16x16x32_bf16 v[96:99], v[170:173], v[218:221], v[96:99]
	v_mfma_f32_16x16x32_bf16 v[68:71], v[174:177], v[190:193], 0
	v_mfma_f32_16x16x32_bf16 v[60:63], v[182:185], v[190:193], 0
	v_mfma_f32_16x16x32_bf16 v[52:55], v[174:177], v[198:201], 0
	v_mfma_f32_16x16x32_bf16 v[48:51], v[182:185], v[198:201], 0
	v_mfma_f32_16x16x32_bf16 v[44:47], v[174:177], v[206:209], 0
	v_mfma_f32_16x16x32_bf16 v[40:43], v[182:185], v[206:209], 0
	v_mfma_f32_16x16x32_bf16 v[36:39], v[174:177], v[214:217], 0
	v_mfma_f32_16x16x32_bf16 v[32:35], v[182:185], v[214:217], 0
	v_mfma_f32_16x16x32_bf16 v[68:71], v[178:181], v[194:197], v[68:71]
	v_mfma_f32_16x16x32_bf16 v[60:63], v[186:189], v[194:197], v[60:63]
	v_mfma_f32_16x16x32_bf16 v[52:55], v[178:181], v[202:205], v[52:55]
	v_mfma_f32_16x16x32_bf16 v[48:51], v[186:189], v[202:205], v[48:51]
	v_mfma_f32_16x16x32_bf16 v[44:47], v[178:181], v[210:213], v[44:47]
	v_mfma_f32_16x16x32_bf16 v[40:43], v[186:189], v[210:213], v[40:43]
	v_mfma_f32_16x16x32_bf16 v[36:39], v[178:181], v[218:221], v[36:39]
	v_mfma_f32_16x16x32_bf16 v[32:35], v[186:189], v[218:221], v[32:35]
	s_barrier
	s_add_i32 s59, s46, s16
	s_mov_b32 m0, s59
	ds_read_b128 v[190:193], v169 offset:16384
	ds_read_b128 v[194:197], v169 offset:17408
	ds_read_b128 v[198:201], v169 offset:18432
	ds_read_b128 v[202:205], v169 offset:19456
	ds_read_b128 v[206:209], v169 offset:20480
	ds_read_b128 v[210:213], v169 offset:21504
	ds_read_b128 v[214:217], v169 offset:22528
	ds_read_b128 v[218:221], v169 offset:23552
	global_load_lds_dwordx4 v130, s[34:35]
	s_add_i32 m0, s59, 0x2000
	s_add_u32 s60, s34, 0x160000
	s_addc_u32 s61, s35, 0
	s_add_i32 s59, s47, s16
	global_load_lds_dwordx4 v134, s[34:35]
	s_mov_b32 m0, s59
	s_nop 0
	global_load_lds_dwordx4 v130, s[60:61]
	s_add_i32 m0, s59, 0x2000
	s_nop 0
	global_load_lds_dwordx4 v134, s[60:61]
	s_mov_b32 m0, s17
	s_nop 0
	global_load_lds_dwordx4 v128, s[38:39]
	s_mov_b32 m0, s18
	s_nop 0
	global_load_lds_dwordx4 v132, s[38:39]
	s_waitcnt vmcnt(8)
	s_waitcnt lgkmcnt(0)
	s_barrier
	s_waitcnt lgkmcnt(0)
	v_mfma_f32_16x16x32_bf16 v[92:95], v[146:149], v[190:193], 0
	v_mfma_f32_16x16x32_bf16 v[88:91], v[154:157], v[190:193], 0
	v_mfma_f32_16x16x32_bf16 v[84:87], v[146:149], v[198:201], 0
	v_mfma_f32_16x16x32_bf16 v[80:83], v[154:157], v[198:201], 0
	v_mfma_f32_16x16x32_bf16 v[76:79], v[146:149], v[206:209], 0
	v_mfma_f32_16x16x32_bf16 v[72:75], v[154:157], v[206:209], 0
	v_mfma_f32_16x16x32_bf16 v[64:67], v[146:149], v[214:217], 0
	v_mfma_f32_16x16x32_bf16 v[56:59], v[154:157], v[214:217], 0
	v_mfma_f32_16x16x32_bf16 v[92:95], v[150:153], v[194:197], v[92:95]
	v_mfma_f32_16x16x32_bf16 v[88:91], v[170:173], v[194:197], v[88:91]
	v_mfma_f32_16x16x32_bf16 v[84:87], v[150:153], v[202:205], v[84:87]
	v_mfma_f32_16x16x32_bf16 v[80:83], v[170:173], v[202:205], v[80:83]
	v_mfma_f32_16x16x32_bf16 v[76:79], v[150:153], v[210:213], v[76:79]
	v_mfma_f32_16x16x32_bf16 v[72:75], v[170:173], v[210:213], v[72:75]
	v_mfma_f32_16x16x32_bf16 v[64:67], v[150:153], v[218:221], v[64:67]
	v_mfma_f32_16x16x32_bf16 v[56:59], v[170:173], v[218:221], v[56:59]
	v_mfma_f32_16x16x32_bf16 v[28:31], v[174:177], v[190:193], 0
	v_mfma_f32_16x16x32_bf16 v[24:27], v[182:185], v[190:193], 0
	v_mfma_f32_16x16x32_bf16 v[20:23], v[174:177], v[198:201], 0
	v_mfma_f32_16x16x32_bf16 v[16:19], v[182:185], v[198:201], 0
	v_mfma_f32_16x16x32_bf16 v[12:15], v[174:177], v[206:209], 0
	v_mfma_f32_16x16x32_bf16 v[8:11], v[182:185], v[206:209], 0
	v_mfma_f32_16x16x32_bf16 v[4:7], v[174:177], v[214:217], 0
	v_mfma_f32_16x16x32_bf16 v[0:3], v[182:185], v[214:217], 0
	v_mfma_f32_16x16x32_bf16 v[28:31], v[178:181], v[194:197], v[28:31]
	v_mfma_f32_16x16x32_bf16 v[24:27], v[186:189], v[194:197], v[24:27]
	v_mfma_f32_16x16x32_bf16 v[20:23], v[178:181], v[202:205], v[20:23]
	v_mfma_f32_16x16x32_bf16 v[16:19], v[186:189], v[202:205], v[16:19]
	v_mfma_f32_16x16x32_bf16 v[12:15], v[178:181], v[210:213], v[12:15]
	v_mfma_f32_16x16x32_bf16 v[8:11], v[186:189], v[210:213], v[8:11]
	v_mfma_f32_16x16x32_bf16 v[4:7], v[178:181], v[218:221], v[4:7]
	v_mfma_f32_16x16x32_bf16 v[0:3], v[186:189], v[218:221], v[0:3]
	s_barrier
; #define PG8_STAGE(bufoff, gbase, voff) do { _Pragma("unroll") for (int _i = 0; _i < 2; ++_i) \
;         __builtin_amdgcn_global_load_lds((const unsigned*)((const char*)(gbase) + (voff)[_i]), (LAS unsigned*)(lds + (bufoff) + ldsw + _i * 8192), 16, 0, 0); } while (0)
; #define PG8_LDA(dst, b, h) do { _Pragma("unroll") for (int m = 0; m < 4; ++m) _Pragma("unroll") for (int k = 0; k < 2; ++k) dst[m][k] = *(const LAS bf16x8*)(lds + PG8_SA(b, h) + aoff + m * 2048 + k * 1024); } while (0)
; #define PG8_LDB(dst, b, h) do { _Pragma("unroll") for (int n = 0; n < 2; ++n) _Pragma("unroll") for (int k = 0; k < 2; ++k) dst[n][k] = *(const LAS bf16x8*)(lds + PG8_SB(b, h) + boff + n * 2048 + k * 1024); } while (0)
; #define PG8_MMA(ai, bj, At, Bt) do { __builtin_amdgcn_s_setprio(1); _Pragma("unroll") for (int m = 0; m < 4; ++m) _Pragma("unroll") for (int n = 0; n < 2; ++n) _Pragma("unroll") for (int k = 0; k < 2; ++k) \
;         acc[ai][bj][m][n] = __builtin_amdgcn_mfma_f32_16x16x32_bf16(Bt[n][k], At[m][k], acc[ai][bj][m][n], 0, 0, 0); __builtin_amdgcn_s_setprio(0); } while (0)
; #define PG8_WAIT_V(n) asm volatile("s_waitcnt vmcnt(" #n ")" ::: "memory")
; #define PG8_WAIT_L(n) asm volatile("s_waitcnt lgkmcnt(" #n ")" ::: "memory")
; #define PG8_BAR __builtin_amdgcn_s_barrier()
; #define PG8_SCHED __builtin_amdgcn_sched_barrier(0)
; __device__ __forceinline__ void gemm_phase(LAS unsigned char* lds, const Params& p, const bf16_t* gA, const bf16_t* gBt, const int gM, const int gN, const int gK, const int epi, const int perm, bf16_t* const Hp, const int goff, const float coef) {
;     ...
;             PG8_LDB(B0, 1, 0); PG8_LDB(B1, 1, 1); PG8_SCHED; PG8_LDA(At, 1, 0); PG8_STAGE(PG8_SA(0, 1), a2 + hstep, voffA);
;             PG8_WAIT_V(8); PG8_WAIT_L(0); PG8_BAR; PG8_MMA(0, 0, At, B0); PG8_MMA(0, 1, At, B1); PG8_BAR; PG8_SCHED;
;             PG8_LDA(At, 1, 1); PG8_STAGE(PG8_SB(1, 0), b3, voffB); PG8_STAGE(PG8_SB(1, 1), b3 + hstep, voffB); PG8_STAGE(PG8_SA(1, 0), a3, voffA);
;             PG8_WAIT_V(8); PG8_WAIT_L(0); PG8_BAR; PG8_MMA(1, 0, At, B0); PG8_MMA(1, 1, At, B1); PG8_BAR; PG8_SCHED;
	s_add_i32 s59, 0, 0x18000
	s_add_i32 s60, 0, 0x1c000
	ds_read_b128 v[146:149], v222
	ds_read_b128 v[150:153], v222 offset:1024
	ds_read_b128 v[154:157], v222 offset:2048
	ds_read_b128 v[170:173], v222 offset:3072
	ds_read_b128 v[174:177], v223
	ds_read_b128 v[178:181], v223 offset:1024
	ds_read_b128 v[182:185], v223 offset:2048
	ds_read_b128 v[186:189], v223 offset:3072
	s_add_u32 s38, s38, 0x160000
	s_addc_u32 s39, s39, 0
	s_mov_b32 m0, s19
	ds_read_b128 v[190:193], v169 offset:32768
	ds_read_b128 v[194:197], v169 offset:33792
	ds_read_b128 v[198:201], v169 offset:34816
	ds_read_b128 v[202:205], v169 offset:35840
	ds_read_b128 v[206:209], v169 offset:36864
	ds_read_b128 v[210:213], v169 offset:37888
	ds_read_b128 v[214:217], v169 offset:38912
	ds_read_b128 v[218:221], v169 offset:39936
	global_load_lds_dwordx4 v128, s[38:39]
	s_mov_b32 m0, s20
	s_nop 0
	global_load_lds_dwordx4 v132, s[38:39]
	s_waitcnt vmcnt(8)
	s_waitcnt lgkmcnt(0)
	s_barrier
	s_waitcnt lgkmcnt(0)
	v_mfma_f32_16x16x32_bf16 v[124:127], v[146:149], v[190:193], v[124:127]
	v_mfma_f32_16x16x32_bf16 v[120:123], v[154:157], v[190:193], v[120:123]
	v_mfma_f32_16x16x32_bf16 v[116:119], v[146:149], v[198:201], v[116:119]
	v_mfma_f32_16x16x32_bf16 v[112:115], v[154:157], v[198:201], v[112:115]
	v_mfma_f32_16x16x32_bf16 v[108:111], v[146:149], v[206:209], v[108:111]
	v_mfma_f32_16x16x32_bf16 v[104:107], v[154:157], v[206:209], v[104:107]
	v_mfma_f32_16x16x32_bf16 v[100:103], v[146:149], v[214:217], v[100:103]
	v_mfma_f32_16x16x32_bf16 v[96:99], v[154:157], v[214:217], v[96:99]
	v_mfma_f32_16x16x32_bf16 v[124:127], v[150:153], v[194:197], v[124:127]
	v_mfma_f32_16x16x32_bf16 v[120:123], v[170:173], v[194:197], v[120:123]
	v_mfma_f32_16x16x32_bf16 v[116:119], v[150:153], v[202:205], v[116:119]
	v_mfma_f32_16x16x32_bf16 v[112:115], v[170:173], v[202:205], v[112:115]
	v_mfma_f32_16x16x32_bf16 v[108:111], v[150:153], v[210:213], v[108:111]
	v_mfma_f32_16x16x32_bf16 v[104:107], v[170:173], v[210:213], v[104:107]
	v_mfma_f32_16x16x32_bf16 v[100:103], v[150:153], v[218:221], v[100:103]
	v_mfma_f32_16x16x32_bf16 v[96:99], v[170:173], v[218:221], v[96:99]
	v_mfma_f32_16x16x32_bf16 v[68:71], v[174:177], v[190:193], v[68:71]
	v_mfma_f32_16x16x32_bf16 v[60:63], v[182:185], v[190:193], v[60:63]
	v_mfma_f32_16x16x32_bf16 v[52:55], v[174:177], v[198:201], v[52:55]
	v_mfma_f32_16x16x32_bf16 v[48:51], v[182:185], v[198:201], v[48:51]
	v_mfma_f32_16x16x32_bf16 v[44:47], v[174:177], v[206:209], v[44:47]
	v_mfma_f32_16x16x32_bf16 v[40:43], v[182:185], v[206:209], v[40:43]
	v_mfma_f32_16x16x32_bf16 v[36:39], v[174:177], v[214:217], v[36:39]
	v_mfma_f32_16x16x32_bf16 v[32:35], v[182:185], v[214:217], v[32:35]
	v_mfma_f32_16x16x32_bf16 v[68:71], v[178:181], v[194:197], v[68:71]
	v_mfma_f32_16x16x32_bf16 v[60:63], v[186:189], v[194:197], v[60:63]
	v_mfma_f32_16x16x32_bf16 v[52:55], v[178:181], v[202:205], v[52:55]
	v_mfma_f32_16x16x32_bf16 v[48:51], v[186:189], v[202:205], v[48:51]
	v_mfma_f32_16x16x32_bf16 v[44:47], v[178:181], v[210:213], v[44:47]
	v_mfma_f32_16x16x32_bf16 v[40:43], v[186:189], v[210:213], v[40:43]
	v_mfma_f32_16x16x32_bf16 v[36:39], v[178:181], v[218:221], v[36:39]
	v_mfma_f32_16x16x32_bf16 v[32:35], v[186:189], v[218:221], v[32:35]
	s_barrier
	s_mov_b64 s[98:99], s[38:39]
	s_add_i32 s38, s59, s16
	s_mov_b32 m0, s38
	ds_read_b128 v[190:193], v169 offset:49152
	ds_read_b128 v[194:197], v169 offset:50176
	ds_read_b128 v[198:201], v169 offset:51200
	ds_read_b128 v[202:205], v169 offset:52224
	ds_read_b128 v[206:209], v169 offset:53248
	ds_read_b128 v[210:213], v169 offset:54272
	ds_read_b128 v[214:217], v169 offset:55296
	ds_read_b128 v[218:221], v169 offset:56320
	s_add_u32 s100, s34, 0x80
	s_addc_u32 s101, s35, 0
	global_load_lds_dwordx4 v130, s[100:101]
	s_add_i32 m0, s38, 0x2000
	s_add_u32 s34, s34, 0x160080
	s_addc_u32 s35, s35, 0
	s_add_i32 s38, s60, s16
	global_load_lds_dwordx4 v134, s[100:101]
	s_mov_b32 m0, s38
	s_nop 0
	global_load_lds_dwordx4 v130, s[34:35]
	s_add_i32 m0, s38, 0x2000
	s_nop 0
	global_load_lds_dwordx4 v134, s[34:35]
	s_mov_b32 m0, s23
	s_nop 0
	s_add_u32 s100, s98, 0xffea0080
	s_addc_u32 s101, s99, -1
	global_load_lds_dwordx4 v128, s[100:101]
	s_mov_b32 m0, s33
	s_nop 0
	global_load_lds_dwordx4 v132, s[100:101]
	s_waitcnt vmcnt(8)
	s_waitcnt lgkmcnt(0)
	s_barrier
	s_waitcnt lgkmcnt(0)
	v_mfma_f32_16x16x32_bf16 v[92:95], v[146:149], v[190:193], v[92:95]
	v_mfma_f32_16x16x32_bf16 v[88:91], v[154:157], v[190:193], v[88:91]
	v_mfma_f32_16x16x32_bf16 v[84:87], v[146:149], v[198:201], v[84:87]
	v_mfma_f32_16x16x32_bf16 v[80:83], v[154:157], v[198:201], v[80:83]
	v_mfma_f32_16x16x32_bf16 v[76:79], v[146:149], v[206:209], v[76:79]
	v_mfma_f32_16x16x32_bf16 v[72:75], v[154:157], v[206:209], v[72:75]
	v_mfma_f32_16x16x32_bf16 v[64:67], v[146:149], v[214:217], v[64:67]
	v_mfma_f32_16x16x32_bf16 v[56:59], v[154:157], v[214:217], v[56:59]
	v_mfma_f32_16x16x32_bf16 v[92:95], v[150:153], v[194:197], v[92:95]
	v_mfma_f32_16x16x32_bf16 v[88:91], v[170:173], v[194:197], v[88:91]
	v_mfma_f32_16x16x32_bf16 v[84:87], v[150:153], v[202:205], v[84:87]
	v_mfma_f32_16x16x32_bf16 v[80:83], v[170:173], v[202:205], v[80:83]
	v_mfma_f32_16x16x32_bf16 v[76:79], v[150:153], v[210:213], v[76:79]
	v_mfma_f32_16x16x32_bf16 v[72:75], v[170:173], v[210:213], v[72:75]
	v_mfma_f32_16x16x32_bf16 v[64:67], v[150:153], v[218:221], v[64:67]
	v_mfma_f32_16x16x32_bf16 v[56:59], v[170:173], v[218:221], v[56:59]
	v_mfma_f32_16x16x32_bf16 v[28:31], v[174:177], v[190:193], v[28:31]
	v_mfma_f32_16x16x32_bf16 v[24:27], v[182:185], v[190:193], v[24:27]
	v_mfma_f32_16x16x32_bf16 v[20:23], v[174:177], v[198:201], v[20:23]
	v_mfma_f32_16x16x32_bf16 v[16:19], v[182:185], v[198:201], v[16:19]
	v_mfma_f32_16x16x32_bf16 v[12:15], v[174:177], v[206:209], v[12:15]
	v_mfma_f32_16x16x32_bf16 v[8:11], v[182:185], v[206:209], v[8:11]
	v_mfma_f32_16x16x32_bf16 v[4:7], v[174:177], v[214:217], v[4:7]
	v_mfma_f32_16x16x32_bf16 v[0:3], v[182:185], v[214:217], v[0:3]
	v_mfma_f32_16x16x32_bf16 v[28:31], v[178:181], v[194:197], v[28:31]
	v_mfma_f32_16x16x32_bf16 v[24:27], v[186:189], v[194:197], v[24:27]
	v_mfma_f32_16x16x32_bf16 v[20:23], v[178:181], v[202:205], v[20:23]
	v_mfma_f32_16x16x32_bf16 v[16:19], v[186:189], v[202:205], v[16:19]
	v_mfma_f32_16x16x32_bf16 v[12:15], v[178:181], v[210:213], v[12:15]
	v_mfma_f32_16x16x32_bf16 v[8:11], v[186:189], v[210:213], v[8:11]
	v_mfma_f32_16x16x32_bf16 v[4:7], v[178:181], v[218:221], v[4:7]
	v_mfma_f32_16x16x32_bf16 v[0:3], v[186:189], v[218:221], v[0:3]
	s_barrier
	s_add_u32 s30, s30, 0x100
	s_addc_u32 s31, s31, 0
	s_add_u32 s56, s56, 0x100
	s_addc_u32 s57, s57, 0
	s_cmp_ge_u32 s58, s54
	s_mov_b64 s[98:99], s[34:35]
	s_mov_b32 s34, s58
	s_cbranch_scc1 .Lpeel_exit_1
; #define PG8_STAGE(bufoff, gbase, voff) do { _Pragma("unroll") for (int _i = 0; _i < 2; ++_i) \
;         __builtin_amdgcn_global_load_lds((const unsigned*)((const char*)(gbase) + (voff)[_i]), (LAS unsigned*)(lds + (bufoff) + ldsw + _i * 8192), 16, 0, 0); } while (0)
; #define PG8_LDA(dst, b, h) do { _Pragma("unroll") for (int m = 0; m < 4; ++m) _Pragma("unroll") for (int k = 0; k < 2; ++k) dst[m][k] = *(const LAS bf16x8*)(lds + PG8_SA(b, h) + aoff + m * 2048 + k * 1024); } while (0)
; #define PG8_LDB(dst, b, h) do { _Pragma("unroll") for (int n = 0; n < 2; ++n) _Pragma("unroll") for (int k = 0; k < 2; ++k) dst[n][k] = *(const LAS bf16x8*)(lds + PG8_SB(b, h) + boff + n * 2048 + k * 1024); } while (0)
; #define PG8_BAR __builtin_amdgcn_s_barrier()
; __device__ __forceinline__ void gemm_phase(LAS unsigned char* lds, const Params& p, const bf16_t* gA, const bf16_t* gBt, const int gM, const int gN, const int gK, const int epi, const int perm, bf16_t* const Hp, const int goff, const float coef) {
;     ...
;         for (int t = 0; t < nt; t += 2) {
;             const bool last = (t == nt - 2);
;             const char* a1 = cA + (size_t)(t + 1) * kstep;
;             const char* a2 = last ? nA : cA + (size_t)(t + 2) * kstep; const char* b2 = last ? nB : cB + (size_t)(t + 2) * kstep;
;             const char* a3 = a2 + kstep; const char* b3 = b2 + kstep;
;             PG8_LDB(B0, 0, 0); PG8_LDB(B1, 0, 1); PG8_SCHED; PG8_LDA(At, 0, 0); PG8_STAGE(PG8_SA(1, 1), a1 + hstep, voffA);
;             PG8_WAIT_V(8); PG8_WAIT_L(0); PG8_BAR; PG8_MMA(0, 0, At, B0); PG8_MMA(0, 1, At, B1); PG8_BAR; PG8_SCHED;
;             PG8_LDA(At, 0, 1); PG8_STAGE(PG8_SB(0, 0), b2, voffB); PG8_STAGE(PG8_SB(0, 1), b2 + hstep, voffB); PG8_STAGE(PG8_SA(0, 0), a2, voffA);
;             PG8_WAIT_V(8); PG8_WAIT_L(0); PG8_BAR; PG8_MMA(1, 0, At, B0); PG8_MMA(1, 1, At, B1); PG8_BAR; PG8_SCHED;
;             PG8_LDB(B0, 1, 0); PG8_LDB(B1, 1, 1); PG8_SCHED; PG8_LDA(At, 1, 0); PG8_STAGE(PG8_SA(0, 1), a2 + hstep, voffA);
;             PG8_WAIT_V(8); PG8_WAIT_L(0); PG8_BAR; PG8_MMA(0, 0, At, B0); PG8_MMA(0, 1, At, B1); PG8_BAR; PG8_SCHED;
;             PG8_LDA(At, 1, 1); PG8_STAGE(PG8_SB(1, 0), b3, voffB); PG8_STAGE(PG8_SB(1, 1), b3 + hstep, voffB); PG8_STAGE(PG8_SA(1, 0), a3, voffA);
;             PG8_WAIT_V(8); PG8_WAIT_L(0); PG8_BAR; PG8_MMA(1, 0, At, B0); PG8_MMA(1, 1, At, B1); PG8_BAR; PG8_SCHED;
.LBB0_264:
	ds_read_b128 v[146:149], v167
	ds_read_b128 v[150:153], v167 offset:1024
	ds_read_b128 v[154:157], v167 offset:2048
	ds_read_b128 v[170:173], v167 offset:3072
	ds_read_b128 v[174:177], v168
	ds_read_b128 v[178:181], v168 offset:1024
	ds_read_b128 v[182:185], v168 offset:2048
	ds_read_b128 v[186:189], v168 offset:3072
	s_add_i32 s58, s34, 2
	s_add_u32 s35, s30, 0xffea0080
	s_addc_u32 s38, s31, -1
	s_cmp_eq_u32 s55, s34
	s_cselect_b32 s34, s28, s56
	s_cselect_b32 s39, s27, s38
	s_cselect_b32 s38, s26, s35
	s_cselect_b32 s35, s29, s57
	s_add_i32 m0, s17, 0xc000
	ds_read_b128 v[190:193], v169
	ds_read_b128 v[194:197], v169 offset:1024
	ds_read_b128 v[198:201], v169 offset:2048
	ds_read_b128 v[202:205], v169 offset:3072
	ds_read_b128 v[206:209], v169 offset:4096
	ds_read_b128 v[210:213], v169 offset:5120
	ds_read_b128 v[214:217], v169 offset:6144
	ds_read_b128 v[218:221], v169 offset:7168
	global_load_lds_dwordx4 v136, s[30:31]
	s_add_i32 m0, s17, 0xe000
	s_nop 0
	global_load_lds_dwordx4 v138, s[30:31]
	s_waitcnt vmcnt(8)
	s_waitcnt lgkmcnt(0)
	s_barrier
	s_waitcnt lgkmcnt(0)
	v_mfma_f32_16x16x32_bf16 v[124:127], v[146:149], v[190:193], v[124:127]
	v_mfma_f32_16x16x32_bf16 v[120:123], v[154:157], v[190:193], v[120:123]
	v_mfma_f32_16x16x32_bf16 v[116:119], v[146:149], v[198:201], v[116:119]
	v_mfma_f32_16x16x32_bf16 v[112:115], v[154:157], v[198:201], v[112:115]
	v_mfma_f32_16x16x32_bf16 v[108:111], v[146:149], v[206:209], v[108:111]
	v_mfma_f32_16x16x32_bf16 v[104:107], v[154:157], v[206:209], v[104:107]
	v_mfma_f32_16x16x32_bf16 v[100:103], v[146:149], v[214:217], v[100:103]
	v_mfma_f32_16x16x32_bf16 v[96:99], v[154:157], v[214:217], v[96:99]
	v_mfma_f32_16x16x32_bf16 v[124:127], v[150:153], v[194:197], v[124:127]
	v_mfma_f32_16x16x32_bf16 v[120:123], v[170:173], v[194:197], v[120:123]
	v_mfma_f32_16x16x32_bf16 v[116:119], v[150:153], v[202:205], v[116:119]
	v_mfma_f32_16x16x32_bf16 v[112:115], v[170:173], v[202:205], v[112:115]
	v_mfma_f32_16x16x32_bf16 v[108:111], v[150:153], v[210:213], v[108:111]
	v_mfma_f32_16x16x32_bf16 v[104:107], v[170:173], v[210:213], v[104:107]
	v_mfma_f32_16x16x32_bf16 v[100:103], v[150:153], v[218:221], v[100:103]
	v_mfma_f32_16x16x32_bf16 v[96:99], v[170:173], v[218:221], v[96:99]
	v_mfma_f32_16x16x32_bf16 v[68:71], v[174:177], v[190:193], v[68:71]
	v_mfma_f32_16x16x32_bf16 v[60:63], v[182:185], v[190:193], v[60:63]
	v_mfma_f32_16x16x32_bf16 v[52:55], v[174:177], v[198:201], v[52:55]
	v_mfma_f32_16x16x32_bf16 v[48:51], v[182:185], v[198:201], v[48:51]
	v_mfma_f32_16x16x32_bf16 v[44:47], v[174:177], v[206:209], v[44:47]
	v_mfma_f32_16x16x32_bf16 v[40:43], v[182:185], v[206:209], v[40:43]
	v_mfma_f32_16x16x32_bf16 v[36:39], v[174:177], v[214:217], v[36:39]
	v_mfma_f32_16x16x32_bf16 v[32:35], v[182:185], v[214:217], v[32:35]
	v_mfma_f32_16x16x32_bf16 v[68:71], v[178:181], v[194:197], v[68:71]
	v_mfma_f32_16x16x32_bf16 v[60:63], v[186:189], v[194:197], v[60:63]
	v_mfma_f32_16x16x32_bf16 v[52:55], v[178:181], v[202:205], v[52:55]
	v_mfma_f32_16x16x32_bf16 v[48:51], v[186:189], v[202:205], v[48:51]
	v_mfma_f32_16x16x32_bf16 v[44:47], v[178:181], v[210:213], v[44:47]
	v_mfma_f32_16x16x32_bf16 v[40:43], v[186:189], v[210:213], v[40:43]
	v_mfma_f32_16x16x32_bf16 v[36:39], v[178:181], v[218:221], v[36:39]
	v_mfma_f32_16x16x32_bf16 v[32:35], v[186:189], v[218:221], v[32:35]
	s_barrier
	s_add_i32 s59, s46, s16
	s_mov_b32 m0, s59
	ds_read_b128 v[190:193], v169 offset:16384
	ds_read_b128 v[194:197], v169 offset:17408
	ds_read_b128 v[198:201], v169 offset:18432
	ds_read_b128 v[202:205], v169 offset:19456
	ds_read_b128 v[206:209], v169 offset:20480
	ds_read_b128 v[210:213], v169 offset:21504
	ds_read_b128 v[214:217], v169 offset:22528
	ds_read_b128 v[218:221], v169 offset:23552
	global_load_lds_dwordx4 v130, s[34:35]
	s_add_i32 m0, s59, 0x2000
	s_add_u32 s60, s34, 0x160000
	s_addc_u32 s61, s35, 0
	s_add_i32 s59, s47, s16
	global_load_lds_dwordx4 v134, s[34:35]
	s_mov_b32 m0, s59
	s_nop 0
	global_load_lds_dwordx4 v130, s[60:61]
	s_add_i32 m0, s59, 0x2000
	s_nop 0
	global_load_lds_dwordx4 v134, s[60:61]
	s_mov_b32 m0, s17
	s_nop 0
	global_load_lds_dwordx4 v128, s[38:39]
	s_mov_b32 m0, s18
	s_nop 0
	global_load_lds_dwordx4 v132, s[38:39]
	s_waitcnt vmcnt(8)
	s_waitcnt lgkmcnt(0)
	s_barrier
	s_waitcnt lgkmcnt(0)
	v_mfma_f32_16x16x32_bf16 v[92:95], v[146:149], v[190:193], v[92:95]
	v_mfma_f32_16x16x32_bf16 v[88:91], v[154:157], v[190:193], v[88:91]
	v_mfma_f32_16x16x32_bf16 v[84:87], v[146:149], v[198:201], v[84:87]
	v_mfma_f32_16x16x32_bf16 v[80:83], v[154:157], v[198:201], v[80:83]
	v_mfma_f32_16x16x32_bf16 v[76:79], v[146:149], v[206:209], v[76:79]
	v_mfma_f32_16x16x32_bf16 v[72:75], v[154:157], v[206:209], v[72:75]
	v_mfma_f32_16x16x32_bf16 v[64:67], v[146:149], v[214:217], v[64:67]
	v_mfma_f32_16x16x32_bf16 v[56:59], v[154:157], v[214:217], v[56:59]
	v_mfma_f32_16x16x32_bf16 v[92:95], v[150:153], v[194:197], v[92:95]
	v_mfma_f32_16x16x32_bf16 v[88:91], v[170:173], v[194:197], v[88:91]
	v_mfma_f32_16x16x32_bf16 v[84:87], v[150:153], v[202:205], v[84:87]
	v_mfma_f32_16x16x32_bf16 v[80:83], v[170:173], v[202:205], v[80:83]
	v_mfma_f32_16x16x32_bf16 v[76:79], v[150:153], v[210:213], v[76:79]
	v_mfma_f32_16x16x32_bf16 v[72:75], v[170:173], v[210:213], v[72:75]
	v_mfma_f32_16x16x32_bf16 v[64:67], v[150:153], v[218:221], v[64:67]
	v_mfma_f32_16x16x32_bf16 v[56:59], v[170:173], v[218:221], v[56:59]
	v_mfma_f32_16x16x32_bf16 v[28:31], v[174:177], v[190:193], v[28:31]
	v_mfma_f32_16x16x32_bf16 v[24:27], v[182:185], v[190:193], v[24:27]
	v_mfma_f32_16x16x32_bf16 v[20:23], v[174:177], v[198:201], v[20:23]
	v_mfma_f32_16x16x32_bf16 v[16:19], v[182:185], v[198:201], v[16:19]
	v_mfma_f32_16x16x32_bf16 v[12:15], v[174:177], v[206:209], v[12:15]
	v_mfma_f32_16x16x32_bf16 v[8:11], v[182:185], v[206:209], v[8:11]
	v_mfma_f32_16x16x32_bf16 v[4:7], v[174:177], v[214:217], v[4:7]
	v_mfma_f32_16x16x32_bf16 v[0:3], v[182:185], v[214:217], v[0:3]
	v_mfma_f32_16x16x32_bf16 v[28:31], v[178:181], v[194:197], v[28:31]
	v_mfma_f32_16x16x32_bf16 v[24:27], v[186:189], v[194:197], v[24:27]
	v_mfma_f32_16x16x32_bf16 v[20:23], v[178:181], v[202:205], v[20:23]
	v_mfma_f32_16x16x32_bf16 v[16:19], v[186:189], v[202:205], v[16:19]
	v_mfma_f32_16x16x32_bf16 v[12:15], v[178:181], v[210:213], v[12:15]
	v_mfma_f32_16x16x32_bf16 v[8:11], v[186:189], v[210:213], v[8:11]
	v_mfma_f32_16x16x32_bf16 v[4:7], v[178:181], v[218:221], v[4:7]
	v_mfma_f32_16x16x32_bf16 v[0:3], v[186:189], v[218:221], v[0:3]
	s_barrier
; #define PG8_STAGE(bufoff, gbase, voff) do { _Pragma("unroll") for (int _i = 0; _i < 2; ++_i) \
;         __builtin_amdgcn_global_load_lds((const unsigned*)((const char*)(gbase) + (voff)[_i]), (LAS unsigned*)(lds + (bufoff) + ldsw + _i * 8192), 16, 0, 0); } while (0)
; #define PG8_LDA(dst, b, h) do { _Pragma("unroll") for (int m = 0; m < 4; ++m) _Pragma("unroll") for (int k = 0; k < 2; ++k) dst[m][k] = *(const LAS bf16x8*)(lds + PG8_SA(b, h) + aoff + m * 2048 + k * 1024); } while (0)
; #define PG8_LDB(dst, b, h) do { _Pragma("unroll") for (int n = 0; n < 2; ++n) _Pragma("unroll") for (int k = 0; k < 2; ++k) dst[n][k] = *(const LAS bf16x8*)(lds + PG8_SB(b, h) + boff + n * 2048 + k * 1024); } while (0)
; #define PG8_MMA(ai, bj, At, Bt) do { __builtin_amdgcn_s_setprio(1); _Pragma("unroll") for (int m = 0; m < 4; ++m) _Pragma("unroll") for (int n = 0; n < 2; ++n) _Pragma("unroll") for (int k = 0; k < 2; ++k) \
;         acc[ai][bj][m][n] = __builtin_amdgcn_mfma_f32_16x16x32_bf16(Bt[n][k], At[m][k], acc[ai][bj][m][n], 0, 0, 0); __builtin_amdgcn_s_setprio(0); } while (0)
; #define PG8_WAIT_V(n) asm volatile("s_waitcnt vmcnt(" #n ")" ::: "memory")
; #define PG8_WAIT_L(n) asm volatile("s_waitcnt lgkmcnt(" #n ")" ::: "memory")
; #define PG8_BAR __builtin_amdgcn_s_barrier()
; #define PG8_SCHED __builtin_amdgcn_sched_barrier(0)
; __device__ __forceinline__ void gemm_phase(LAS unsigned char* lds, const Params& p, const bf16_t* gA, const bf16_t* gBt, const int gM, const int gN, const int gK, const int epi, const int perm, bf16_t* const Hp, const int goff, const float coef) {
;     ...
;             PG8_LDB(B0, 1, 0); PG8_LDB(B1, 1, 1); PG8_SCHED; PG8_LDA(At, 1, 0); PG8_STAGE(PG8_SA(0, 1), a2 + hstep, voffA);
;             PG8_WAIT_V(8); PG8_WAIT_L(0); PG8_BAR; PG8_MMA(0, 0, At, B0); PG8_MMA(0, 1, At, B1); PG8_BAR; PG8_SCHED;
;             PG8_LDA(At, 1, 1); PG8_STAGE(PG8_SB(1, 0), b3, voffB); PG8_STAGE(PG8_SB(1, 1), b3 + hstep, voffB); PG8_STAGE(PG8_SA(1, 0), a3, voffA);
;             PG8_WAIT_V(8); PG8_WAIT_L(0); PG8_BAR; PG8_MMA(1, 0, At, B0); PG8_MMA(1, 1, At, B1); PG8_BAR; PG8_SCHED;
	s_add_i32 s59, 0, 0x18000
	s_add_i32 s60, 0, 0x1c000
	ds_read_b128 v[146:149], v222
	ds_read_b128 v[150:153], v222 offset:1024
	ds_read_b128 v[154:157], v222 offset:2048
	ds_read_b128 v[170:173], v222 offset:3072
	ds_read_b128 v[174:177], v223
	ds_read_b128 v[178:181], v223 offset:1024
	ds_read_b128 v[182:185], v223 offset:2048
	ds_read_b128 v[186:189], v223 offset:3072
	s_add_u32 s38, s38, 0x160000
	s_addc_u32 s39, s39, 0
	s_mov_b32 m0, s19
	ds_read_b128 v[190:193], v169 offset:32768
	ds_read_b128 v[194:197], v169 offset:33792
	ds_read_b128 v[198:201], v169 offset:34816
	ds_read_b128 v[202:205], v169 offset:35840
	ds_read_b128 v[206:209], v169 offset:36864
	ds_read_b128 v[210:213], v169 offset:37888
	ds_read_b128 v[214:217], v169 offset:38912
	ds_read_b128 v[218:221], v169 offset:39936
	global_load_lds_dwordx4 v128, s[38:39]
	s_mov_b32 m0, s20
	s_nop 0
	global_load_lds_dwordx4 v132, s[38:39]
	s_waitcnt vmcnt(8)
	s_waitcnt lgkmcnt(0)
	s_barrier
	s_waitcnt lgkmcnt(0)
	v_mfma_f32_16x16x32_bf16 v[124:127], v[146:149], v[190:193], v[124:127]
	v_mfma_f32_16x16x32_bf16 v[120:123], v[154:157], v[190:193], v[120:123]
	v_mfma_f32_16x16x32_bf16 v[116:119], v[146:149], v[198:201], v[116:119]
	v_mfma_f32_16x16x32_bf16 v[112:115], v[154:157], v[198:201], v[112:115]
	v_mfma_f32_16x16x32_bf16 v[108:111], v[146:149], v[206:209], v[108:111]
	v_mfma_f32_16x16x32_bf16 v[104:107], v[154:157], v[206:209], v[104:107]
	v_mfma_f32_16x16x32_bf16 v[100:103], v[146:149], v[214:217], v[100:103]
	v_mfma_f32_16x16x32_bf16 v[96:99], v[154:157], v[214:217], v[96:99]
	v_mfma_f32_16x16x32_bf16 v[124:127], v[150:153], v[194:197], v[124:127]
	v_mfma_f32_16x16x32_bf16 v[120:123], v[170:173], v[194:197], v[120:123]
	v_mfma_f32_16x16x32_bf16 v[116:119], v[150:153], v[202:205], v[116:119]
	v_mfma_f32_16x16x32_bf16 v[112:115], v[170:173], v[202:205], v[112:115]
	v_mfma_f32_16x16x32_bf16 v[108:111], v[150:153], v[210:213], v[108:111]
	v_mfma_f32_16x16x32_bf16 v[104:107], v[170:173], v[210:213], v[104:107]
	v_mfma_f32_16x16x32_bf16 v[100:103], v[150:153], v[218:221], v[100:103]
	v_mfma_f32_16x16x32_bf16 v[96:99], v[170:173], v[218:221], v[96:99]
	v_mfma_f32_16x16x32_bf16 v[68:71], v[174:177], v[190:193], v[68:71]
	v_mfma_f32_16x16x32_bf16 v[60:63], v[182:185], v[190:193], v[60:63]
	v_mfma_f32_16x16x32_bf16 v[52:55], v[174:177], v[198:201], v[52:55]
	v_mfma_f32_16x16x32_bf16 v[48:51], v[182:185], v[198:201], v[48:51]
	v_mfma_f32_16x16x32_bf16 v[44:47], v[174:177], v[206:209], v[44:47]
	v_mfma_f32_16x16x32_bf16 v[40:43], v[182:185], v[206:209], v[40:43]
	v_mfma_f32_16x16x32_bf16 v[36:39], v[174:177], v[214:217], v[36:39]
	v_mfma_f32_16x16x32_bf16 v[32:35], v[182:185], v[214:217], v[32:35]
	v_mfma_f32_16x16x32_bf16 v[68:71], v[178:181], v[194:197], v[68:71]
	v_mfma_f32_16x16x32_bf16 v[60:63], v[186:189], v[194:197], v[60:63]
	v_mfma_f32_16x16x32_bf16 v[52:55], v[178:181], v[202:205], v[52:55]
	v_mfma_f32_16x16x32_bf16 v[48:51], v[186:189], v[202:205], v[48:51]
	v_mfma_f32_16x16x32_bf16 v[44:47], v[178:181], v[210:213], v[44:47]
	v_mfma_f32_16x16x32_bf16 v[40:43], v[186:189], v[210:213], v[40:43]
	v_mfma_f32_16x16x32_bf16 v[36:39], v[178:181], v[218:221], v[36:39]
	v_mfma_f32_16x16x32_bf16 v[32:35], v[186:189], v[218:221], v[32:35]
	s_barrier
	s_mov_b64 s[98:99], s[38:39]
	s_add_i32 s38, s59, s16
	s_mov_b32 m0, s38
	ds_read_b128 v[190:193], v169 offset:49152
	ds_read_b128 v[194:197], v169 offset:50176
	ds_read_b128 v[198:201], v169 offset:51200
	ds_read_b128 v[202:205], v169 offset:52224
	ds_read_b128 v[206:209], v169 offset:53248
	ds_read_b128 v[210:213], v169 offset:54272
	ds_read_b128 v[214:217], v169 offset:55296
	ds_read_b128 v[218:221], v169 offset:56320
	s_add_u32 s100, s34, 0x80
	s_addc_u32 s101, s35, 0
	global_load_lds_dwordx4 v130, s[100:101]
	s_add_i32 m0, s38, 0x2000
	s_add_u32 s34, s34, 0x160080
	s_addc_u32 s35, s35, 0
	s_add_i32 s38, s60, s16
	global_load_lds_dwordx4 v134, s[100:101]
	s_mov_b32 m0, s38
	s_nop 0
	global_load_lds_dwordx4 v130, s[34:35]
	s_add_i32 m0, s38, 0x2000
	s_nop 0
	global_load_lds_dwordx4 v134, s[34:35]
	s_mov_b32 m0, s23
	s_nop 0
	s_add_u32 s100, s98, 0xffea0080
	s_addc_u32 s101, s99, -1
	global_load_lds_dwordx4 v128, s[100:101]
	s_mov_b32 m0, s33
	s_nop 0
	global_load_lds_dwordx4 v132, s[100:101]
	s_waitcnt vmcnt(8)
	s_waitcnt lgkmcnt(0)
	s_barrier
	s_waitcnt lgkmcnt(0)
	v_mfma_f32_16x16x32_bf16 v[92:95], v[146:149], v[190:193], v[92:95]
	v_mfma_f32_16x16x32_bf16 v[88:91], v[154:157], v[190:193], v[88:91]
	v_mfma_f32_16x16x32_bf16 v[84:87], v[146:149], v[198:201], v[84:87]
	v_mfma_f32_16x16x32_bf16 v[80:83], v[154:157], v[198:201], v[80:83]
	v_mfma_f32_16x16x32_bf16 v[76:79], v[146:149], v[206:209], v[76:79]
	v_mfma_f32_16x16x32_bf16 v[72:75], v[154:157], v[206:209], v[72:75]
	v_mfma_f32_16x16x32_bf16 v[64:67], v[146:149], v[214:217], v[64:67]
	v_mfma_f32_16x16x32_bf16 v[56:59], v[154:157], v[214:217], v[56:59]
	v_mfma_f32_16x16x32_bf16 v[92:95], v[150:153], v[194:197], v[92:95]
	v_mfma_f32_16x16x32_bf16 v[88:91], v[170:173], v[194:197], v[88:91]
	v_mfma_f32_16x16x32_bf16 v[84:87], v[150:153], v[202:205], v[84:87]
	v_mfma_f32_16x16x32_bf16 v[80:83], v[170:173], v[202:205], v[80:83]
	v_mfma_f32_16x16x32_bf16 v[76:79], v[150:153], v[210:213], v[76:79]
	v_mfma_f32_16x16x32_bf16 v[72:75], v[170:173], v[210:213], v[72:75]
	v_mfma_f32_16x16x32_bf16 v[64:67], v[150:153], v[218:221], v[64:67]
	v_mfma_f32_16x16x32_bf16 v[56:59], v[170:173], v[218:221], v[56:59]
	v_mfma_f32_16x16x32_bf16 v[28:31], v[174:177], v[190:193], v[28:31]
	v_mfma_f32_16x16x32_bf16 v[24:27], v[182:185], v[190:193], v[24:27]
	v_mfma_f32_16x16x32_bf16 v[20:23], v[174:177], v[198:201], v[20:23]
	v_mfma_f32_16x16x32_bf16 v[16:19], v[182:185], v[198:201], v[16:19]
	v_mfma_f32_16x16x32_bf16 v[12:15], v[174:177], v[206:209], v[12:15]
	v_mfma_f32_16x16x32_bf16 v[8:11], v[182:185], v[206:209], v[8:11]
	v_mfma_f32_16x16x32_bf16 v[4:7], v[174:177], v[214:217], v[4:7]
	v_mfma_f32_16x16x32_bf16 v[0:3], v[182:185], v[214:217], v[0:3]
	v_mfma_f32_16x16x32_bf16 v[28:31], v[178:181], v[194:197], v[28:31]
	v_mfma_f32_16x16x32_bf16 v[24:27], v[186:189], v[194:197], v[24:27]
	v_mfma_f32_16x16x32_bf16 v[20:23], v[178:181], v[202:205], v[20:23]
	v_mfma_f32_16x16x32_bf16 v[16:19], v[186:189], v[202:205], v[16:19]
	v_mfma_f32_16x16x32_bf16 v[12:15], v[178:181], v[210:213], v[12:15]
	v_mfma_f32_16x16x32_bf16 v[8:11], v[186:189], v[210:213], v[8:11]
	v_mfma_f32_16x16x32_bf16 v[4:7], v[178:181], v[218:221], v[4:7]
	v_mfma_f32_16x16x32_bf16 v[0:3], v[186:189], v[218:221], v[0:3]
	s_barrier
	s_add_u32 s30, s30, 0x100
	s_addc_u32 s31, s31, 0
	s_add_u32 s56, s56, 0x100
	s_addc_u32 s57, s57, 0
	s_cmp_ge_u32 s58, s54
	s_mov_b64 s[98:99], s[34:35]
	s_mov_b32 s34, s58
	s_cbranch_scc0 .LBB0_264

; #define PG8_STAGE(bufoff, gbase, voff) do { _Pragma("unroll") for (int _i = 0; _i < 2; ++_i) \
;         __builtin_amdgcn_global_load_lds((const unsigned*)((const char*)(gbase) + (voff)[_i]), (LAS unsigned*)(lds + (bufoff) + ldsw + _i * 8192), 16, 0, 0); } while (0)
; #define PG8_WAIT_V(n) asm volatile("s_waitcnt vmcnt(" #n ")" ::: "memory")
; #define PG8_WAIT_L(n) asm volatile("s_waitcnt lgkmcnt(" #n ")" ::: "memory")
; __device__ __forceinline__ void gemm_phase(LAS unsigned char* lds, const Params& p, const bf16_t* gA, const bf16_t* gBt, const int gM, const int gN, const int gK, const int epi, const int perm, bf16_t* const Hp, const int goff, const float coef) {
;     ...
;         const bool has_next = S.next(ui + 1, nxt);
;         const char* nA = has_next ? (const char*)gA + (size_t)nxt.pm * tstep + (nxt.ks > 0 ? nxt.ks * ksl : 0) : cA; const char* nB = has_next ? (const char*)gBt + (size_t)nxt.pn * tstep + (nxt.ks > 0 ? nxt.ks * ksl : 0) : cB;
;         const int nt = cur.ks >= 0 ? ntf / 4 : ntf;
;         for (int t = 0; t < nt; t += 2) {
;             const bool last = (t == nt - 2);
;             const char* a1 = cA + (size_t)(t + 1) * kstep;
;             const char* a2 = last ? nA : cA + (size_t)(t + 2) * kstep; const char* b2 = last ? nB : cB + (size_t)(t + 2) * kstep;
;             const char* a3 = a2 + kstep; const char* b3 = b2 + kstep;
;             PG8_LDB(B0, 0, 0); PG8_LDB(B1, 0, 1); PG8_SCHED; PG8_LDA(At, 0, 0); PG8_STAGE(PG8_SA(1, 1), a1 + hstep, voffA);
;             PG8_WAIT_V(8); PG8_WAIT_L(0); PG8_BAR; PG8_MMA(0, 0, At, B0); PG8_MMA(0, 1, At, B1); PG8_BAR; PG8_SCHED;
;             PG8_LDA(At, 0, 1); PG8_STAGE(PG8_SB(0, 0), b2, voffB); PG8_STAGE(PG8_SB(0, 1), b2 + hstep, voffB); PG8_STAGE(PG8_SA(0, 0), a2, voffA);
;             PG8_WAIT_V(8); PG8_WAIT_L(0); PG8_BAR; PG8_MMA(1, 0, At, B0); PG8_MMA(1, 1, At, B1); PG8_BAR; PG8_SCHED;
;             PG8_LDB(B0, 1, 0); PG8_LDB(B1, 1, 1); PG8_SCHED; PG8_LDA(At, 1, 0); PG8_STAGE(PG8_SA(0, 1), a2 + hstep, voffA);
;             PG8_WAIT_V(8); PG8_WAIT_L(0); PG8_BAR; PG8_MMA(0, 0, At, B0); PG8_MMA(0, 1, At, B1); PG8_BAR; PG8_SCHED;
;             PG8_LDA(At, 1, 1); PG8_STAGE(PG8_SB(1, 0), b3, voffB); PG8_STAGE(PG8_SB(1, 1), b3 + hstep, voffB); PG8_STAGE(PG8_SA(1, 0), a3, voffA);
;             PG8_WAIT_V(8); PG8_WAIT_L(0); PG8_BAR; PG8_MMA(1, 0, At, B0); PG8_MMA(1, 1, At, B1); PG8_BAR; PG8_SCHED;
.LBB0_435:
	s_ashr_i32 s35, s34, 31
	s_lshl_b64 s[14:15], s[34:35], 20
	s_add_u32 s16, s3, s14
	s_addc_u32 s17, s27, s15
	s_lshl_b64 s[14:15], s[6:7], 10
	s_cmp_gt_i32 s6, 0
	s_cselect_b32 s33, s14, 0
	s_cselect_b32 s23, s15, 0
	s_add_u32 s40, s16, s33
	s_addc_u32 s41, s17, s23
	s_and_b64 s[14:15], s[38:39], exec
	s_cselect_b32 s14, s41, s1
	s_cselect_b32 s15, s40, s0
	s_ashr_i32 s37, s36, 31
	s_lshl_b64 s[16:17], s[36:37], 20
	s_add_u32 s16, s29, s16
	s_addc_u32 s17, s31, s17
	s_add_u32 s42, s16, s33
	s_addc_u32 s43, s17, s23
	s_and_b64 s[16:17], s[38:39], exec
	s_cselect_b32 s16, s43, s5
	s_cselect_b32 s17, s42, s4
	s_cmp_gt_i32 s22, -1
	s_cselect_b32 s22, 8, 32
	s_add_i32 s23, s22, -2
	s_add_u32 s0, s0, 0x80080
	s_addc_u32 s1, s1, 0
	s_add_u32 s33, s4, 0x100
	s_mov_b32 s45, 0
	s_addc_u32 s35, s5, 0
	v_add_u32_e32 v168, 0x18000, v171
	v_add_u32_e32 v169, 0x1c000, v171
	ds_read_b128 v[128:131], v180
	ds_read_b128 v[132:135], v180 offset:1024
	ds_read_b128 v[136:139], v180 offset:2048
	ds_read_b128 v[184:187], v180 offset:3072
	ds_read_b128 v[188:191], v181
	ds_read_b128 v[192:195], v181 offset:1024
	ds_read_b128 v[196:199], v181 offset:2048
	ds_read_b128 v[200:203], v181 offset:3072
	s_add_i32 s37, s45, 2
	s_add_u32 s4, s0, 0xfff80080
	s_addc_u32 s5, s1, -1
	s_cmp_eq_u32 s23, s45
	s_cselect_b32 s49, s14, s5
	s_cselect_b32 s48, s15, s4
	s_cselect_b32 s5, s16, s35
	s_cselect_b32 s4, s17, s33
	s_add_i32 m0, s47, 0xc000
	ds_read_b128 v[204:207], v182
	ds_read_b128 v[208:211], v182 offset:1024
	ds_read_b128 v[212:215], v182 offset:2048
	ds_read_b128 v[216:219], v182 offset:3072
	ds_read_b128 v[220:223], v182 offset:4096
	ds_read_b128 v[224:227], v182 offset:5120
	ds_read_b128 v[228:231], v182 offset:6144
	ds_read_b128 v[232:235], v182 offset:7168
	global_load_lds_dwordx4 v160, s[0:1]
	s_add_i32 m0, s47, 0xe000
	s_nop 0
	global_load_lds_dwordx4 v162, s[0:1]
	s_waitcnt vmcnt(8)
	s_waitcnt lgkmcnt(0)
	s_barrier
	s_waitcnt lgkmcnt(0)
	v_mfma_f32_16x16x32_bf16 v[124:127], v[128:131], v[204:207], 0
	v_mfma_f32_16x16x32_bf16 v[120:123], v[136:139], v[204:207], 0
	v_mfma_f32_16x16x32_bf16 v[108:111], v[128:131], v[212:215], 0
	v_mfma_f32_16x16x32_bf16 v[104:107], v[136:139], v[212:215], 0
	v_mfma_f32_16x16x32_bf16 v[92:95], v[128:131], v[220:223], 0
	v_mfma_f32_16x16x32_bf16 v[88:91], v[136:139], v[220:223], 0
	v_mfma_f32_16x16x32_bf16 v[76:79], v[128:131], v[228:231], 0
	v_mfma_f32_16x16x32_bf16 v[72:75], v[136:139], v[228:231], 0
	v_mfma_f32_16x16x32_bf16 v[124:127], v[132:135], v[208:211], v[124:127]
	v_mfma_f32_16x16x32_bf16 v[120:123], v[184:187], v[208:211], v[120:123]
	v_mfma_f32_16x16x32_bf16 v[108:111], v[132:135], v[216:219], v[108:111]
	v_mfma_f32_16x16x32_bf16 v[104:107], v[184:187], v[216:219], v[104:107]
	v_mfma_f32_16x16x32_bf16 v[92:95], v[132:135], v[224:227], v[92:95]
	v_mfma_f32_16x16x32_bf16 v[88:91], v[184:187], v[224:227], v[88:91]
	v_mfma_f32_16x16x32_bf16 v[76:79], v[132:135], v[232:235], v[76:79]
	v_mfma_f32_16x16x32_bf16 v[72:75], v[184:187], v[232:235], v[72:75]
	v_mfma_f32_16x16x32_bf16 v[116:119], v[188:191], v[204:207], 0
	v_mfma_f32_16x16x32_bf16 v[112:115], v[196:199], v[204:207], 0
	v_mfma_f32_16x16x32_bf16 v[100:103], v[188:191], v[212:215], 0
	v_mfma_f32_16x16x32_bf16 v[96:99], v[196:199], v[212:215], 0
	v_mfma_f32_16x16x32_bf16 v[84:87], v[188:191], v[220:223], 0
	v_mfma_f32_16x16x32_bf16 v[80:83], v[196:199], v[220:223], 0
	v_mfma_f32_16x16x32_bf16 v[68:71], v[188:191], v[228:231], 0
	v_mfma_f32_16x16x32_bf16 v[64:67], v[196:199], v[228:231], 0
	v_mfma_f32_16x16x32_bf16 v[116:119], v[192:195], v[208:211], v[116:119]
	v_mfma_f32_16x16x32_bf16 v[112:115], v[200:203], v[208:211], v[112:115]
	v_mfma_f32_16x16x32_bf16 v[100:103], v[192:195], v[216:219], v[100:103]
	v_mfma_f32_16x16x32_bf16 v[96:99], v[200:203], v[216:219], v[96:99]
	v_mfma_f32_16x16x32_bf16 v[84:87], v[192:195], v[224:227], v[84:87]
	v_mfma_f32_16x16x32_bf16 v[80:83], v[200:203], v[224:227], v[80:83]
	v_mfma_f32_16x16x32_bf16 v[68:71], v[192:195], v[232:235], v[68:71]
	v_mfma_f32_16x16x32_bf16 v[64:67], v[200:203], v[232:235], v[64:67]
	s_barrier
	s_add_i32 s45, s19, s52
	s_mov_b32 m0, s45
	ds_read_b128 v[204:207], v182 offset:16384
	ds_read_b128 v[208:211], v182 offset:17408
	ds_read_b128 v[212:215], v182 offset:18432
	ds_read_b128 v[216:219], v182 offset:19456
	ds_read_b128 v[220:223], v182 offset:20480
	ds_read_b128 v[224:227], v182 offset:21504
	ds_read_b128 v[228:231], v182 offset:22528
	ds_read_b128 v[232:235], v182 offset:23552
	global_load_lds_dwordx4 v144, s[4:5]
	s_add_i32 m0, s45, 0x2000
	s_add_u32 s50, s4, 0x80000
	s_addc_u32 s51, s5, 0
	s_add_i32 s45, s21, s52
	global_load_lds_dwordx4 v148, s[4:5]
	s_mov_b32 m0, s45
	s_nop 0
	global_load_lds_dwordx4 v144, s[50:51]
	s_add_i32 m0, s45, 0x2000
	s_nop 0
	global_load_lds_dwordx4 v148, s[50:51]
	s_mov_b32 m0, s47
	s_nop 0
	global_load_lds_dwordx4 v142, s[48:49]
	s_mov_b32 m0, s53
	s_nop 0
	global_load_lds_dwordx4 v146, s[48:49]
	s_waitcnt vmcnt(8)
	s_waitcnt lgkmcnt(0)
	s_barrier
; #define PG8_STAGE(bufoff, gbase, voff) do { _Pragma("unroll") for (int _i = 0; _i < 2; ++_i) \
;         __builtin_amdgcn_global_load_lds((const unsigned*)((const char*)(gbase) + (voff)[_i]), (LAS unsigned*)(lds + (bufoff) + ldsw + _i * 8192), 16, 0, 0); } while (0)
; #define PG8_LDA(dst, b, h) do { _Pragma("unroll") for (int m = 0; m < 4; ++m) _Pragma("unroll") for (int k = 0; k < 2; ++k) dst[m][k] = *(const LAS bf16x8*)(lds + PG8_SA(b, h) + aoff + m * 2048 + k * 1024); } while (0)
; #define PG8_LDB(dst, b, h) do { _Pragma("unroll") for (int n = 0; n < 2; ++n) _Pragma("unroll") for (int k = 0; k < 2; ++k) dst[n][k] = *(const LAS bf16x8*)(lds + PG8_SB(b, h) + boff + n * 2048 + k * 1024); } while (0)
; #define PG8_MMA(ai, bj, At, Bt) do { __builtin_amdgcn_s_setprio(1); _Pragma("unroll") for (int m = 0; m < 4; ++m) _Pragma("unroll") for (int n = 0; n < 2; ++n) _Pragma("unroll") for (int k = 0; k < 2; ++k) \
;         acc[ai][bj][m][n] = __builtin_amdgcn_mfma_f32_16x16x32_bf16(Bt[n][k], At[m][k], acc[ai][bj][m][n], 0, 0, 0); __builtin_amdgcn_s_setprio(0); } while (0)
; #define PG8_WAIT_V(n) asm volatile("s_waitcnt vmcnt(" #n ")" ::: "memory")
; #define PG8_WAIT_L(n) asm volatile("s_waitcnt lgkmcnt(" #n ")" ::: "memory")
; #define PG8_BAR __builtin_amdgcn_s_barrier()
; #define PG8_SCHED __builtin_amdgcn_sched_barrier(0)
; __device__ __forceinline__ void gemm_phase(LAS unsigned char* lds, const Params& p, const bf16_t* gA, const bf16_t* gBt, const int gM, const int gN, const int gK, const int epi, const int perm, bf16_t* const Hp, const int goff, const float coef) {
;     ...
;             PG8_WAIT_V(8); PG8_WAIT_L(0); PG8_BAR; PG8_MMA(0, 0, At, B0); PG8_MMA(0, 1, At, B1); PG8_BAR; PG8_SCHED;
;             PG8_LDA(At, 0, 1); PG8_STAGE(PG8_SB(0, 0), b2, voffB); PG8_STAGE(PG8_SB(0, 1), b2 + hstep, voffB); PG8_STAGE(PG8_SA(0, 0), a2, voffA);
;             PG8_WAIT_V(8); PG8_WAIT_L(0); PG8_BAR; PG8_MMA(1, 0, At, B0); PG8_MMA(1, 1, At, B1); PG8_BAR; PG8_SCHED;
;             PG8_LDB(B0, 1, 0); PG8_LDB(B1, 1, 1); PG8_SCHED; PG8_LDA(At, 1, 0); PG8_STAGE(PG8_SA(0, 1), a2 + hstep, voffA);
;             PG8_WAIT_V(8); PG8_WAIT_L(0); PG8_BAR; PG8_MMA(0, 0, At, B0); PG8_MMA(0, 1, At, B1); PG8_BAR; PG8_SCHED;
	s_waitcnt lgkmcnt(0)
	v_mfma_f32_16x16x32_bf16 v[60:63], v[128:131], v[204:207], 0
	v_mfma_f32_16x16x32_bf16 v[56:59], v[136:139], v[204:207], 0
	v_mfma_f32_16x16x32_bf16 v[44:47], v[128:131], v[212:215], 0
	v_mfma_f32_16x16x32_bf16 v[40:43], v[136:139], v[212:215], 0
	v_mfma_f32_16x16x32_bf16 v[28:31], v[128:131], v[220:223], 0
	v_mfma_f32_16x16x32_bf16 v[24:27], v[136:139], v[220:223], 0
	v_mfma_f32_16x16x32_bf16 v[12:15], v[128:131], v[228:231], 0
	v_mfma_f32_16x16x32_bf16 v[8:11], v[136:139], v[228:231], 0
	v_mfma_f32_16x16x32_bf16 v[60:63], v[132:135], v[208:211], v[60:63]
	v_mfma_f32_16x16x32_bf16 v[56:59], v[184:187], v[208:211], v[56:59]
	v_mfma_f32_16x16x32_bf16 v[44:47], v[132:135], v[216:219], v[44:47]
	v_mfma_f32_16x16x32_bf16 v[40:43], v[184:187], v[216:219], v[40:43]
	v_mfma_f32_16x16x32_bf16 v[28:31], v[132:135], v[224:227], v[28:31]
	v_mfma_f32_16x16x32_bf16 v[24:27], v[184:187], v[224:227], v[24:27]
	v_mfma_f32_16x16x32_bf16 v[12:15], v[132:135], v[232:235], v[12:15]
	v_mfma_f32_16x16x32_bf16 v[8:11], v[184:187], v[232:235], v[8:11]
	v_mfma_f32_16x16x32_bf16 v[52:55], v[188:191], v[204:207], 0
	v_mfma_f32_16x16x32_bf16 v[48:51], v[196:199], v[204:207], 0
	v_mfma_f32_16x16x32_bf16 v[36:39], v[188:191], v[212:215], 0
	v_mfma_f32_16x16x32_bf16 v[32:35], v[196:199], v[212:215], 0
	v_mfma_f32_16x16x32_bf16 v[20:23], v[188:191], v[220:223], 0
	v_mfma_f32_16x16x32_bf16 v[16:19], v[196:199], v[220:223], 0
	v_mfma_f32_16x16x32_bf16 v[4:7], v[188:191], v[228:231], 0
	v_mfma_f32_16x16x32_bf16 v[0:3], v[196:199], v[228:231], 0
	v_mfma_f32_16x16x32_bf16 v[52:55], v[192:195], v[208:211], v[52:55]
	v_mfma_f32_16x16x32_bf16 v[48:51], v[200:203], v[208:211], v[48:51]
	v_mfma_f32_16x16x32_bf16 v[36:39], v[192:195], v[216:219], v[36:39]
	v_mfma_f32_16x16x32_bf16 v[32:35], v[200:203], v[216:219], v[32:35]
	v_mfma_f32_16x16x32_bf16 v[20:23], v[192:195], v[224:227], v[20:23]
	v_mfma_f32_16x16x32_bf16 v[16:19], v[200:203], v[224:227], v[16:19]
	v_mfma_f32_16x16x32_bf16 v[4:7], v[192:195], v[232:235], v[4:7]
	v_mfma_f32_16x16x32_bf16 v[0:3], v[200:203], v[232:235], v[0:3]
	s_barrier
	s_add_i32 s45, 0, 0x18000
	s_add_i32 s50, 0, 0x1c000
	ds_read_b128 v[128:131], v168
	ds_read_b128 v[132:135], v168 offset:1024
	ds_read_b128 v[136:139], v168 offset:2048
	ds_read_b128 v[184:187], v168 offset:3072
	ds_read_b128 v[188:191], v169
	ds_read_b128 v[192:195], v169 offset:1024
	ds_read_b128 v[196:199], v169 offset:2048
	ds_read_b128 v[200:203], v169 offset:3072
	s_add_u32 s48, s48, 0x80000
	s_addc_u32 s49, s49, 0
	s_mov_b32 m0, s54
	ds_read_b128 v[204:207], v182 offset:32768
	ds_read_b128 v[208:211], v182 offset:33792
	ds_read_b128 v[212:215], v182 offset:34816
	ds_read_b128 v[216:219], v182 offset:35840
	ds_read_b128 v[220:223], v182 offset:36864
	ds_read_b128 v[224:227], v182 offset:37888
	ds_read_b128 v[228:231], v182 offset:38912
	ds_read_b128 v[232:235], v182 offset:39936
	global_load_lds_dwordx4 v142, s[48:49]
	s_mov_b32 m0, s55
	s_nop 0
	global_load_lds_dwordx4 v146, s[48:49]
	s_waitcnt vmcnt(8)
	s_waitcnt lgkmcnt(0)
	s_barrier
	s_waitcnt lgkmcnt(0)
	v_mfma_f32_16x16x32_bf16 v[124:127], v[128:131], v[204:207], v[124:127]
	v_mfma_f32_16x16x32_bf16 v[120:123], v[136:139], v[204:207], v[120:123]
	v_mfma_f32_16x16x32_bf16 v[108:111], v[128:131], v[212:215], v[108:111]
	v_mfma_f32_16x16x32_bf16 v[104:107], v[136:139], v[212:215], v[104:107]
	v_mfma_f32_16x16x32_bf16 v[92:95], v[128:131], v[220:223], v[92:95]
	v_mfma_f32_16x16x32_bf16 v[88:91], v[136:139], v[220:223], v[88:91]
	v_mfma_f32_16x16x32_bf16 v[76:79], v[128:131], v[228:231], v[76:79]
	v_mfma_f32_16x16x32_bf16 v[72:75], v[136:139], v[228:231], v[72:75]
	v_mfma_f32_16x16x32_bf16 v[124:127], v[132:135], v[208:211], v[124:127]
	v_mfma_f32_16x16x32_bf16 v[120:123], v[184:187], v[208:211], v[120:123]
	v_mfma_f32_16x16x32_bf16 v[108:111], v[132:135], v[216:219], v[108:111]
	v_mfma_f32_16x16x32_bf16 v[104:107], v[184:187], v[216:219], v[104:107]
	v_mfma_f32_16x16x32_bf16 v[92:95], v[132:135], v[224:227], v[92:95]
	v_mfma_f32_16x16x32_bf16 v[88:91], v[184:187], v[224:227], v[88:91]
	v_mfma_f32_16x16x32_bf16 v[76:79], v[132:135], v[232:235], v[76:79]
	v_mfma_f32_16x16x32_bf16 v[72:75], v[184:187], v[232:235], v[72:75]
	v_mfma_f32_16x16x32_bf16 v[116:119], v[188:191], v[204:207], v[116:119]
	v_mfma_f32_16x16x32_bf16 v[112:115], v[196:199], v[204:207], v[112:115]
	v_mfma_f32_16x16x32_bf16 v[100:103], v[188:191], v[212:215], v[100:103]
	v_mfma_f32_16x16x32_bf16 v[96:99], v[196:199], v[212:215], v[96:99]
	v_mfma_f32_16x16x32_bf16 v[84:87], v[188:191], v[220:223], v[84:87]
	v_mfma_f32_16x16x32_bf16 v[80:83], v[196:199], v[220:223], v[80:83]
	v_mfma_f32_16x16x32_bf16 v[68:71], v[188:191], v[228:231], v[68:71]
	v_mfma_f32_16x16x32_bf16 v[64:67], v[196:199], v[228:231], v[64:67]
	v_mfma_f32_16x16x32_bf16 v[116:119], v[192:195], v[208:211], v[116:119]
	v_mfma_f32_16x16x32_bf16 v[112:115], v[200:203], v[208:211], v[112:115]
	v_mfma_f32_16x16x32_bf16 v[100:103], v[192:195], v[216:219], v[100:103]
	v_mfma_f32_16x16x32_bf16 v[96:99], v[200:203], v[216:219], v[96:99]
	v_mfma_f32_16x16x32_bf16 v[84:87], v[192:195], v[224:227], v[84:87]
	v_mfma_f32_16x16x32_bf16 v[80:83], v[200:203], v[224:227], v[80:83]
	v_mfma_f32_16x16x32_bf16 v[68:71], v[192:195], v[232:235], v[68:71]
	v_mfma_f32_16x16x32_bf16 v[64:67], v[200:203], v[232:235], v[64:67]
	s_barrier
; #define PG8_STAGE(bufoff, gbase, voff) do { _Pragma("unroll") for (int _i = 0; _i < 2; ++_i) \
;         __builtin_amdgcn_global_load_lds((const unsigned*)((const char*)(gbase) + (voff)[_i]), (LAS unsigned*)(lds + (bufoff) + ldsw + _i * 8192), 16, 0, 0); } while (0)
; #define PG8_LDA(dst, b, h) do { _Pragma("unroll") for (int m = 0; m < 4; ++m) _Pragma("unroll") for (int k = 0; k < 2; ++k) dst[m][k] = *(const LAS bf16x8*)(lds + PG8_SA(b, h) + aoff + m * 2048 + k * 1024); } while (0)
; #define PG8_LDB(dst, b, h) do { _Pragma("unroll") for (int n = 0; n < 2; ++n) _Pragma("unroll") for (int k = 0; k < 2; ++k) dst[n][k] = *(const LAS bf16x8*)(lds + PG8_SB(b, h) + boff + n * 2048 + k * 1024); } while (0)
; #define PG8_MMA(ai, bj, At, Bt) do { __builtin_amdgcn_s_setprio(1); _Pragma("unroll") for (int m = 0; m < 4; ++m) _Pragma("unroll") for (int n = 0; n < 2; ++n) _Pragma("unroll") for (int k = 0; k < 2; ++k) \
;         acc[ai][bj][m][n] = __builtin_amdgcn_mfma_f32_16x16x32_bf16(Bt[n][k], At[m][k], acc[ai][bj][m][n], 0, 0, 0); __builtin_amdgcn_s_setprio(0); } while (0)
; #define PG8_WAIT_V(n) asm volatile("s_waitcnt vmcnt(" #n ")" ::: "memory")
; #define PG8_WAIT_L(n) asm volatile("s_waitcnt lgkmcnt(" #n ")" ::: "memory")
; #define PG8_BAR __builtin_amdgcn_s_barrier()
; #define PG8_SCHED __builtin_amdgcn_sched_barrier(0)
; __device__ __forceinline__ void gemm_phase(LAS unsigned char* lds, const Params& p, const bf16_t* gA, const bf16_t* gBt, const int gM, const int gN, const int gK, const int epi, const int perm, bf16_t* const Hp, const int goff, const float coef) {
;     ...
;             PG8_LDB(B0, 0, 0); PG8_LDB(B1, 0, 1); PG8_SCHED; PG8_LDA(At, 0, 0); PG8_STAGE(PG8_SA(1, 1), a1 + hstep, voffA);
;             PG8_WAIT_V(8); PG8_WAIT_L(0); PG8_BAR; PG8_MMA(0, 0, At, B0); PG8_MMA(0, 1, At, B1); PG8_BAR; PG8_SCHED;
;     ...
;             PG8_LDA(At, 1, 1); PG8_STAGE(PG8_SB(1, 0), b3, voffB); PG8_STAGE(PG8_SB(1, 1), b3 + hstep, voffB); PG8_STAGE(PG8_SA(1, 0), a3, voffA);
;             PG8_WAIT_V(8); PG8_WAIT_L(0); PG8_BAR; PG8_MMA(1, 0, At, B0); PG8_MMA(1, 1, At, B1); PG8_BAR; PG8_SCHED;
	s_add_i32 s45, s45, s52
	s_mov_b32 m0, s45
	ds_read_b128 v[204:207], v182 offset:49152
	ds_read_b128 v[208:211], v182 offset:50176
	ds_read_b128 v[212:215], v182 offset:51200
	ds_read_b128 v[216:219], v182 offset:52224
	ds_read_b128 v[220:223], v182 offset:53248
	ds_read_b128 v[224:227], v182 offset:54272
	ds_read_b128 v[228:231], v182 offset:55296
	ds_read_b128 v[232:235], v182 offset:56320
	s_add_u32 s98, s4, 0x80
	s_addc_u32 s99, s5, 0
	global_load_lds_dwordx4 v144, s[98:99]
	s_add_i32 m0, s45, 0x2000
	s_add_u32 s4, s4, 0x80080
	s_addc_u32 s5, s5, 0
	s_add_i32 s45, s50, s52
	global_load_lds_dwordx4 v148, s[98:99]
	s_mov_b32 m0, s45
	s_nop 0
	global_load_lds_dwordx4 v144, s[4:5]
	s_add_i32 m0, s45, 0x2000
	s_nop 0
	global_load_lds_dwordx4 v148, s[4:5]
	s_mov_b32 m0, s57
	s_nop 0
	s_add_u32 s100, s48, 0xfff80080
	s_addc_u32 s101, s49, -1
	global_load_lds_dwordx4 v142, s[100:101]
	s_mov_b32 m0, s58
	s_nop 0
	global_load_lds_dwordx4 v146, s[100:101]
	s_waitcnt vmcnt(8)
	s_waitcnt lgkmcnt(0)
	s_barrier
	s_waitcnt lgkmcnt(0)
	v_mfma_f32_16x16x32_bf16 v[60:63], v[128:131], v[204:207], v[60:63]
	v_mfma_f32_16x16x32_bf16 v[56:59], v[136:139], v[204:207], v[56:59]
	v_mfma_f32_16x16x32_bf16 v[44:47], v[128:131], v[212:215], v[44:47]
	v_mfma_f32_16x16x32_bf16 v[40:43], v[136:139], v[212:215], v[40:43]
	v_mfma_f32_16x16x32_bf16 v[28:31], v[128:131], v[220:223], v[28:31]
	v_mfma_f32_16x16x32_bf16 v[24:27], v[136:139], v[220:223], v[24:27]
	v_mfma_f32_16x16x32_bf16 v[12:15], v[128:131], v[228:231], v[12:15]
	v_mfma_f32_16x16x32_bf16 v[8:11], v[136:139], v[228:231], v[8:11]
	v_mfma_f32_16x16x32_bf16 v[60:63], v[132:135], v[208:211], v[60:63]
	v_mfma_f32_16x16x32_bf16 v[56:59], v[184:187], v[208:211], v[56:59]
	v_mfma_f32_16x16x32_bf16 v[44:47], v[132:135], v[216:219], v[44:47]
	v_mfma_f32_16x16x32_bf16 v[40:43], v[184:187], v[216:219], v[40:43]
	v_mfma_f32_16x16x32_bf16 v[28:31], v[132:135], v[224:227], v[28:31]
	v_mfma_f32_16x16x32_bf16 v[24:27], v[184:187], v[224:227], v[24:27]
	v_mfma_f32_16x16x32_bf16 v[12:15], v[132:135], v[232:235], v[12:15]
	v_mfma_f32_16x16x32_bf16 v[8:11], v[184:187], v[232:235], v[8:11]
	v_mfma_f32_16x16x32_bf16 v[52:55], v[188:191], v[204:207], v[52:55]
	v_mfma_f32_16x16x32_bf16 v[48:51], v[196:199], v[204:207], v[48:51]
	v_mfma_f32_16x16x32_bf16 v[36:39], v[188:191], v[212:215], v[36:39]
	v_mfma_f32_16x16x32_bf16 v[32:35], v[196:199], v[212:215], v[32:35]
	v_mfma_f32_16x16x32_bf16 v[20:23], v[188:191], v[220:223], v[20:23]
	v_mfma_f32_16x16x32_bf16 v[16:19], v[196:199], v[220:223], v[16:19]
	v_mfma_f32_16x16x32_bf16 v[4:7], v[188:191], v[228:231], v[4:7]
	v_mfma_f32_16x16x32_bf16 v[0:3], v[196:199], v[228:231], v[0:3]
	v_mfma_f32_16x16x32_bf16 v[52:55], v[192:195], v[208:211], v[52:55]
	v_mfma_f32_16x16x32_bf16 v[48:51], v[200:203], v[208:211], v[48:51]
	v_mfma_f32_16x16x32_bf16 v[36:39], v[192:195], v[216:219], v[36:39]
	v_mfma_f32_16x16x32_bf16 v[32:35], v[200:203], v[216:219], v[32:35]
	v_mfma_f32_16x16x32_bf16 v[20:23], v[192:195], v[224:227], v[20:23]
	v_mfma_f32_16x16x32_bf16 v[16:19], v[200:203], v[224:227], v[16:19]
	v_mfma_f32_16x16x32_bf16 v[4:7], v[192:195], v[232:235], v[4:7]
	v_mfma_f32_16x16x32_bf16 v[0:3], v[200:203], v[232:235], v[0:3]
	s_barrier
	s_add_u32 s0, s0, 0x100
	s_addc_u32 s1, s1, 0
	s_add_u32 s33, s33, 0x100
	s_addc_u32 s35, s35, 0
	s_cmp_ge_u32 s37, s22
	s_mov_b32 s45, s37
	s_cbranch_scc1 .Lpeel_exit_2
.LBB0_436:
	ds_read_b128 v[128:131], v180
	ds_read_b128 v[132:135], v180 offset:1024
	ds_read_b128 v[136:139], v180 offset:2048
	ds_read_b128 v[184:187], v180 offset:3072
	ds_read_b128 v[188:191], v181
	ds_read_b128 v[192:195], v181 offset:1024
	ds_read_b128 v[196:199], v181 offset:2048
	ds_read_b128 v[200:203], v181 offset:3072
	s_add_i32 s37, s45, 2
	s_add_u32 s4, s0, 0xfff80080
	s_addc_u32 s5, s1, -1
	s_cmp_eq_u32 s23, s45
	s_cselect_b32 s49, s14, s5
	s_cselect_b32 s48, s15, s4
	s_cselect_b32 s5, s16, s35
	s_cselect_b32 s4, s17, s33
	s_add_i32 m0, s47, 0xc000
	ds_read_b128 v[204:207], v182
	ds_read_b128 v[208:211], v182 offset:1024
	ds_read_b128 v[212:215], v182 offset:2048
	ds_read_b128 v[216:219], v182 offset:3072
	ds_read_b128 v[220:223], v182 offset:4096
	ds_read_b128 v[224:227], v182 offset:5120
	ds_read_b128 v[228:231], v182 offset:6144
	ds_read_b128 v[232:235], v182 offset:7168
	global_load_lds_dwordx4 v160, s[0:1]
	s_add_i32 m0, s47, 0xe000
	s_nop 0
	global_load_lds_dwordx4 v162, s[0:1]
	s_waitcnt vmcnt(8)
	s_waitcnt lgkmcnt(0)
	s_barrier
	s_waitcnt lgkmcnt(0)
	v_mfma_f32_16x16x32_bf16 v[124:127], v[128:131], v[204:207], v[124:127]
	v_mfma_f32_16x16x32_bf16 v[120:123], v[136:139], v[204:207], v[120:123]
	v_mfma_f32_16x16x32_bf16 v[108:111], v[128:131], v[212:215], v[108:111]
	v_mfma_f32_16x16x32_bf16 v[104:107], v[136:139], v[212:215], v[104:107]
	v_mfma_f32_16x16x32_bf16 v[92:95], v[128:131], v[220:223], v[92:95]
	v_mfma_f32_16x16x32_bf16 v[88:91], v[136:139], v[220:223], v[88:91]
	v_mfma_f32_16x16x32_bf16 v[76:79], v[128:131], v[228:231], v[76:79]
	v_mfma_f32_16x16x32_bf16 v[72:75], v[136:139], v[228:231], v[72:75]
	v_mfma_f32_16x16x32_bf16 v[124:127], v[132:135], v[208:211], v[124:127]
	v_mfma_f32_16x16x32_bf16 v[120:123], v[184:187], v[208:211], v[120:123]
	v_mfma_f32_16x16x32_bf16 v[108:111], v[132:135], v[216:219], v[108:111]
	v_mfma_f32_16x16x32_bf16 v[104:107], v[184:187], v[216:219], v[104:107]
	v_mfma_f32_16x16x32_bf16 v[92:95], v[132:135], v[224:227], v[92:95]
	v_mfma_f32_16x16x32_bf16 v[88:91], v[184:187], v[224:227], v[88:91]
	v_mfma_f32_16x16x32_bf16 v[76:79], v[132:135], v[232:235], v[76:79]
	v_mfma_f32_16x16x32_bf16 v[72:75], v[184:187], v[232:235], v[72:75]
	v_mfma_f32_16x16x32_bf16 v[116:119], v[188:191], v[204:207], v[116:119]
	v_mfma_f32_16x16x32_bf16 v[112:115], v[196:199], v[204:207], v[112:115]
	v_mfma_f32_16x16x32_bf16 v[100:103], v[188:191], v[212:215], v[100:103]
	v_mfma_f32_16x16x32_bf16 v[96:99], v[196:199], v[212:215], v[96:99]
	v_mfma_f32_16x16x32_bf16 v[84:87], v[188:191], v[220:223], v[84:87]
	v_mfma_f32_16x16x32_bf16 v[80:83], v[196:199], v[220:223], v[80:83]
	v_mfma_f32_16x16x32_bf16 v[68:71], v[188:191], v[228:231], v[68:71]
	v_mfma_f32_16x16x32_bf16 v[64:67], v[196:199], v[228:231], v[64:67]
	v_mfma_f32_16x16x32_bf16 v[116:119], v[192:195], v[208:211], v[116:119]
	v_mfma_f32_16x16x32_bf16 v[112:115], v[200:203], v[208:211], v[112:115]
	v_mfma_f32_16x16x32_bf16 v[100:103], v[192:195], v[216:219], v[100:103]
	v_mfma_f32_16x16x32_bf16 v[96:99], v[200:203], v[216:219], v[96:99]
	v_mfma_f32_16x16x32_bf16 v[84:87], v[192:195], v[224:227], v[84:87]
	v_mfma_f32_16x16x32_bf16 v[80:83], v[200:203], v[224:227], v[80:83]
	v_mfma_f32_16x16x32_bf16 v[68:71], v[192:195], v[232:235], v[68:71]
	v_mfma_f32_16x16x32_bf16 v[64:67], v[200:203], v[232:235], v[64:67]
	s_barrier
; #define PG8_STAGE(bufoff, gbase, voff) do { _Pragma("unroll") for (int _i = 0; _i < 2; ++_i) \
;         __builtin_amdgcn_global_load_lds((const unsigned*)((const char*)(gbase) + (voff)[_i]), (LAS unsigned*)(lds + (bufoff) + ldsw + _i * 8192), 16, 0, 0); } while (0)
; #define PG8_LDA(dst, b, h) do { _Pragma("unroll") for (int m = 0; m < 4; ++m) _Pragma("unroll") for (int k = 0; k < 2; ++k) dst[m][k] = *(const LAS bf16x8*)(lds + PG8_SA(b, h) + aoff + m * 2048 + k * 1024); } while (0)
; #define PG8_LDB(dst, b, h) do { _Pragma("unroll") for (int n = 0; n < 2; ++n) _Pragma("unroll") for (int k = 0; k < 2; ++k) dst[n][k] = *(const LAS bf16x8*)(lds + PG8_SB(b, h) + boff + n * 2048 + k * 1024); } while (0)
; #define PG8_MMA(ai, bj, At, Bt) do { __builtin_amdgcn_s_setprio(1); _Pragma("unroll") for (int m = 0; m < 4; ++m) _Pragma("unroll") for (int n = 0; n < 2; ++n) _Pragma("unroll") for (int k = 0; k < 2; ++k) \
;         acc[ai][bj][m][n] = __builtin_amdgcn_mfma_f32_16x16x32_bf16(Bt[n][k], At[m][k], acc[ai][bj][m][n], 0, 0, 0); __builtin_amdgcn_s_setprio(0); } while (0)
; #define PG8_WAIT_V(n) asm volatile("s_waitcnt vmcnt(" #n ")" ::: "memory")
; #define PG8_WAIT_L(n) asm volatile("s_waitcnt lgkmcnt(" #n ")" ::: "memory")
; #define PG8_BAR __builtin_amdgcn_s_barrier()
; #define PG8_SCHED __builtin_amdgcn_sched_barrier(0)
; __device__ __forceinline__ void gemm_phase(LAS unsigned char* lds, const Params& p, const bf16_t* gA, const bf16_t* gBt, const int gM, const int gN, const int gK, const int epi, const int perm, bf16_t* const Hp, const int goff, const float coef) {
;     ...
;             PG8_LDA(At, 0, 1); PG8_STAGE(PG8_SB(0, 0), b2, voffB); PG8_STAGE(PG8_SB(0, 1), b2 + hstep, voffB); PG8_STAGE(PG8_SA(0, 0), a2, voffA);
;             PG8_WAIT_V(8); PG8_WAIT_L(0); PG8_BAR; PG8_MMA(1, 0, At, B0); PG8_MMA(1, 1, At, B1); PG8_BAR; PG8_SCHED;
;             PG8_LDB(B0, 1, 0); PG8_LDB(B1, 1, 1); PG8_SCHED; PG8_LDA(At, 1, 0); PG8_STAGE(PG8_SA(0, 1), a2 + hstep, voffA);
;             PG8_WAIT_V(8); PG8_WAIT_L(0); PG8_BAR; PG8_MMA(0, 0, At, B0); PG8_MMA(0, 1, At, B1); PG8_BAR; PG8_SCHED;
	s_add_i32 s45, s19, s52
	s_mov_b32 m0, s45
	ds_read_b128 v[204:207], v182 offset:16384
	ds_read_b128 v[208:211], v182 offset:17408
	ds_read_b128 v[212:215], v182 offset:18432
	ds_read_b128 v[216:219], v182 offset:19456
	ds_read_b128 v[220:223], v182 offset:20480
	ds_read_b128 v[224:227], v182 offset:21504
	ds_read_b128 v[228:231], v182 offset:22528
	ds_read_b128 v[232:235], v182 offset:23552
	global_load_lds_dwordx4 v144, s[4:5]
	s_add_i32 m0, s45, 0x2000
	s_add_u32 s50, s4, 0x80000
	s_addc_u32 s51, s5, 0
	s_add_i32 s45, s21, s52
	global_load_lds_dwordx4 v148, s[4:5]
	s_mov_b32 m0, s45
	s_nop 0
	global_load_lds_dwordx4 v144, s[50:51]
	s_add_i32 m0, s45, 0x2000
	s_nop 0
	global_load_lds_dwordx4 v148, s[50:51]
	s_mov_b32 m0, s47
	s_nop 0
	global_load_lds_dwordx4 v142, s[48:49]
	s_mov_b32 m0, s53
	s_nop 0
	global_load_lds_dwordx4 v146, s[48:49]
	s_waitcnt vmcnt(8)
	s_waitcnt lgkmcnt(0)
	s_barrier
	s_waitcnt lgkmcnt(0)
	v_mfma_f32_16x16x32_bf16 v[60:63], v[128:131], v[204:207], v[60:63]
	v_mfma_f32_16x16x32_bf16 v[56:59], v[136:139], v[204:207], v[56:59]
	v_mfma_f32_16x16x32_bf16 v[44:47], v[128:131], v[212:215], v[44:47]
	v_mfma_f32_16x16x32_bf16 v[40:43], v[136:139], v[212:215], v[40:43]
	v_mfma_f32_16x16x32_bf16 v[28:31], v[128:131], v[220:223], v[28:31]
	v_mfma_f32_16x16x32_bf16 v[24:27], v[136:139], v[220:223], v[24:27]
	v_mfma_f32_16x16x32_bf16 v[12:15], v[128:131], v[228:231], v[12:15]
	v_mfma_f32_16x16x32_bf16 v[8:11], v[136:139], v[228:231], v[8:11]
	v_mfma_f32_16x16x32_bf16 v[60:63], v[132:135], v[208:211], v[60:63]
	v_mfma_f32_16x16x32_bf16 v[56:59], v[184:187], v[208:211], v[56:59]
	v_mfma_f32_16x16x32_bf16 v[44:47], v[132:135], v[216:219], v[44:47]
	v_mfma_f32_16x16x32_bf16 v[40:43], v[184:187], v[216:219], v[40:43]
	v_mfma_f32_16x16x32_bf16 v[28:31], v[132:135], v[224:227], v[28:31]
	v_mfma_f32_16x16x32_bf16 v[24:27], v[184:187], v[224:227], v[24:27]
	v_mfma_f32_16x16x32_bf16 v[12:15], v[132:135], v[232:235], v[12:15]
	v_mfma_f32_16x16x32_bf16 v[8:11], v[184:187], v[232:235], v[8:11]
	v_mfma_f32_16x16x32_bf16 v[52:55], v[188:191], v[204:207], v[52:55]
	v_mfma_f32_16x16x32_bf16 v[48:51], v[196:199], v[204:207], v[48:51]
	v_mfma_f32_16x16x32_bf16 v[36:39], v[188:191], v[212:215], v[36:39]
	v_mfma_f32_16x16x32_bf16 v[32:35], v[196:199], v[212:215], v[32:35]
	v_mfma_f32_16x16x32_bf16 v[20:23], v[188:191], v[220:223], v[20:23]
	v_mfma_f32_16x16x32_bf16 v[16:19], v[196:199], v[220:223], v[16:19]
	v_mfma_f32_16x16x32_bf16 v[4:7], v[188:191], v[228:231], v[4:7]
	v_mfma_f32_16x16x32_bf16 v[0:3], v[196:199], v[228:231], v[0:3]
	v_mfma_f32_16x16x32_bf16 v[52:55], v[192:195], v[208:211], v[52:55]
	v_mfma_f32_16x16x32_bf16 v[48:51], v[200:203], v[208:211], v[48:51]
	v_mfma_f32_16x16x32_bf16 v[36:39], v[192:195], v[216:219], v[36:39]
	v_mfma_f32_16x16x32_bf16 v[32:35], v[200:203], v[216:219], v[32:35]
	v_mfma_f32_16x16x32_bf16 v[20:23], v[192:195], v[224:227], v[20:23]
	v_mfma_f32_16x16x32_bf16 v[16:19], v[200:203], v[224:227], v[16:19]
	v_mfma_f32_16x16x32_bf16 v[4:7], v[192:195], v[232:235], v[4:7]
	v_mfma_f32_16x16x32_bf16 v[0:3], v[200:203], v[232:235], v[0:3]
	s_barrier
	s_add_i32 s45, 0, 0x18000
	s_add_i32 s50, 0, 0x1c000
	ds_read_b128 v[128:131], v168
	ds_read_b128 v[132:135], v168 offset:1024
	ds_read_b128 v[136:139], v168 offset:2048
	ds_read_b128 v[184:187], v168 offset:3072
	ds_read_b128 v[188:191], v169
	ds_read_b128 v[192:195], v169 offset:1024
	ds_read_b128 v[196:199], v169 offset:2048
	ds_read_b128 v[200:203], v169 offset:3072
	s_add_u32 s48, s48, 0x80000
	s_addc_u32 s49, s49, 0
	s_mov_b32 m0, s54
	ds_read_b128 v[204:207], v182 offset:32768
	ds_read_b128 v[208:211], v182 offset:33792
	ds_read_b128 v[212:215], v182 offset:34816
	ds_read_b128 v[216:219], v182 offset:35840
	ds_read_b128 v[220:223], v182 offset:36864
	ds_read_b128 v[224:227], v182 offset:37888
	ds_read_b128 v[228:231], v182 offset:38912
	ds_read_b128 v[232:235], v182 offset:39936
	global_load_lds_dwordx4 v142, s[48:49]
	s_mov_b32 m0, s55
	s_nop 0
	global_load_lds_dwordx4 v146, s[48:49]
	s_waitcnt vmcnt(8)
	s_waitcnt lgkmcnt(0)
	s_barrier
; #define PG8_STAGE(bufoff, gbase, voff) do { _Pragma("unroll") for (int _i = 0; _i < 2; ++_i) \
;         __builtin_amdgcn_global_load_lds((const unsigned*)((const char*)(gbase) + (voff)[_i]), (LAS unsigned*)(lds + (bufoff) + ldsw + _i * 8192), 16, 0, 0); } while (0)
; #define PG8_LDA(dst, b, h) do { _Pragma("unroll") for (int m = 0; m < 4; ++m) _Pragma("unroll") for (int k = 0; k < 2; ++k) dst[m][k] = *(const LAS bf16x8*)(lds + PG8_SA(b, h) + aoff + m * 2048 + k * 1024); } while (0)
; #define PG8_LDB(dst, b, h) do { _Pragma("unroll") for (int n = 0; n < 2; ++n) _Pragma("unroll") for (int k = 0; k < 2; ++k) dst[n][k] = *(const LAS bf16x8*)(lds + PG8_SB(b, h) + boff + n * 2048 + k * 1024); } while (0)
; #define PG8_MMA(ai, bj, At, Bt) do { __builtin_amdgcn_s_setprio(1); _Pragma("unroll") for (int m = 0; m < 4; ++m) _Pragma("unroll") for (int n = 0; n < 2; ++n) _Pragma("unroll") for (int k = 0; k < 2; ++k) \
;         acc[ai][bj][m][n] = __builtin_amdgcn_mfma_f32_16x16x32_bf16(Bt[n][k], At[m][k], acc[ai][bj][m][n], 0, 0, 0); __builtin_amdgcn_s_setprio(0); } while (0)
; #define PG8_WAIT_V(n) asm volatile("s_waitcnt vmcnt(" #n ")" ::: "memory")
; #define PG8_WAIT_L(n) asm volatile("s_waitcnt lgkmcnt(" #n ")" ::: "memory")
; #define PG8_BAR __builtin_amdgcn_s_barrier()
; #define PG8_SCHED __builtin_amdgcn_sched_barrier(0)
; __device__ __forceinline__ void gemm_phase(LAS unsigned char* lds, const Params& p, const bf16_t* gA, const bf16_t* gBt, const int gM, const int gN, const int gK, const int epi, const int perm, bf16_t* const Hp, const int goff, const float coef) {
;     ...
;             PG8_LDB(B0, 1, 0); PG8_LDB(B1, 1, 1); PG8_SCHED; PG8_LDA(At, 1, 0); PG8_STAGE(PG8_SA(0, 1), a2 + hstep, voffA);
;             PG8_WAIT_V(8); PG8_WAIT_L(0); PG8_BAR; PG8_MMA(0, 0, At, B0); PG8_MMA(0, 1, At, B1); PG8_BAR; PG8_SCHED;
;             PG8_LDA(At, 1, 1); PG8_STAGE(PG8_SB(1, 0), b3, voffB); PG8_STAGE(PG8_SB(1, 1), b3 + hstep, voffB); PG8_STAGE(PG8_SA(1, 0), a3, voffA);
;             PG8_WAIT_V(8); PG8_WAIT_L(0); PG8_BAR; PG8_MMA(1, 0, At, B0); PG8_MMA(1, 1, At, B1); PG8_BAR; PG8_SCHED;
	s_waitcnt lgkmcnt(0)
	v_mfma_f32_16x16x32_bf16 v[124:127], v[128:131], v[204:207], v[124:127]
	v_mfma_f32_16x16x32_bf16 v[120:123], v[136:139], v[204:207], v[120:123]
	v_mfma_f32_16x16x32_bf16 v[108:111], v[128:131], v[212:215], v[108:111]
	v_mfma_f32_16x16x32_bf16 v[104:107], v[136:139], v[212:215], v[104:107]
	v_mfma_f32_16x16x32_bf16 v[92:95], v[128:131], v[220:223], v[92:95]
	v_mfma_f32_16x16x32_bf16 v[88:91], v[136:139], v[220:223], v[88:91]
	v_mfma_f32_16x16x32_bf16 v[76:79], v[128:131], v[228:231], v[76:79]
	v_mfma_f32_16x16x32_bf16 v[72:75], v[136:139], v[228:231], v[72:75]
	v_mfma_f32_16x16x32_bf16 v[124:127], v[132:135], v[208:211], v[124:127]
	v_mfma_f32_16x16x32_bf16 v[120:123], v[184:187], v[208:211], v[120:123]
	v_mfma_f32_16x16x32_bf16 v[108:111], v[132:135], v[216:219], v[108:111]
	v_mfma_f32_16x16x32_bf16 v[104:107], v[184:187], v[216:219], v[104:107]
	v_mfma_f32_16x16x32_bf16 v[92:95], v[132:135], v[224:227], v[92:95]
	v_mfma_f32_16x16x32_bf16 v[88:91], v[184:187], v[224:227], v[88:91]
	v_mfma_f32_16x16x32_bf16 v[76:79], v[132:135], v[232:235], v[76:79]
	v_mfma_f32_16x16x32_bf16 v[72:75], v[184:187], v[232:235], v[72:75]
	v_mfma_f32_16x16x32_bf16 v[116:119], v[188:191], v[204:207], v[116:119]
	v_mfma_f32_16x16x32_bf16 v[112:115], v[196:199], v[204:207], v[112:115]
	v_mfma_f32_16x16x32_bf16 v[100:103], v[188:191], v[212:215], v[100:103]
	v_mfma_f32_16x16x32_bf16 v[96:99], v[196:199], v[212:215], v[96:99]
	v_mfma_f32_16x16x32_bf16 v[84:87], v[188:191], v[220:223], v[84:87]
	v_mfma_f32_16x16x32_bf16 v[80:83], v[196:199], v[220:223], v[80:83]
	v_mfma_f32_16x16x32_bf16 v[68:71], v[188:191], v[228:231], v[68:71]
	v_mfma_f32_16x16x32_bf16 v[64:67], v[196:199], v[228:231], v[64:67]
	v_mfma_f32_16x16x32_bf16 v[116:119], v[192:195], v[208:211], v[116:119]
	v_mfma_f32_16x16x32_bf16 v[112:115], v[200:203], v[208:211], v[112:115]
	v_mfma_f32_16x16x32_bf16 v[100:103], v[192:195], v[216:219], v[100:103]
	v_mfma_f32_16x16x32_bf16 v[96:99], v[200:203], v[216:219], v[96:99]
	v_mfma_f32_16x16x32_bf16 v[84:87], v[192:195], v[224:227], v[84:87]
	v_mfma_f32_16x16x32_bf16 v[80:83], v[200:203], v[224:227], v[80:83]
	v_mfma_f32_16x16x32_bf16 v[68:71], v[192:195], v[232:235], v[68:71]
	v_mfma_f32_16x16x32_bf16 v[64:67], v[200:203], v[232:235], v[64:67]
	s_barrier
	s_add_i32 s45, s45, s52
	s_mov_b32 m0, s45
	ds_read_b128 v[204:207], v182 offset:49152
	ds_read_b128 v[208:211], v182 offset:50176
	ds_read_b128 v[212:215], v182 offset:51200
	ds_read_b128 v[216:219], v182 offset:52224
	ds_read_b128 v[220:223], v182 offset:53248
	ds_read_b128 v[224:227], v182 offset:54272
	ds_read_b128 v[228:231], v182 offset:55296
	ds_read_b128 v[232:235], v182 offset:56320
	s_add_u32 s98, s4, 0x80
	s_addc_u32 s99, s5, 0
	global_load_lds_dwordx4 v144, s[98:99]
	s_add_i32 m0, s45, 0x2000
	s_add_u32 s4, s4, 0x80080
	s_addc_u32 s5, s5, 0
	s_add_i32 s45, s50, s52
	global_load_lds_dwordx4 v148, s[98:99]
	s_mov_b32 m0, s45
	s_nop 0
	global_load_lds_dwordx4 v144, s[4:5]
	s_add_i32 m0, s45, 0x2000
	s_nop 0
	global_load_lds_dwordx4 v148, s[4:5]
	s_mov_b32 m0, s57
	s_nop 0
	s_add_u32 s100, s48, 0xfff80080
	s_addc_u32 s101, s49, -1
	global_load_lds_dwordx4 v142, s[100:101]
	s_mov_b32 m0, s58
	s_nop 0
	global_load_lds_dwordx4 v146, s[100:101]
	s_waitcnt vmcnt(8)
	s_waitcnt lgkmcnt(0)
	s_barrier
	s_waitcnt lgkmcnt(0)
	v_mfma_f32_16x16x32_bf16 v[60:63], v[128:131], v[204:207], v[60:63]
	v_mfma_f32_16x16x32_bf16 v[56:59], v[136:139], v[204:207], v[56:59]
	v_mfma_f32_16x16x32_bf16 v[44:47], v[128:131], v[212:215], v[44:47]
	v_mfma_f32_16x16x32_bf16 v[40:43], v[136:139], v[212:215], v[40:43]
	v_mfma_f32_16x16x32_bf16 v[28:31], v[128:131], v[220:223], v[28:31]
	v_mfma_f32_16x16x32_bf16 v[24:27], v[136:139], v[220:223], v[24:27]
	v_mfma_f32_16x16x32_bf16 v[12:15], v[128:131], v[228:231], v[12:15]
	v_mfma_f32_16x16x32_bf16 v[8:11], v[136:139], v[228:231], v[8:11]
	v_mfma_f32_16x16x32_bf16 v[60:63], v[132:135], v[208:211], v[60:63]
	v_mfma_f32_16x16x32_bf16 v[56:59], v[184:187], v[208:211], v[56:59]
	v_mfma_f32_16x16x32_bf16 v[44:47], v[132:135], v[216:219], v[44:47]
	v_mfma_f32_16x16x32_bf16 v[40:43], v[184:187], v[216:219], v[40:43]
	v_mfma_f32_16x16x32_bf16 v[28:31], v[132:135], v[224:227], v[28:31]
	v_mfma_f32_16x16x32_bf16 v[24:27], v[184:187], v[224:227], v[24:27]
	v_mfma_f32_16x16x32_bf16 v[12:15], v[132:135], v[232:235], v[12:15]
	v_mfma_f32_16x16x32_bf16 v[8:11], v[184:187], v[232:235], v[8:11]
	v_mfma_f32_16x16x32_bf16 v[52:55], v[188:191], v[204:207], v[52:55]
	v_mfma_f32_16x16x32_bf16 v[48:51], v[196:199], v[204:207], v[48:51]
	v_mfma_f32_16x16x32_bf16 v[36:39], v[188:191], v[212:215], v[36:39]
	v_mfma_f32_16x16x32_bf16 v[32:35], v[196:199], v[212:215], v[32:35]
	v_mfma_f32_16x16x32_bf16 v[20:23], v[188:191], v[220:223], v[20:23]
	v_mfma_f32_16x16x32_bf16 v[16:19], v[196:199], v[220:223], v[16:19]
	v_mfma_f32_16x16x32_bf16 v[4:7], v[188:191], v[228:231], v[4:7]
	v_mfma_f32_16x16x32_bf16 v[0:3], v[196:199], v[228:231], v[0:3]
	v_mfma_f32_16x16x32_bf16 v[52:55], v[192:195], v[208:211], v[52:55]
	v_mfma_f32_16x16x32_bf16 v[48:51], v[200:203], v[208:211], v[48:51]
	v_mfma_f32_16x16x32_bf16 v[36:39], v[192:195], v[216:219], v[36:39]
	v_mfma_f32_16x16x32_bf16 v[32:35], v[200:203], v[216:219], v[32:35]
	v_mfma_f32_16x16x32_bf16 v[20:23], v[192:195], v[224:227], v[20:23]
	v_mfma_f32_16x16x32_bf16 v[16:19], v[200:203], v[224:227], v[16:19]
	v_mfma_f32_16x16x32_bf16 v[4:7], v[192:195], v[232:235], v[4:7]
	v_mfma_f32_16x16x32_bf16 v[0:3], v[200:203], v[232:235], v[0:3]
	s_barrier
	s_add_u32 s0, s0, 0x100
	s_addc_u32 s1, s1, 0
	s_add_u32 s33, s33, 0x100
	s_addc_u32 s35, s35, 0
	s_cmp_ge_u32 s37, s22
	s_mov_b32 s45, s37
	s_cbranch_scc0 .LBB0_436

; #define PG8_STAGE(bufoff, gbase, voff) do { _Pragma("unroll") for (int _i = 0; _i < 2; ++_i) \
;         __builtin_amdgcn_global_load_lds((const unsigned*)((const char*)(gbase) + (voff)[_i]), (LAS unsigned*)(lds + (bufoff) + ldsw + _i * 8192), 16, 0, 0); } while (0)
; #define PG8_WAIT_V(n) asm volatile("s_waitcnt vmcnt(" #n ")" ::: "memory")
; #define PG8_WAIT_L(n) asm volatile("s_waitcnt lgkmcnt(" #n ")" ::: "memory")
; __device__ __forceinline__ void gemm_phase(LAS unsigned char* lds, const Params& p, const bf16_t* gA, const bf16_t* gBt, const int gM, const int gN, const int gK, const int epi, const int perm, bf16_t* const Hp, const int goff, const float coef) {
;     ...
;         const bool has_next = S.next(ui + 1, nxt);
;         const char* nA = has_next ? (const char*)gA + (size_t)nxt.pm * tstep + (nxt.ks > 0 ? nxt.ks * ksl : 0) : cA; const char* nB = has_next ? (const char*)gBt + (size_t)nxt.pn * tstep + (nxt.ks > 0 ? nxt.ks * ksl : 0) : cB;
;         const int nt = cur.ks >= 0 ? ntf / 4 : ntf;
;         for (int t = 0; t < nt; t += 2) {
;             const bool last = (t == nt - 2);
;             const char* a1 = cA + (size_t)(t + 1) * kstep;
;             const char* a2 = last ? nA : cA + (size_t)(t + 2) * kstep; const char* b2 = last ? nB : cB + (size_t)(t + 2) * kstep;
;             const char* a3 = a2 + kstep; const char* b3 = b2 + kstep;
;             PG8_LDB(B0, 0, 0); PG8_LDB(B1, 0, 1); PG8_SCHED; PG8_LDA(At, 0, 0); PG8_STAGE(PG8_SA(1, 1), a1 + hstep, voffA);
;             PG8_WAIT_V(8); PG8_WAIT_L(0); PG8_BAR; PG8_MMA(0, 0, At, B0); PG8_MMA(0, 1, At, B1); PG8_BAR; PG8_SCHED;
;             PG8_LDA(At, 0, 1); PG8_STAGE(PG8_SB(0, 0), b2, voffB); PG8_STAGE(PG8_SB(0, 1), b2 + hstep, voffB); PG8_STAGE(PG8_SA(0, 0), a2, voffA);
;             PG8_WAIT_V(8); PG8_WAIT_L(0); PG8_BAR; PG8_MMA(1, 0, At, B0); PG8_MMA(1, 1, At, B1); PG8_BAR; PG8_SCHED;
;             PG8_LDB(B0, 1, 0); PG8_LDB(B1, 1, 1); PG8_SCHED; PG8_LDA(At, 1, 0); PG8_STAGE(PG8_SA(0, 1), a2 + hstep, voffA);
;             PG8_WAIT_V(8); PG8_WAIT_L(0); PG8_BAR; PG8_MMA(0, 0, At, B0); PG8_MMA(0, 1, At, B1); PG8_BAR; PG8_SCHED;
;             PG8_LDA(At, 1, 1); PG8_STAGE(PG8_SB(1, 0), b3, voffB); PG8_STAGE(PG8_SB(1, 1), b3 + hstep, voffB); PG8_STAGE(PG8_SA(1, 0), a3, voffA);
;             PG8_WAIT_V(8); PG8_WAIT_L(0); PG8_BAR; PG8_MMA(1, 0, At, B0); PG8_MMA(1, 1, At, B1); PG8_BAR; PG8_SCHED;
.LBB0_1592:
	s_ashr_i32 s13, s12, 31
	s_lshl_b64 s[0:1], s[12:13], 20
	s_add_u32 s13, s3, s0
	s_mov_b32 s19, s5
	s_addc_u32 s15, s33, s1
	s_lshl_b64 s[0:1], s[18:19], 10
	s_cmp_gt_i32 s18, 0
	s_cselect_b32 s22, s0, 0
	s_cselect_b32 s23, s1, 0
	s_add_u32 s20, s13, s22
	s_addc_u32 s21, s15, s23
	s_and_b64 s[0:1], s[16:17], exec
	s_cselect_b32 s13, s21, s27
	s_cselect_b32 s19, s20, s26
	s_ashr_i32 s15, s14, 31
	s_lshl_b64 s[0:1], s[14:15], 20
	s_add_u32 s0, s34, s0
	s_addc_u32 s1, s35, s1
	s_add_u32 s22, s0, s22
	s_addc_u32 s23, s1, s23
	s_and_b64 s[0:1], s[16:17], exec
	s_cselect_b32 s15, s23, s29
	s_cselect_b32 s25, s22, s28
	s_cmp_gt_i32 s4, -1
	s_cselect_b64 s[0:1], -1, 0
	s_and_b64 s[52:53], s[0:1], exec
	s_cselect_b32 s52, 8, 32
	s_add_i32 s53, s52, -2
	s_add_u32 s26, s26, 0x80080
	s_addc_u32 s27, s27, 0
	s_add_u32 s54, s28, 0x100
	s_mov_b32 s30, 0
	s_addc_u32 s55, s29, 0
	v_add_u32_e32 v222, 0x18000, v165
	v_add_u32_e32 v223, 0x1c000, v165
	ds_read_b128 v[128:131], v174
	ds_read_b128 v[132:135], v174 offset:1024
	ds_read_b128 v[152:155], v174 offset:2048
	ds_read_b128 v[156:159], v174 offset:3072
	ds_read_b128 v[160:163], v175
	ds_read_b128 v[178:181], v175 offset:1024
	ds_read_b128 v[182:185], v175 offset:2048
	ds_read_b128 v[186:189], v175 offset:3072
	s_add_i32 s56, s30, 2
	s_add_u32 s28, s26, 0xfff80080
	s_addc_u32 s29, s27, -1
	s_cmp_eq_u32 s53, s30
	s_cselect_b32 s30, s19, s28
	s_cselect_b32 s31, s13, s29
	s_cselect_b32 s29, s15, s55
	s_cselect_b32 s28, s25, s54
	s_add_i32 m0, s37, 0xc000
	ds_read_b128 v[190:193], v176
	ds_read_b128 v[194:197], v176 offset:1024
	ds_read_b128 v[198:201], v176 offset:2048
	ds_read_b128 v[202:205], v176 offset:3072
	ds_read_b128 v[206:209], v176 offset:4096
	ds_read_b128 v[210:213], v176 offset:5120
	ds_read_b128 v[214:217], v176 offset:6144
	ds_read_b128 v[218:221], v176 offset:7168
	global_load_lds_dwordx4 v146, s[26:27]
	s_add_i32 m0, s37, 0xe000
	s_nop 0
	global_load_lds_dwordx4 v148, s[26:27]
	s_waitcnt vmcnt(8)
	s_waitcnt lgkmcnt(0)
	s_barrier
	s_waitcnt lgkmcnt(0)
	v_mfma_f32_16x16x32_bf16 v[124:127], v[128:131], v[190:193], 0
	v_mfma_f32_16x16x32_bf16 v[120:123], v[152:155], v[190:193], 0
	v_mfma_f32_16x16x32_bf16 v[116:119], v[128:131], v[198:201], 0
	v_mfma_f32_16x16x32_bf16 v[112:115], v[152:155], v[198:201], 0
	v_mfma_f32_16x16x32_bf16 v[108:111], v[128:131], v[206:209], 0
	v_mfma_f32_16x16x32_bf16 v[104:107], v[152:155], v[206:209], 0
	v_mfma_f32_16x16x32_bf16 v[100:103], v[128:131], v[214:217], 0
	v_mfma_f32_16x16x32_bf16 v[96:99], v[152:155], v[214:217], 0
	v_mfma_f32_16x16x32_bf16 v[124:127], v[132:135], v[194:197], v[124:127]
	v_mfma_f32_16x16x32_bf16 v[120:123], v[156:159], v[194:197], v[120:123]
	v_mfma_f32_16x16x32_bf16 v[116:119], v[132:135], v[202:205], v[116:119]
	v_mfma_f32_16x16x32_bf16 v[112:115], v[156:159], v[202:205], v[112:115]
	v_mfma_f32_16x16x32_bf16 v[108:111], v[132:135], v[210:213], v[108:111]
	v_mfma_f32_16x16x32_bf16 v[104:107], v[156:159], v[210:213], v[104:107]
	v_mfma_f32_16x16x32_bf16 v[100:103], v[132:135], v[218:221], v[100:103]
	v_mfma_f32_16x16x32_bf16 v[96:99], v[156:159], v[218:221], v[96:99]
	v_mfma_f32_16x16x32_bf16 v[68:71], v[160:163], v[190:193], 0
	v_mfma_f32_16x16x32_bf16 v[64:67], v[182:185], v[190:193], 0
	v_mfma_f32_16x16x32_bf16 v[52:55], v[160:163], v[198:201], 0
	v_mfma_f32_16x16x32_bf16 v[48:51], v[182:185], v[198:201], 0
	v_mfma_f32_16x16x32_bf16 v[44:47], v[160:163], v[206:209], 0
	v_mfma_f32_16x16x32_bf16 v[40:43], v[182:185], v[206:209], 0
	v_mfma_f32_16x16x32_bf16 v[36:39], v[160:163], v[214:217], 0
	v_mfma_f32_16x16x32_bf16 v[32:35], v[182:185], v[214:217], 0
	v_mfma_f32_16x16x32_bf16 v[68:71], v[178:181], v[194:197], v[68:71]
	v_mfma_f32_16x16x32_bf16 v[64:67], v[186:189], v[194:197], v[64:67]
	v_mfma_f32_16x16x32_bf16 v[52:55], v[178:181], v[202:205], v[52:55]
	v_mfma_f32_16x16x32_bf16 v[48:51], v[186:189], v[202:205], v[48:51]
	v_mfma_f32_16x16x32_bf16 v[44:47], v[178:181], v[210:213], v[44:47]
	v_mfma_f32_16x16x32_bf16 v[40:43], v[186:189], v[210:213], v[40:43]
	v_mfma_f32_16x16x32_bf16 v[36:39], v[178:181], v[218:221], v[36:39]
	v_mfma_f32_16x16x32_bf16 v[32:35], v[186:189], v[218:221], v[32:35]
	s_barrier
	s_add_i32 s57, s48, s36
	s_mov_b32 m0, s57
	ds_read_b128 v[190:193], v176 offset:16384
	ds_read_b128 v[194:197], v176 offset:17408
	ds_read_b128 v[198:201], v176 offset:18432
	ds_read_b128 v[202:205], v176 offset:19456
	ds_read_b128 v[206:209], v176 offset:20480
	ds_read_b128 v[210:213], v176 offset:21504
	ds_read_b128 v[214:217], v176 offset:22528
	ds_read_b128 v[218:221], v176 offset:23552
	global_load_lds_dwordx4 v138, s[28:29]
	s_add_i32 m0, s57, 0x2000
	s_add_u32 s58, s28, 0x80000
	s_addc_u32 s59, s29, 0
	s_add_i32 s57, s49, s36
	global_load_lds_dwordx4 v144, s[28:29]
	s_mov_b32 m0, s57
	s_nop 0
	global_load_lds_dwordx4 v138, s[58:59]
	s_add_i32 m0, s57, 0x2000
	s_nop 0
	global_load_lds_dwordx4 v144, s[58:59]
	s_mov_b32 m0, s37
	s_nop 0
	global_load_lds_dwordx4 v136, s[30:31]
	s_mov_b32 m0, s38
	s_nop 0
	global_load_lds_dwordx4 v142, s[30:31]
	s_waitcnt vmcnt(8)
	s_waitcnt lgkmcnt(0)
	s_barrier
; #define PG8_STAGE(bufoff, gbase, voff) do { _Pragma("unroll") for (int _i = 0; _i < 2; ++_i) \
;         __builtin_amdgcn_global_load_lds((const unsigned*)((const char*)(gbase) + (voff)[_i]), (LAS unsigned*)(lds + (bufoff) + ldsw + _i * 8192), 16, 0, 0); } while (0)
; #define PG8_LDA(dst, b, h) do { _Pragma("unroll") for (int m = 0; m < 4; ++m) _Pragma("unroll") for (int k = 0; k < 2; ++k) dst[m][k] = *(const LAS bf16x8*)(lds + PG8_SA(b, h) + aoff + m * 2048 + k * 1024); } while (0)
; #define PG8_LDB(dst, b, h) do { _Pragma("unroll") for (int n = 0; n < 2; ++n) _Pragma("unroll") for (int k = 0; k < 2; ++k) dst[n][k] = *(const LAS bf16x8*)(lds + PG8_SB(b, h) + boff + n * 2048 + k * 1024); } while (0)
; #define PG8_MMA(ai, bj, At, Bt) do { __builtin_amdgcn_s_setprio(1); _Pragma("unroll") for (int m = 0; m < 4; ++m) _Pragma("unroll") for (int n = 0; n < 2; ++n) _Pragma("unroll") for (int k = 0; k < 2; ++k) \
;         acc[ai][bj][m][n] = __builtin_amdgcn_mfma_f32_16x16x32_bf16(Bt[n][k], At[m][k], acc[ai][bj][m][n], 0, 0, 0); __builtin_amdgcn_s_setprio(0); } while (0)
; #define PG8_WAIT_V(n) asm volatile("s_waitcnt vmcnt(" #n ")" ::: "memory")
; #define PG8_WAIT_L(n) asm volatile("s_waitcnt lgkmcnt(" #n ")" ::: "memory")
; #define PG8_BAR __builtin_amdgcn_s_barrier()
; #define PG8_SCHED __builtin_amdgcn_sched_barrier(0)
; __device__ __forceinline__ void gemm_phase(LAS unsigned char* lds, const Params& p, const bf16_t* gA, const bf16_t* gBt, const int gM, const int gN, const int gK, const int epi, const int perm, bf16_t* const Hp, const int goff, const float coef) {
;     ...
;             PG8_WAIT_V(8); PG8_WAIT_L(0); PG8_BAR; PG8_MMA(0, 0, At, B0); PG8_MMA(0, 1, At, B1); PG8_BAR; PG8_SCHED;
;             PG8_LDA(At, 0, 1); PG8_STAGE(PG8_SB(0, 0), b2, voffB); PG8_STAGE(PG8_SB(0, 1), b2 + hstep, voffB); PG8_STAGE(PG8_SA(0, 0), a2, voffA);
;             PG8_WAIT_V(8); PG8_WAIT_L(0); PG8_BAR; PG8_MMA(1, 0, At, B0); PG8_MMA(1, 1, At, B1); PG8_BAR; PG8_SCHED;
;             PG8_LDB(B0, 1, 0); PG8_LDB(B1, 1, 1); PG8_SCHED; PG8_LDA(At, 1, 0); PG8_STAGE(PG8_SA(0, 1), a2 + hstep, voffA);
;             PG8_WAIT_V(8); PG8_WAIT_L(0); PG8_BAR; PG8_MMA(0, 0, At, B0); PG8_MMA(0, 1, At, B1); PG8_BAR; PG8_SCHED;
	s_waitcnt lgkmcnt(0)
	v_mfma_f32_16x16x32_bf16 v[92:95], v[128:131], v[190:193], 0
	v_mfma_f32_16x16x32_bf16 v[88:91], v[152:155], v[190:193], 0
	v_mfma_f32_16x16x32_bf16 v[84:87], v[128:131], v[198:201], 0
	v_mfma_f32_16x16x32_bf16 v[80:83], v[152:155], v[198:201], 0
	v_mfma_f32_16x16x32_bf16 v[76:79], v[128:131], v[206:209], 0
	v_mfma_f32_16x16x32_bf16 v[72:75], v[152:155], v[206:209], 0
	v_mfma_f32_16x16x32_bf16 v[60:63], v[128:131], v[214:217], 0
	v_mfma_f32_16x16x32_bf16 v[56:59], v[152:155], v[214:217], 0
	v_mfma_f32_16x16x32_bf16 v[92:95], v[132:135], v[194:197], v[92:95]
	v_mfma_f32_16x16x32_bf16 v[88:91], v[156:159], v[194:197], v[88:91]
	v_mfma_f32_16x16x32_bf16 v[84:87], v[132:135], v[202:205], v[84:87]
	v_mfma_f32_16x16x32_bf16 v[80:83], v[156:159], v[202:205], v[80:83]
	v_mfma_f32_16x16x32_bf16 v[76:79], v[132:135], v[210:213], v[76:79]
	v_mfma_f32_16x16x32_bf16 v[72:75], v[156:159], v[210:213], v[72:75]
	v_mfma_f32_16x16x32_bf16 v[60:63], v[132:135], v[218:221], v[60:63]
	v_mfma_f32_16x16x32_bf16 v[56:59], v[156:159], v[218:221], v[56:59]
	v_mfma_f32_16x16x32_bf16 v[28:31], v[160:163], v[190:193], 0
	v_mfma_f32_16x16x32_bf16 v[24:27], v[182:185], v[190:193], 0
	v_mfma_f32_16x16x32_bf16 v[20:23], v[160:163], v[198:201], 0
	v_mfma_f32_16x16x32_bf16 v[16:19], v[182:185], v[198:201], 0
	v_mfma_f32_16x16x32_bf16 v[12:15], v[160:163], v[206:209], 0
	v_mfma_f32_16x16x32_bf16 v[8:11], v[182:185], v[206:209], 0
	v_mfma_f32_16x16x32_bf16 v[4:7], v[160:163], v[214:217], 0
	v_mfma_f32_16x16x32_bf16 v[0:3], v[182:185], v[214:217], 0
	v_mfma_f32_16x16x32_bf16 v[28:31], v[178:181], v[194:197], v[28:31]
	v_mfma_f32_16x16x32_bf16 v[24:27], v[186:189], v[194:197], v[24:27]
	v_mfma_f32_16x16x32_bf16 v[20:23], v[178:181], v[202:205], v[20:23]
	v_mfma_f32_16x16x32_bf16 v[16:19], v[186:189], v[202:205], v[16:19]
	v_mfma_f32_16x16x32_bf16 v[12:15], v[178:181], v[210:213], v[12:15]
	v_mfma_f32_16x16x32_bf16 v[8:11], v[186:189], v[210:213], v[8:11]
	v_mfma_f32_16x16x32_bf16 v[4:7], v[178:181], v[218:221], v[4:7]
	v_mfma_f32_16x16x32_bf16 v[0:3], v[186:189], v[218:221], v[0:3]
	s_barrier
	s_add_i32 s57, 0, 0x18000
	s_add_i32 s58, 0, 0x1c000
	ds_read_b128 v[128:131], v222
	ds_read_b128 v[132:135], v222 offset:1024
	ds_read_b128 v[152:155], v222 offset:2048
	ds_read_b128 v[156:159], v222 offset:3072
	ds_read_b128 v[160:163], v223
	ds_read_b128 v[178:181], v223 offset:1024
	ds_read_b128 v[182:185], v223 offset:2048
	ds_read_b128 v[186:189], v223 offset:3072
	s_add_u32 s30, s30, 0x80000
	s_addc_u32 s31, s31, 0
	s_mov_b32 m0, s39
	ds_read_b128 v[190:193], v176 offset:32768
	ds_read_b128 v[194:197], v176 offset:33792
	ds_read_b128 v[198:201], v176 offset:34816
	ds_read_b128 v[202:205], v176 offset:35840
	ds_read_b128 v[206:209], v176 offset:36864
	ds_read_b128 v[210:213], v176 offset:37888
	ds_read_b128 v[214:217], v176 offset:38912
	ds_read_b128 v[218:221], v176 offset:39936
	global_load_lds_dwordx4 v136, s[30:31]
	s_mov_b32 m0, s40
	s_nop 0
	global_load_lds_dwordx4 v142, s[30:31]
	s_waitcnt vmcnt(8)
	s_waitcnt lgkmcnt(0)
	s_barrier
	s_waitcnt lgkmcnt(0)
	v_mfma_f32_16x16x32_bf16 v[124:127], v[128:131], v[190:193], v[124:127]
	v_mfma_f32_16x16x32_bf16 v[120:123], v[152:155], v[190:193], v[120:123]
	v_mfma_f32_16x16x32_bf16 v[116:119], v[128:131], v[198:201], v[116:119]
	v_mfma_f32_16x16x32_bf16 v[112:115], v[152:155], v[198:201], v[112:115]
	v_mfma_f32_16x16x32_bf16 v[108:111], v[128:131], v[206:209], v[108:111]
	v_mfma_f32_16x16x32_bf16 v[104:107], v[152:155], v[206:209], v[104:107]
	v_mfma_f32_16x16x32_bf16 v[100:103], v[128:131], v[214:217], v[100:103]
	v_mfma_f32_16x16x32_bf16 v[96:99], v[152:155], v[214:217], v[96:99]
	v_mfma_f32_16x16x32_bf16 v[124:127], v[132:135], v[194:197], v[124:127]
	v_mfma_f32_16x16x32_bf16 v[120:123], v[156:159], v[194:197], v[120:123]
	v_mfma_f32_16x16x32_bf16 v[116:119], v[132:135], v[202:205], v[116:119]
	v_mfma_f32_16x16x32_bf16 v[112:115], v[156:159], v[202:205], v[112:115]
	v_mfma_f32_16x16x32_bf16 v[108:111], v[132:135], v[210:213], v[108:111]
	v_mfma_f32_16x16x32_bf16 v[104:107], v[156:159], v[210:213], v[104:107]
	v_mfma_f32_16x16x32_bf16 v[100:103], v[132:135], v[218:221], v[100:103]
	v_mfma_f32_16x16x32_bf16 v[96:99], v[156:159], v[218:221], v[96:99]
	v_mfma_f32_16x16x32_bf16 v[68:71], v[160:163], v[190:193], v[68:71]
	v_mfma_f32_16x16x32_bf16 v[64:67], v[182:185], v[190:193], v[64:67]
	v_mfma_f32_16x16x32_bf16 v[52:55], v[160:163], v[198:201], v[52:55]
	v_mfma_f32_16x16x32_bf16 v[48:51], v[182:185], v[198:201], v[48:51]
	v_mfma_f32_16x16x32_bf16 v[44:47], v[160:163], v[206:209], v[44:47]
	v_mfma_f32_16x16x32_bf16 v[40:43], v[182:185], v[206:209], v[40:43]
	v_mfma_f32_16x16x32_bf16 v[36:39], v[160:163], v[214:217], v[36:39]
	v_mfma_f32_16x16x32_bf16 v[32:35], v[182:185], v[214:217], v[32:35]
	v_mfma_f32_16x16x32_bf16 v[68:71], v[178:181], v[194:197], v[68:71]
	v_mfma_f32_16x16x32_bf16 v[64:67], v[186:189], v[194:197], v[64:67]
	v_mfma_f32_16x16x32_bf16 v[52:55], v[178:181], v[202:205], v[52:55]
	v_mfma_f32_16x16x32_bf16 v[48:51], v[186:189], v[202:205], v[48:51]
	v_mfma_f32_16x16x32_bf16 v[44:47], v[178:181], v[210:213], v[44:47]
	v_mfma_f32_16x16x32_bf16 v[40:43], v[186:189], v[210:213], v[40:43]
	v_mfma_f32_16x16x32_bf16 v[36:39], v[178:181], v[218:221], v[36:39]
	v_mfma_f32_16x16x32_bf16 v[32:35], v[186:189], v[218:221], v[32:35]
	s_barrier
; #define PG8_STAGE(bufoff, gbase, voff) do { _Pragma("unroll") for (int _i = 0; _i < 2; ++_i) \
;         __builtin_amdgcn_global_load_lds((const unsigned*)((const char*)(gbase) + (voff)[_i]), (LAS unsigned*)(lds + (bufoff) + ldsw + _i * 8192), 16, 0, 0); } while (0)
; #define PG8_LDA(dst, b, h) do { _Pragma("unroll") for (int m = 0; m < 4; ++m) _Pragma("unroll") for (int k = 0; k < 2; ++k) dst[m][k] = *(const LAS bf16x8*)(lds + PG8_SA(b, h) + aoff + m * 2048 + k * 1024); } while (0)
; #define PG8_LDB(dst, b, h) do { _Pragma("unroll") for (int n = 0; n < 2; ++n) _Pragma("unroll") for (int k = 0; k < 2; ++k) dst[n][k] = *(const LAS bf16x8*)(lds + PG8_SB(b, h) + boff + n * 2048 + k * 1024); } while (0)
; #define PG8_MMA(ai, bj, At, Bt) do { __builtin_amdgcn_s_setprio(1); _Pragma("unroll") for (int m = 0; m < 4; ++m) _Pragma("unroll") for (int n = 0; n < 2; ++n) _Pragma("unroll") for (int k = 0; k < 2; ++k) \
;         acc[ai][bj][m][n] = __builtin_amdgcn_mfma_f32_16x16x32_bf16(Bt[n][k], At[m][k], acc[ai][bj][m][n], 0, 0, 0); __builtin_amdgcn_s_setprio(0); } while (0)
; #define PG8_WAIT_V(n) asm volatile("s_waitcnt vmcnt(" #n ")" ::: "memory")
; #define PG8_WAIT_L(n) asm volatile("s_waitcnt lgkmcnt(" #n ")" ::: "memory")
; #define PG8_BAR __builtin_amdgcn_s_barrier()
; #define PG8_SCHED __builtin_amdgcn_sched_barrier(0)
; __device__ __forceinline__ void gemm_phase(LAS unsigned char* lds, const Params& p, const bf16_t* gA, const bf16_t* gBt, const int gM, const int gN, const int gK, const int epi, const int perm, bf16_t* const Hp, const int goff, const float coef) {
;     ...
;             PG8_LDB(B0, 0, 0); PG8_LDB(B1, 0, 1); PG8_SCHED; PG8_LDA(At, 0, 0); PG8_STAGE(PG8_SA(1, 1), a1 + hstep, voffA);
;             PG8_WAIT_V(8); PG8_WAIT_L(0); PG8_BAR; PG8_MMA(0, 0, At, B0); PG8_MMA(0, 1, At, B1); PG8_BAR; PG8_SCHED;
;     ...
;             PG8_LDA(At, 1, 1); PG8_STAGE(PG8_SB(1, 0), b3, voffB); PG8_STAGE(PG8_SB(1, 1), b3 + hstep, voffB); PG8_STAGE(PG8_SA(1, 0), a3, voffA);
;             PG8_WAIT_V(8); PG8_WAIT_L(0); PG8_BAR; PG8_MMA(1, 0, At, B0); PG8_MMA(1, 1, At, B1); PG8_BAR; PG8_SCHED;
	s_mov_b64 s[98:99], s[30:31]
	s_add_i32 s30, s57, s36
	s_mov_b32 m0, s30
	ds_read_b128 v[190:193], v176 offset:49152
	ds_read_b128 v[194:197], v176 offset:50176
	ds_read_b128 v[198:201], v176 offset:51200
	ds_read_b128 v[202:205], v176 offset:52224
	ds_read_b128 v[206:209], v176 offset:53248
	ds_read_b128 v[210:213], v176 offset:54272
	ds_read_b128 v[214:217], v176 offset:55296
	ds_read_b128 v[218:221], v176 offset:56320
	s_add_u32 s100, s28, 0x80
	s_addc_u32 s101, s29, 0
	global_load_lds_dwordx4 v138, s[100:101]
	s_add_i32 m0, s30, 0x2000
	s_add_u32 s28, s28, 0x80080
	s_addc_u32 s29, s29, 0
	s_add_i32 s30, s58, s36
	global_load_lds_dwordx4 v144, s[100:101]
	s_mov_b32 m0, s30
	s_nop 0
	global_load_lds_dwordx4 v138, s[28:29]
	s_add_i32 m0, s30, 0x2000
	s_nop 0
	global_load_lds_dwordx4 v144, s[28:29]
	s_mov_b32 m0, s44
	s_nop 0
	s_add_u32 s100, s98, 0xfff80080
	s_addc_u32 s101, s99, -1
	global_load_lds_dwordx4 v136, s[100:101]
	s_mov_b32 m0, s45
	s_nop 0
	global_load_lds_dwordx4 v142, s[100:101]
	s_waitcnt vmcnt(8)
	s_waitcnt lgkmcnt(0)
	s_barrier
	s_waitcnt lgkmcnt(0)
	v_mfma_f32_16x16x32_bf16 v[92:95], v[128:131], v[190:193], v[92:95]
	v_mfma_f32_16x16x32_bf16 v[88:91], v[152:155], v[190:193], v[88:91]
	v_mfma_f32_16x16x32_bf16 v[84:87], v[128:131], v[198:201], v[84:87]
	v_mfma_f32_16x16x32_bf16 v[80:83], v[152:155], v[198:201], v[80:83]
	v_mfma_f32_16x16x32_bf16 v[76:79], v[128:131], v[206:209], v[76:79]
	v_mfma_f32_16x16x32_bf16 v[72:75], v[152:155], v[206:209], v[72:75]
	v_mfma_f32_16x16x32_bf16 v[60:63], v[128:131], v[214:217], v[60:63]
	v_mfma_f32_16x16x32_bf16 v[56:59], v[152:155], v[214:217], v[56:59]
	v_mfma_f32_16x16x32_bf16 v[92:95], v[132:135], v[194:197], v[92:95]
	v_mfma_f32_16x16x32_bf16 v[88:91], v[156:159], v[194:197], v[88:91]
	v_mfma_f32_16x16x32_bf16 v[84:87], v[132:135], v[202:205], v[84:87]
	v_mfma_f32_16x16x32_bf16 v[80:83], v[156:159], v[202:205], v[80:83]
	v_mfma_f32_16x16x32_bf16 v[76:79], v[132:135], v[210:213], v[76:79]
	v_mfma_f32_16x16x32_bf16 v[72:75], v[156:159], v[210:213], v[72:75]
	v_mfma_f32_16x16x32_bf16 v[60:63], v[132:135], v[218:221], v[60:63]
	v_mfma_f32_16x16x32_bf16 v[56:59], v[156:159], v[218:221], v[56:59]
	v_mfma_f32_16x16x32_bf16 v[28:31], v[160:163], v[190:193], v[28:31]
	v_mfma_f32_16x16x32_bf16 v[24:27], v[182:185], v[190:193], v[24:27]
	v_mfma_f32_16x16x32_bf16 v[20:23], v[160:163], v[198:201], v[20:23]
	v_mfma_f32_16x16x32_bf16 v[16:19], v[182:185], v[198:201], v[16:19]
	v_mfma_f32_16x16x32_bf16 v[12:15], v[160:163], v[206:209], v[12:15]
	v_mfma_f32_16x16x32_bf16 v[8:11], v[182:185], v[206:209], v[8:11]
	v_mfma_f32_16x16x32_bf16 v[4:7], v[160:163], v[214:217], v[4:7]
	v_mfma_f32_16x16x32_bf16 v[0:3], v[182:185], v[214:217], v[0:3]
	v_mfma_f32_16x16x32_bf16 v[28:31], v[178:181], v[194:197], v[28:31]
	v_mfma_f32_16x16x32_bf16 v[24:27], v[186:189], v[194:197], v[24:27]
	v_mfma_f32_16x16x32_bf16 v[20:23], v[178:181], v[202:205], v[20:23]
	v_mfma_f32_16x16x32_bf16 v[16:19], v[186:189], v[202:205], v[16:19]
	v_mfma_f32_16x16x32_bf16 v[12:15], v[178:181], v[210:213], v[12:15]
	v_mfma_f32_16x16x32_bf16 v[8:11], v[186:189], v[210:213], v[8:11]
	v_mfma_f32_16x16x32_bf16 v[4:7], v[178:181], v[218:221], v[4:7]
	v_mfma_f32_16x16x32_bf16 v[0:3], v[186:189], v[218:221], v[0:3]
	s_barrier
	s_add_u32 s26, s26, 0x100
	s_addc_u32 s27, s27, 0
	s_add_u32 s54, s54, 0x100
	s_addc_u32 s55, s55, 0
	s_cmp_ge_u32 s56, s52
	s_mov_b32 s30, s56
	s_cbranch_scc1 .Lpeel_exit_3
.LBB0_1593:
	ds_read_b128 v[128:131], v174
	ds_read_b128 v[132:135], v174 offset:1024
	ds_read_b128 v[152:155], v174 offset:2048
	ds_read_b128 v[156:159], v174 offset:3072
	ds_read_b128 v[160:163], v175
	ds_read_b128 v[178:181], v175 offset:1024
	ds_read_b128 v[182:185], v175 offset:2048
	ds_read_b128 v[186:189], v175 offset:3072
	s_add_i32 s56, s30, 2
	s_add_u32 s28, s26, 0xfff80080
	s_addc_u32 s29, s27, -1
	s_cmp_eq_u32 s53, s30
	s_cselect_b32 s30, s19, s28
	s_cselect_b32 s31, s13, s29
	s_cselect_b32 s29, s15, s55
	s_cselect_b32 s28, s25, s54
	s_add_i32 m0, s37, 0xc000
	ds_read_b128 v[190:193], v176
	ds_read_b128 v[194:197], v176 offset:1024
	ds_read_b128 v[198:201], v176 offset:2048
	ds_read_b128 v[202:205], v176 offset:3072
	ds_read_b128 v[206:209], v176 offset:4096
	ds_read_b128 v[210:213], v176 offset:5120
	ds_read_b128 v[214:217], v176 offset:6144
	ds_read_b128 v[218:221], v176 offset:7168
	global_load_lds_dwordx4 v146, s[26:27]
	s_add_i32 m0, s37, 0xe000
	s_nop 0
	global_load_lds_dwordx4 v148, s[26:27]
	s_waitcnt vmcnt(8)
	s_waitcnt lgkmcnt(0)
	s_barrier
; #define PG8_STAGE(bufoff, gbase, voff) do { _Pragma("unroll") for (int _i = 0; _i < 2; ++_i) \
;         __builtin_amdgcn_global_load_lds((const unsigned*)((const char*)(gbase) + (voff)[_i]), (LAS unsigned*)(lds + (bufoff) + ldsw + _i * 8192), 16, 0, 0); } while (0)
; #define PG8_LDA(dst, b, h) do { _Pragma("unroll") for (int m = 0; m < 4; ++m) _Pragma("unroll") for (int k = 0; k < 2; ++k) dst[m][k] = *(const LAS bf16x8*)(lds + PG8_SA(b, h) + aoff + m * 2048 + k * 1024); } while (0)
; #define PG8_MMA(ai, bj, At, Bt) do { __builtin_amdgcn_s_setprio(1); _Pragma("unroll") for (int m = 0; m < 4; ++m) _Pragma("unroll") for (int n = 0; n < 2; ++n) _Pragma("unroll") for (int k = 0; k < 2; ++k) \
;         acc[ai][bj][m][n] = __builtin_amdgcn_mfma_f32_16x16x32_bf16(Bt[n][k], At[m][k], acc[ai][bj][m][n], 0, 0, 0); __builtin_amdgcn_s_setprio(0); } while (0)
; #define PG8_WAIT_V(n) asm volatile("s_waitcnt vmcnt(" #n ")" ::: "memory")
; #define PG8_WAIT_L(n) asm volatile("s_waitcnt lgkmcnt(" #n ")" ::: "memory")
; #define PG8_BAR __builtin_amdgcn_s_barrier()
; #define PG8_SCHED __builtin_amdgcn_sched_barrier(0)
; __device__ __forceinline__ void gemm_phase(LAS unsigned char* lds, const Params& p, const bf16_t* gA, const bf16_t* gBt, const int gM, const int gN, const int gK, const int epi, const int perm, bf16_t* const Hp, const int goff, const float coef) {
;     ...
;             PG8_WAIT_V(8); PG8_WAIT_L(0); PG8_BAR; PG8_MMA(0, 0, At, B0); PG8_MMA(0, 1, At, B1); PG8_BAR; PG8_SCHED;
;             PG8_LDA(At, 0, 1); PG8_STAGE(PG8_SB(0, 0), b2, voffB); PG8_STAGE(PG8_SB(0, 1), b2 + hstep, voffB); PG8_STAGE(PG8_SA(0, 0), a2, voffA);
;             PG8_WAIT_V(8); PG8_WAIT_L(0); PG8_BAR; PG8_MMA(1, 0, At, B0); PG8_MMA(1, 1, At, B1); PG8_BAR; PG8_SCHED;
	s_waitcnt lgkmcnt(0)
	v_mfma_f32_16x16x32_bf16 v[124:127], v[128:131], v[190:193], v[124:127]
	v_mfma_f32_16x16x32_bf16 v[120:123], v[152:155], v[190:193], v[120:123]
	v_mfma_f32_16x16x32_bf16 v[116:119], v[128:131], v[198:201], v[116:119]
	v_mfma_f32_16x16x32_bf16 v[112:115], v[152:155], v[198:201], v[112:115]
	v_mfma_f32_16x16x32_bf16 v[108:111], v[128:131], v[206:209], v[108:111]
	v_mfma_f32_16x16x32_bf16 v[104:107], v[152:155], v[206:209], v[104:107]
	v_mfma_f32_16x16x32_bf16 v[100:103], v[128:131], v[214:217], v[100:103]
	v_mfma_f32_16x16x32_bf16 v[96:99], v[152:155], v[214:217], v[96:99]
	v_mfma_f32_16x16x32_bf16 v[124:127], v[132:135], v[194:197], v[124:127]
	v_mfma_f32_16x16x32_bf16 v[120:123], v[156:159], v[194:197], v[120:123]
	v_mfma_f32_16x16x32_bf16 v[116:119], v[132:135], v[202:205], v[116:119]
	v_mfma_f32_16x16x32_bf16 v[112:115], v[156:159], v[202:205], v[112:115]
	v_mfma_f32_16x16x32_bf16 v[108:111], v[132:135], v[210:213], v[108:111]
	v_mfma_f32_16x16x32_bf16 v[104:107], v[156:159], v[210:213], v[104:107]
	v_mfma_f32_16x16x32_bf16 v[100:103], v[132:135], v[218:221], v[100:103]
	v_mfma_f32_16x16x32_bf16 v[96:99], v[156:159], v[218:221], v[96:99]
	v_mfma_f32_16x16x32_bf16 v[68:71], v[160:163], v[190:193], v[68:71]
	v_mfma_f32_16x16x32_bf16 v[64:67], v[182:185], v[190:193], v[64:67]
	v_mfma_f32_16x16x32_bf16 v[52:55], v[160:163], v[198:201], v[52:55]
	v_mfma_f32_16x16x32_bf16 v[48:51], v[182:185], v[198:201], v[48:51]
	v_mfma_f32_16x16x32_bf16 v[44:47], v[160:163], v[206:209], v[44:47]
	v_mfma_f32_16x16x32_bf16 v[40:43], v[182:185], v[206:209], v[40:43]
	v_mfma_f32_16x16x32_bf16 v[36:39], v[160:163], v[214:217], v[36:39]
	v_mfma_f32_16x16x32_bf16 v[32:35], v[182:185], v[214:217], v[32:35]
	v_mfma_f32_16x16x32_bf16 v[68:71], v[178:181], v[194:197], v[68:71]
	v_mfma_f32_16x16x32_bf16 v[64:67], v[186:189], v[194:197], v[64:67]
	v_mfma_f32_16x16x32_bf16 v[52:55], v[178:181], v[202:205], v[52:55]
	v_mfma_f32_16x16x32_bf16 v[48:51], v[186:189], v[202:205], v[48:51]
	v_mfma_f32_16x16x32_bf16 v[44:47], v[178:181], v[210:213], v[44:47]
	v_mfma_f32_16x16x32_bf16 v[40:43], v[186:189], v[210:213], v[40:43]
	v_mfma_f32_16x16x32_bf16 v[36:39], v[178:181], v[218:221], v[36:39]
	v_mfma_f32_16x16x32_bf16 v[32:35], v[186:189], v[218:221], v[32:35]
	s_barrier
	s_add_i32 s57, s48, s36
	s_mov_b32 m0, s57
	ds_read_b128 v[190:193], v176 offset:16384
	ds_read_b128 v[194:197], v176 offset:17408
	ds_read_b128 v[198:201], v176 offset:18432
	ds_read_b128 v[202:205], v176 offset:19456
	ds_read_b128 v[206:209], v176 offset:20480
	ds_read_b128 v[210:213], v176 offset:21504
	ds_read_b128 v[214:217], v176 offset:22528
	ds_read_b128 v[218:221], v176 offset:23552
	global_load_lds_dwordx4 v138, s[28:29]
	s_add_i32 m0, s57, 0x2000
	s_add_u32 s58, s28, 0x80000
	s_addc_u32 s59, s29, 0
	s_add_i32 s57, s49, s36
	global_load_lds_dwordx4 v144, s[28:29]
	s_mov_b32 m0, s57
	s_nop 0
	global_load_lds_dwordx4 v138, s[58:59]
	s_add_i32 m0, s57, 0x2000
	s_nop 0
	global_load_lds_dwordx4 v144, s[58:59]
	s_mov_b32 m0, s37
	s_nop 0
	global_load_lds_dwordx4 v136, s[30:31]
	s_mov_b32 m0, s38
	s_nop 0
	global_load_lds_dwordx4 v142, s[30:31]
	s_waitcnt vmcnt(8)
	s_waitcnt lgkmcnt(0)
	s_barrier
	s_waitcnt lgkmcnt(0)
	v_mfma_f32_16x16x32_bf16 v[92:95], v[128:131], v[190:193], v[92:95]
	v_mfma_f32_16x16x32_bf16 v[88:91], v[152:155], v[190:193], v[88:91]
	v_mfma_f32_16x16x32_bf16 v[84:87], v[128:131], v[198:201], v[84:87]
	v_mfma_f32_16x16x32_bf16 v[80:83], v[152:155], v[198:201], v[80:83]
	v_mfma_f32_16x16x32_bf16 v[76:79], v[128:131], v[206:209], v[76:79]
	v_mfma_f32_16x16x32_bf16 v[72:75], v[152:155], v[206:209], v[72:75]
	v_mfma_f32_16x16x32_bf16 v[60:63], v[128:131], v[214:217], v[60:63]
	v_mfma_f32_16x16x32_bf16 v[56:59], v[152:155], v[214:217], v[56:59]
	v_mfma_f32_16x16x32_bf16 v[92:95], v[132:135], v[194:197], v[92:95]
	v_mfma_f32_16x16x32_bf16 v[88:91], v[156:159], v[194:197], v[88:91]
	v_mfma_f32_16x16x32_bf16 v[84:87], v[132:135], v[202:205], v[84:87]
	v_mfma_f32_16x16x32_bf16 v[80:83], v[156:159], v[202:205], v[80:83]
	v_mfma_f32_16x16x32_bf16 v[76:79], v[132:135], v[210:213], v[76:79]
	v_mfma_f32_16x16x32_bf16 v[72:75], v[156:159], v[210:213], v[72:75]
	v_mfma_f32_16x16x32_bf16 v[60:63], v[132:135], v[218:221], v[60:63]
	v_mfma_f32_16x16x32_bf16 v[56:59], v[156:159], v[218:221], v[56:59]
	v_mfma_f32_16x16x32_bf16 v[28:31], v[160:163], v[190:193], v[28:31]
	v_mfma_f32_16x16x32_bf16 v[24:27], v[182:185], v[190:193], v[24:27]
	v_mfma_f32_16x16x32_bf16 v[20:23], v[160:163], v[198:201], v[20:23]
	v_mfma_f32_16x16x32_bf16 v[16:19], v[182:185], v[198:201], v[16:19]
	v_mfma_f32_16x16x32_bf16 v[12:15], v[160:163], v[206:209], v[12:15]
	v_mfma_f32_16x16x32_bf16 v[8:11], v[182:185], v[206:209], v[8:11]
	v_mfma_f32_16x16x32_bf16 v[4:7], v[160:163], v[214:217], v[4:7]
	v_mfma_f32_16x16x32_bf16 v[0:3], v[182:185], v[214:217], v[0:3]
	v_mfma_f32_16x16x32_bf16 v[28:31], v[178:181], v[194:197], v[28:31]
	v_mfma_f32_16x16x32_bf16 v[24:27], v[186:189], v[194:197], v[24:27]
	v_mfma_f32_16x16x32_bf16 v[20:23], v[178:181], v[202:205], v[20:23]
	v_mfma_f32_16x16x32_bf16 v[16:19], v[186:189], v[202:205], v[16:19]
	v_mfma_f32_16x16x32_bf16 v[12:15], v[178:181], v[210:213], v[12:15]
	v_mfma_f32_16x16x32_bf16 v[8:11], v[186:189], v[210:213], v[8:11]
	v_mfma_f32_16x16x32_bf16 v[4:7], v[178:181], v[218:221], v[4:7]
	v_mfma_f32_16x16x32_bf16 v[0:3], v[186:189], v[218:221], v[0:3]
	s_barrier
; #define PG8_STAGE(bufoff, gbase, voff) do { _Pragma("unroll") for (int _i = 0; _i < 2; ++_i) \
;         __builtin_amdgcn_global_load_lds((const unsigned*)((const char*)(gbase) + (voff)[_i]), (LAS unsigned*)(lds + (bufoff) + ldsw + _i * 8192), 16, 0, 0); } while (0)
; #define PG8_LDA(dst, b, h) do { _Pragma("unroll") for (int m = 0; m < 4; ++m) _Pragma("unroll") for (int k = 0; k < 2; ++k) dst[m][k] = *(const LAS bf16x8*)(lds + PG8_SA(b, h) + aoff + m * 2048 + k * 1024); } while (0)
; #define PG8_LDB(dst, b, h) do { _Pragma("unroll") for (int n = 0; n < 2; ++n) _Pragma("unroll") for (int k = 0; k < 2; ++k) dst[n][k] = *(const LAS bf16x8*)(lds + PG8_SB(b, h) + boff + n * 2048 + k * 1024); } while (0)
; #define PG8_MMA(ai, bj, At, Bt) do { __builtin_amdgcn_s_setprio(1); _Pragma("unroll") for (int m = 0; m < 4; ++m) _Pragma("unroll") for (int n = 0; n < 2; ++n) _Pragma("unroll") for (int k = 0; k < 2; ++k) \
;         acc[ai][bj][m][n] = __builtin_amdgcn_mfma_f32_16x16x32_bf16(Bt[n][k], At[m][k], acc[ai][bj][m][n], 0, 0, 0); __builtin_amdgcn_s_setprio(0); } while (0)
; #define PG8_WAIT_V(n) asm volatile("s_waitcnt vmcnt(" #n ")" ::: "memory")
; #define PG8_WAIT_L(n) asm volatile("s_waitcnt lgkmcnt(" #n ")" ::: "memory")
; #define PG8_BAR __builtin_amdgcn_s_barrier()
; #define PG8_SCHED __builtin_amdgcn_sched_barrier(0)
; __device__ __forceinline__ void gemm_phase(LAS unsigned char* lds, const Params& p, const bf16_t* gA, const bf16_t* gBt, const int gM, const int gN, const int gK, const int epi, const int perm, bf16_t* const Hp, const int goff, const float coef) {
;     ...
;             PG8_LDB(B0, 1, 0); PG8_LDB(B1, 1, 1); PG8_SCHED; PG8_LDA(At, 1, 0); PG8_STAGE(PG8_SA(0, 1), a2 + hstep, voffA);
;             PG8_WAIT_V(8); PG8_WAIT_L(0); PG8_BAR; PG8_MMA(0, 0, At, B0); PG8_MMA(0, 1, At, B1); PG8_BAR; PG8_SCHED;
;             PG8_LDA(At, 1, 1); PG8_STAGE(PG8_SB(1, 0), b3, voffB); PG8_STAGE(PG8_SB(1, 1), b3 + hstep, voffB); PG8_STAGE(PG8_SA(1, 0), a3, voffA);
;             PG8_WAIT_V(8); PG8_WAIT_L(0); PG8_BAR; PG8_MMA(1, 0, At, B0); PG8_MMA(1, 1, At, B1); PG8_BAR; PG8_SCHED;
	s_add_i32 s57, 0, 0x18000
	s_add_i32 s58, 0, 0x1c000
	ds_read_b128 v[128:131], v222
	ds_read_b128 v[132:135], v222 offset:1024
	ds_read_b128 v[152:155], v222 offset:2048
	ds_read_b128 v[156:159], v222 offset:3072
	ds_read_b128 v[160:163], v223
	ds_read_b128 v[178:181], v223 offset:1024
	ds_read_b128 v[182:185], v223 offset:2048
	ds_read_b128 v[186:189], v223 offset:3072
	s_add_u32 s30, s30, 0x80000
	s_addc_u32 s31, s31, 0
	s_mov_b32 m0, s39
	ds_read_b128 v[190:193], v176 offset:32768
	ds_read_b128 v[194:197], v176 offset:33792
	ds_read_b128 v[198:201], v176 offset:34816
	ds_read_b128 v[202:205], v176 offset:35840
	ds_read_b128 v[206:209], v176 offset:36864
	ds_read_b128 v[210:213], v176 offset:37888
	ds_read_b128 v[214:217], v176 offset:38912
	ds_read_b128 v[218:221], v176 offset:39936
	global_load_lds_dwordx4 v136, s[30:31]
	s_mov_b32 m0, s40
	s_nop 0
	global_load_lds_dwordx4 v142, s[30:31]
	s_waitcnt vmcnt(8)
	s_waitcnt lgkmcnt(0)
	s_barrier
	s_waitcnt lgkmcnt(0)
	v_mfma_f32_16x16x32_bf16 v[124:127], v[128:131], v[190:193], v[124:127]
	v_mfma_f32_16x16x32_bf16 v[120:123], v[152:155], v[190:193], v[120:123]
	v_mfma_f32_16x16x32_bf16 v[116:119], v[128:131], v[198:201], v[116:119]
	v_mfma_f32_16x16x32_bf16 v[112:115], v[152:155], v[198:201], v[112:115]
	v_mfma_f32_16x16x32_bf16 v[108:111], v[128:131], v[206:209], v[108:111]
	v_mfma_f32_16x16x32_bf16 v[104:107], v[152:155], v[206:209], v[104:107]
	v_mfma_f32_16x16x32_bf16 v[100:103], v[128:131], v[214:217], v[100:103]
	v_mfma_f32_16x16x32_bf16 v[96:99], v[152:155], v[214:217], v[96:99]
	v_mfma_f32_16x16x32_bf16 v[124:127], v[132:135], v[194:197], v[124:127]
	v_mfma_f32_16x16x32_bf16 v[120:123], v[156:159], v[194:197], v[120:123]
	v_mfma_f32_16x16x32_bf16 v[116:119], v[132:135], v[202:205], v[116:119]
	v_mfma_f32_16x16x32_bf16 v[112:115], v[156:159], v[202:205], v[112:115]
	v_mfma_f32_16x16x32_bf16 v[108:111], v[132:135], v[210:213], v[108:111]
	v_mfma_f32_16x16x32_bf16 v[104:107], v[156:159], v[210:213], v[104:107]
	v_mfma_f32_16x16x32_bf16 v[100:103], v[132:135], v[218:221], v[100:103]
	v_mfma_f32_16x16x32_bf16 v[96:99], v[156:159], v[218:221], v[96:99]
	v_mfma_f32_16x16x32_bf16 v[68:71], v[160:163], v[190:193], v[68:71]
	v_mfma_f32_16x16x32_bf16 v[64:67], v[182:185], v[190:193], v[64:67]
	v_mfma_f32_16x16x32_bf16 v[52:55], v[160:163], v[198:201], v[52:55]
	v_mfma_f32_16x16x32_bf16 v[48:51], v[182:185], v[198:201], v[48:51]
	v_mfma_f32_16x16x32_bf16 v[44:47], v[160:163], v[206:209], v[44:47]
	v_mfma_f32_16x16x32_bf16 v[40:43], v[182:185], v[206:209], v[40:43]
	v_mfma_f32_16x16x32_bf16 v[36:39], v[160:163], v[214:217], v[36:39]
	v_mfma_f32_16x16x32_bf16 v[32:35], v[182:185], v[214:217], v[32:35]
	v_mfma_f32_16x16x32_bf16 v[68:71], v[178:181], v[194:197], v[68:71]
	v_mfma_f32_16x16x32_bf16 v[64:67], v[186:189], v[194:197], v[64:67]
	v_mfma_f32_16x16x32_bf16 v[52:55], v[178:181], v[202:205], v[52:55]
	v_mfma_f32_16x16x32_bf16 v[48:51], v[186:189], v[202:205], v[48:51]
	v_mfma_f32_16x16x32_bf16 v[44:47], v[178:181], v[210:213], v[44:47]
	v_mfma_f32_16x16x32_bf16 v[40:43], v[186:189], v[210:213], v[40:43]
	v_mfma_f32_16x16x32_bf16 v[36:39], v[178:181], v[218:221], v[36:39]
	v_mfma_f32_16x16x32_bf16 v[32:35], v[186:189], v[218:221], v[32:35]
	s_barrier
	s_mov_b64 s[98:99], s[30:31]
	s_add_i32 s30, s57, s36
	s_mov_b32 m0, s30
	ds_read_b128 v[190:193], v176 offset:49152
	ds_read_b128 v[194:197], v176 offset:50176
	ds_read_b128 v[198:201], v176 offset:51200
	ds_read_b128 v[202:205], v176 offset:52224
	ds_read_b128 v[206:209], v176 offset:53248
	ds_read_b128 v[210:213], v176 offset:54272
	ds_read_b128 v[214:217], v176 offset:55296
	ds_read_b128 v[218:221], v176 offset:56320
	s_add_u32 s100, s28, 0x80
	s_addc_u32 s101, s29, 0
	global_load_lds_dwordx4 v138, s[100:101]
	s_add_i32 m0, s30, 0x2000
	s_add_u32 s28, s28, 0x80080
	s_addc_u32 s29, s29, 0
	s_add_i32 s30, s58, s36
	global_load_lds_dwordx4 v144, s[100:101]
	s_mov_b32 m0, s30
	s_nop 0
	global_load_lds_dwordx4 v138, s[28:29]
	s_add_i32 m0, s30, 0x2000
	s_nop 0
	global_load_lds_dwordx4 v144, s[28:29]
	s_mov_b32 m0, s44
	s_nop 0
	s_add_u32 s100, s98, 0xfff80080
	s_addc_u32 s101, s99, -1
	global_load_lds_dwordx4 v136, s[100:101]
	s_mov_b32 m0, s45
	s_nop 0
	global_load_lds_dwordx4 v142, s[100:101]
	s_waitcnt vmcnt(8)
	s_waitcnt lgkmcnt(0)
	s_barrier
	s_waitcnt lgkmcnt(0)
	v_mfma_f32_16x16x32_bf16 v[92:95], v[128:131], v[190:193], v[92:95]
	v_mfma_f32_16x16x32_bf16 v[88:91], v[152:155], v[190:193], v[88:91]
	v_mfma_f32_16x16x32_bf16 v[84:87], v[128:131], v[198:201], v[84:87]
	v_mfma_f32_16x16x32_bf16 v[80:83], v[152:155], v[198:201], v[80:83]
	v_mfma_f32_16x16x32_bf16 v[76:79], v[128:131], v[206:209], v[76:79]
	v_mfma_f32_16x16x32_bf16 v[72:75], v[152:155], v[206:209], v[72:75]
	v_mfma_f32_16x16x32_bf16 v[60:63], v[128:131], v[214:217], v[60:63]
	v_mfma_f32_16x16x32_bf16 v[56:59], v[152:155], v[214:217], v[56:59]
	v_mfma_f32_16x16x32_bf16 v[92:95], v[132:135], v[194:197], v[92:95]
	v_mfma_f32_16x16x32_bf16 v[88:91], v[156:159], v[194:197], v[88:91]
	v_mfma_f32_16x16x32_bf16 v[84:87], v[132:135], v[202:205], v[84:87]
	v_mfma_f32_16x16x32_bf16 v[80:83], v[156:159], v[202:205], v[80:83]
	v_mfma_f32_16x16x32_bf16 v[76:79], v[132:135], v[210:213], v[76:79]
	v_mfma_f32_16x16x32_bf16 v[72:75], v[156:159], v[210:213], v[72:75]
	v_mfma_f32_16x16x32_bf16 v[60:63], v[132:135], v[218:221], v[60:63]
	v_mfma_f32_16x16x32_bf16 v[56:59], v[156:159], v[218:221], v[56:59]
	v_mfma_f32_16x16x32_bf16 v[28:31], v[160:163], v[190:193], v[28:31]
	v_mfma_f32_16x16x32_bf16 v[24:27], v[182:185], v[190:193], v[24:27]
	v_mfma_f32_16x16x32_bf16 v[20:23], v[160:163], v[198:201], v[20:23]
	v_mfma_f32_16x16x32_bf16 v[16:19], v[182:185], v[198:201], v[16:19]
	v_mfma_f32_16x16x32_bf16 v[12:15], v[160:163], v[206:209], v[12:15]
	v_mfma_f32_16x16x32_bf16 v[8:11], v[182:185], v[206:209], v[8:11]
	v_mfma_f32_16x16x32_bf16 v[4:7], v[160:163], v[214:217], v[4:7]
	v_mfma_f32_16x16x32_bf16 v[0:3], v[182:185], v[214:217], v[0:3]
	v_mfma_f32_16x16x32_bf16 v[28:31], v[178:181], v[194:197], v[28:31]
	v_mfma_f32_16x16x32_bf16 v[24:27], v[186:189], v[194:197], v[24:27]
	v_mfma_f32_16x16x32_bf16 v[20:23], v[178:181], v[202:205], v[20:23]
	v_mfma_f32_16x16x32_bf16 v[16:19], v[186:189], v[202:205], v[16:19]
	v_mfma_f32_16x16x32_bf16 v[12:15], v[178:181], v[210:213], v[12:15]
	v_mfma_f32_16x16x32_bf16 v[8:11], v[186:189], v[210:213], v[8:11]
	v_mfma_f32_16x16x32_bf16 v[4:7], v[178:181], v[218:221], v[4:7]
	v_mfma_f32_16x16x32_bf16 v[0:3], v[186:189], v[218:221], v[0:3]
	s_barrier
	s_add_u32 s26, s26, 0x100
	s_addc_u32 s27, s27, 0
	s_add_u32 s54, s54, 0x100
	s_addc_u32 s55, s55, 0
	s_cmp_ge_u32 s56, s52
	s_mov_b32 s30, s56
	s_cbranch_scc0 .LBB0_1593

; #define PG8_STAGE(bufoff, gbase, voff) do { _Pragma("unroll") for (int _i = 0; _i < 2; ++_i) \
;         __builtin_amdgcn_global_load_lds((const unsigned*)((const char*)(gbase) + (voff)[_i]), (LAS unsigned*)(lds + (bufoff) + ldsw + _i * 8192), 16, 0, 0); } while (0)
; #define PG8_WAIT_V(n) asm volatile("s_waitcnt vmcnt(" #n ")" ::: "memory")
; #define PG8_WAIT_L(n) asm volatile("s_waitcnt lgkmcnt(" #n ")" ::: "memory")
; __device__ __forceinline__ void gemm_phase(LAS unsigned char* lds, const Params& p, const bf16_t* gA, const bf16_t* gBt, const int gM, const int gN, const int gK, const int epi, const int perm, bf16_t* const Hp, const int goff, const float coef) {
;     ...
;         const bool has_next = S.next(ui + 1, nxt);
;         const char* nA = has_next ? (const char*)gA + (size_t)nxt.pm * tstep + (nxt.ks > 0 ? nxt.ks * ksl : 0) : cA; const char* nB = has_next ? (const char*)gBt + (size_t)nxt.pn * tstep + (nxt.ks > 0 ? nxt.ks * ksl : 0) : cB;
;         const int nt = cur.ks >= 0 ? ntf / 4 : ntf;
;         for (int t = 0; t < nt; t += 2) {
;             const bool last = (t == nt - 2);
;             const char* a1 = cA + (size_t)(t + 1) * kstep;
;             const char* a2 = last ? nA : cA + (size_t)(t + 2) * kstep; const char* b2 = last ? nB : cB + (size_t)(t + 2) * kstep;
;             const char* a3 = a2 + kstep; const char* b3 = b2 + kstep;
;             PG8_LDB(B0, 0, 0); PG8_LDB(B1, 0, 1); PG8_SCHED; PG8_LDA(At, 0, 0); PG8_STAGE(PG8_SA(1, 1), a1 + hstep, voffA);
;             PG8_WAIT_V(8); PG8_WAIT_L(0); PG8_BAR; PG8_MMA(0, 0, At, B0); PG8_MMA(0, 1, At, B1); PG8_BAR; PG8_SCHED;
;             PG8_LDA(At, 0, 1); PG8_STAGE(PG8_SB(0, 0), b2, voffB); PG8_STAGE(PG8_SB(0, 1), b2 + hstep, voffB); PG8_STAGE(PG8_SA(0, 0), a2, voffA);
;             PG8_WAIT_V(8); PG8_WAIT_L(0); PG8_BAR; PG8_MMA(1, 0, At, B0); PG8_MMA(1, 1, At, B1); PG8_BAR; PG8_SCHED;
;             PG8_LDB(B0, 1, 0); PG8_LDB(B1, 1, 1); PG8_SCHED; PG8_LDA(At, 1, 0); PG8_STAGE(PG8_SA(0, 1), a2 + hstep, voffA);
;             PG8_WAIT_V(8); PG8_WAIT_L(0); PG8_BAR; PG8_MMA(0, 0, At, B0); PG8_MMA(0, 1, At, B1); PG8_BAR; PG8_SCHED;
;             PG8_LDA(At, 1, 1); PG8_STAGE(PG8_SB(1, 0), b3, voffB); PG8_STAGE(PG8_SB(1, 1), b3 + hstep, voffB); PG8_STAGE(PG8_SA(1, 0), a3, voffA);
;             PG8_WAIT_V(8); PG8_WAIT_L(0); PG8_BAR; PG8_MMA(1, 0, At, B0); PG8_MMA(1, 1, At, B1); PG8_BAR; PG8_SCHED;
.LBB0_1736:
	s_ashr_i32 s13, s12, 31
	s_lshl_b64 s[18:19], s[12:13], 20
	s_add_u32 s13, s3, s18
	s_addc_u32 s15, s33, s19
	s_lshl_b64 s[18:19], s[0:1], 10
	s_cmp_gt_i32 s0, 0
	s_cselect_b32 s50, s18, 0
	s_cselect_b32 s49, s19, 0
	s_add_u32 s18, s13, s50
	s_addc_u32 s19, s15, s49
	s_and_b64 s[20:21], s[16:17], exec
	s_cselect_b32 s13, s19, s27
	s_cselect_b32 s48, s18, s26
	s_ashr_i32 s15, s14, 31
	s_lshl_b64 s[20:21], s[14:15], 20
	s_add_u32 s15, s34, s20
	s_addc_u32 s21, s35, s21
	s_add_u32 s20, s15, s50
	s_addc_u32 s21, s21, s49
	s_and_b64 s[50:51], s[16:17], exec
	s_cselect_b32 s15, s21, s29
	s_cselect_b32 s49, s20, s28
	s_cmp_gt_i32 s31, -1
	s_cselect_b32 s50, 8, 32
	s_add_i32 s51, s50, -2
	s_add_u32 s26, s26, 0x80080
	s_addc_u32 s27, s27, 0
	s_add_u32 s52, s28, 0x100
	s_mov_b32 s30, 0
	s_addc_u32 s53, s29, 0
	v_add_u32_e32 v224, 0x18000, v147
	v_add_u32_e32 v225, 0x1c000, v147
	ds_read_b128 v[160:163], v156
	ds_read_b128 v[164:167], v156 offset:1024
	ds_read_b128 v[168:171], v156 offset:2048
	ds_read_b128 v[172:175], v156 offset:3072
	ds_read_b128 v[176:179], v157
	ds_read_b128 v[180:183], v157 offset:1024
	ds_read_b128 v[184:187], v157 offset:2048
	ds_read_b128 v[188:191], v157 offset:3072
	s_add_i32 s54, s30, 2
	s_add_u32 s28, s26, 0xfff80080
	s_addc_u32 s29, s27, -1
	s_cmp_eq_u32 s51, s30
	s_cselect_b32 s30, s48, s28
	s_cselect_b32 s31, s13, s29
	s_cselect_b32 s29, s15, s53
	s_cselect_b32 s28, s49, s52
	s_add_i32 m0, s23, 0xc000
	ds_read_b128 v[192:195], v158
	ds_read_b128 v[196:199], v158 offset:1024
	ds_read_b128 v[200:203], v158 offset:2048
	ds_read_b128 v[204:207], v158 offset:3072
	ds_read_b128 v[208:211], v158 offset:4096
	ds_read_b128 v[212:215], v158 offset:5120
	ds_read_b128 v[216:219], v158 offset:6144
	ds_read_b128 v[220:223], v158 offset:7168
	global_load_lds_dwordx4 v136, s[26:27]
	s_add_i32 m0, s23, 0xe000
	s_nop 0
	global_load_lds_dwordx4 v138, s[26:27]
	s_waitcnt vmcnt(8)
	s_waitcnt lgkmcnt(0)
	s_barrier
	s_waitcnt lgkmcnt(0)
	v_mfma_f32_16x16x32_bf16 v[124:127], v[160:163], v[192:195], 0
	v_mfma_f32_16x16x32_bf16 v[120:123], v[168:171], v[192:195], 0
	v_mfma_f32_16x16x32_bf16 v[108:111], v[160:163], v[200:203], 0
	v_mfma_f32_16x16x32_bf16 v[104:107], v[168:171], v[200:203], 0
	v_mfma_f32_16x16x32_bf16 v[92:95], v[160:163], v[208:211], 0
	v_mfma_f32_16x16x32_bf16 v[88:91], v[168:171], v[208:211], 0
	v_mfma_f32_16x16x32_bf16 v[76:79], v[160:163], v[216:219], 0
	v_mfma_f32_16x16x32_bf16 v[72:75], v[168:171], v[216:219], 0
	v_mfma_f32_16x16x32_bf16 v[124:127], v[164:167], v[196:199], v[124:127]
	v_mfma_f32_16x16x32_bf16 v[120:123], v[172:175], v[196:199], v[120:123]
	v_mfma_f32_16x16x32_bf16 v[108:111], v[164:167], v[204:207], v[108:111]
	v_mfma_f32_16x16x32_bf16 v[104:107], v[172:175], v[204:207], v[104:107]
	v_mfma_f32_16x16x32_bf16 v[92:95], v[164:167], v[212:215], v[92:95]
	v_mfma_f32_16x16x32_bf16 v[88:91], v[172:175], v[212:215], v[88:91]
	v_mfma_f32_16x16x32_bf16 v[76:79], v[164:167], v[220:223], v[76:79]
	v_mfma_f32_16x16x32_bf16 v[72:75], v[172:175], v[220:223], v[72:75]
	v_mfma_f32_16x16x32_bf16 v[116:119], v[176:179], v[192:195], 0
	v_mfma_f32_16x16x32_bf16 v[112:115], v[184:187], v[192:195], 0
	v_mfma_f32_16x16x32_bf16 v[100:103], v[176:179], v[200:203], 0
	v_mfma_f32_16x16x32_bf16 v[96:99], v[184:187], v[200:203], 0
	v_mfma_f32_16x16x32_bf16 v[84:87], v[176:179], v[208:211], 0
	v_mfma_f32_16x16x32_bf16 v[80:83], v[184:187], v[208:211], 0
	v_mfma_f32_16x16x32_bf16 v[68:71], v[176:179], v[216:219], 0
	v_mfma_f32_16x16x32_bf16 v[64:67], v[184:187], v[216:219], 0
	v_mfma_f32_16x16x32_bf16 v[116:119], v[180:183], v[196:199], v[116:119]
	v_mfma_f32_16x16x32_bf16 v[112:115], v[188:191], v[196:199], v[112:115]
	v_mfma_f32_16x16x32_bf16 v[100:103], v[180:183], v[204:207], v[100:103]
	v_mfma_f32_16x16x32_bf16 v[96:99], v[188:191], v[204:207], v[96:99]
	v_mfma_f32_16x16x32_bf16 v[84:87], v[180:183], v[212:215], v[84:87]
	v_mfma_f32_16x16x32_bf16 v[80:83], v[188:191], v[212:215], v[80:83]
	v_mfma_f32_16x16x32_bf16 v[68:71], v[180:183], v[220:223], v[68:71]
	v_mfma_f32_16x16x32_bf16 v[64:67], v[188:191], v[220:223], v[64:67]
	s_barrier
	s_add_i32 s55, s44, s36
	s_mov_b32 m0, s55
	ds_read_b128 v[192:195], v158 offset:16384
	ds_read_b128 v[196:199], v158 offset:17408
	ds_read_b128 v[200:203], v158 offset:18432
	ds_read_b128 v[204:207], v158 offset:19456
	ds_read_b128 v[208:211], v158 offset:20480
	ds_read_b128 v[212:215], v158 offset:21504
	ds_read_b128 v[216:219], v158 offset:22528
	ds_read_b128 v[220:223], v158 offset:23552
	global_load_lds_dwordx4 v130, s[28:29]
	s_add_i32 m0, s55, 0x2000
	s_add_u32 s56, s28, 0x80000
	s_addc_u32 s57, s29, 0
	s_add_i32 s55, s45, s36
	global_load_lds_dwordx4 v134, s[28:29]
	s_mov_b32 m0, s55
	s_nop 0
	global_load_lds_dwordx4 v130, s[56:57]
	s_add_i32 m0, s55, 0x2000
	s_nop 0
	global_load_lds_dwordx4 v134, s[56:57]
	s_mov_b32 m0, s23
	s_nop 0
	global_load_lds_dwordx4 v128, s[30:31]
	s_mov_b32 m0, s25
	s_nop 0
	global_load_lds_dwordx4 v132, s[30:31]
	s_waitcnt vmcnt(8)
	s_waitcnt lgkmcnt(0)
	s_barrier
; #define PG8_STAGE(bufoff, gbase, voff) do { _Pragma("unroll") for (int _i = 0; _i < 2; ++_i) \
;         __builtin_amdgcn_global_load_lds((const unsigned*)((const char*)(gbase) + (voff)[_i]), (LAS unsigned*)(lds + (bufoff) + ldsw + _i * 8192), 16, 0, 0); } while (0)
; #define PG8_LDA(dst, b, h) do { _Pragma("unroll") for (int m = 0; m < 4; ++m) _Pragma("unroll") for (int k = 0; k < 2; ++k) dst[m][k] = *(const LAS bf16x8*)(lds + PG8_SA(b, h) + aoff + m * 2048 + k * 1024); } while (0)
; #define PG8_LDB(dst, b, h) do { _Pragma("unroll") for (int n = 0; n < 2; ++n) _Pragma("unroll") for (int k = 0; k < 2; ++k) dst[n][k] = *(const LAS bf16x8*)(lds + PG8_SB(b, h) + boff + n * 2048 + k * 1024); } while (0)
; #define PG8_MMA(ai, bj, At, Bt) do { __builtin_amdgcn_s_setprio(1); _Pragma("unroll") for (int m = 0; m < 4; ++m) _Pragma("unroll") for (int n = 0; n < 2; ++n) _Pragma("unroll") for (int k = 0; k < 2; ++k) \
;         acc[ai][bj][m][n] = __builtin_amdgcn_mfma_f32_16x16x32_bf16(Bt[n][k], At[m][k], acc[ai][bj][m][n], 0, 0, 0); __builtin_amdgcn_s_setprio(0); } while (0)
; #define PG8_WAIT_V(n) asm volatile("s_waitcnt vmcnt(" #n ")" ::: "memory")
; #define PG8_WAIT_L(n) asm volatile("s_waitcnt lgkmcnt(" #n ")" ::: "memory")
; #define PG8_BAR __builtin_amdgcn_s_barrier()
; #define PG8_SCHED __builtin_amdgcn_sched_barrier(0)
; __device__ __forceinline__ void gemm_phase(LAS unsigned char* lds, const Params& p, const bf16_t* gA, const bf16_t* gBt, const int gM, const int gN, const int gK, const int epi, const int perm, bf16_t* const Hp, const int goff, const float coef) {
;     ...
;             PG8_WAIT_V(8); PG8_WAIT_L(0); PG8_BAR; PG8_MMA(0, 0, At, B0); PG8_MMA(0, 1, At, B1); PG8_BAR; PG8_SCHED;
;             PG8_LDA(At, 0, 1); PG8_STAGE(PG8_SB(0, 0), b2, voffB); PG8_STAGE(PG8_SB(0, 1), b2 + hstep, voffB); PG8_STAGE(PG8_SA(0, 0), a2, voffA);
;             PG8_WAIT_V(8); PG8_WAIT_L(0); PG8_BAR; PG8_MMA(1, 0, At, B0); PG8_MMA(1, 1, At, B1); PG8_BAR; PG8_SCHED;
;             PG8_LDB(B0, 1, 0); PG8_LDB(B1, 1, 1); PG8_SCHED; PG8_LDA(At, 1, 0); PG8_STAGE(PG8_SA(0, 1), a2 + hstep, voffA);
;             PG8_WAIT_V(8); PG8_WAIT_L(0); PG8_BAR; PG8_MMA(0, 0, At, B0); PG8_MMA(0, 1, At, B1); PG8_BAR; PG8_SCHED;
	s_waitcnt lgkmcnt(0)
	v_mfma_f32_16x16x32_bf16 v[60:63], v[160:163], v[192:195], 0
	v_mfma_f32_16x16x32_bf16 v[56:59], v[168:171], v[192:195], 0
	v_mfma_f32_16x16x32_bf16 v[44:47], v[160:163], v[200:203], 0
	v_mfma_f32_16x16x32_bf16 v[40:43], v[168:171], v[200:203], 0
	v_mfma_f32_16x16x32_bf16 v[28:31], v[160:163], v[208:211], 0
	v_mfma_f32_16x16x32_bf16 v[24:27], v[168:171], v[208:211], 0
	v_mfma_f32_16x16x32_bf16 v[12:15], v[160:163], v[216:219], 0
	v_mfma_f32_16x16x32_bf16 v[8:11], v[168:171], v[216:219], 0
	v_mfma_f32_16x16x32_bf16 v[60:63], v[164:167], v[196:199], v[60:63]
	v_mfma_f32_16x16x32_bf16 v[56:59], v[172:175], v[196:199], v[56:59]
	v_mfma_f32_16x16x32_bf16 v[44:47], v[164:167], v[204:207], v[44:47]
	v_mfma_f32_16x16x32_bf16 v[40:43], v[172:175], v[204:207], v[40:43]
	v_mfma_f32_16x16x32_bf16 v[28:31], v[164:167], v[212:215], v[28:31]
	v_mfma_f32_16x16x32_bf16 v[24:27], v[172:175], v[212:215], v[24:27]
	v_mfma_f32_16x16x32_bf16 v[12:15], v[164:167], v[220:223], v[12:15]
	v_mfma_f32_16x16x32_bf16 v[8:11], v[172:175], v[220:223], v[8:11]
	v_mfma_f32_16x16x32_bf16 v[52:55], v[176:179], v[192:195], 0
	v_mfma_f32_16x16x32_bf16 v[48:51], v[184:187], v[192:195], 0
	v_mfma_f32_16x16x32_bf16 v[36:39], v[176:179], v[200:203], 0
	v_mfma_f32_16x16x32_bf16 v[32:35], v[184:187], v[200:203], 0
	v_mfma_f32_16x16x32_bf16 v[20:23], v[176:179], v[208:211], 0
	v_mfma_f32_16x16x32_bf16 v[16:19], v[184:187], v[208:211], 0
	v_mfma_f32_16x16x32_bf16 v[4:7], v[176:179], v[216:219], 0
	v_mfma_f32_16x16x32_bf16 v[0:3], v[184:187], v[216:219], 0
	v_mfma_f32_16x16x32_bf16 v[52:55], v[180:183], v[196:199], v[52:55]
	v_mfma_f32_16x16x32_bf16 v[48:51], v[188:191], v[196:199], v[48:51]
	v_mfma_f32_16x16x32_bf16 v[36:39], v[180:183], v[204:207], v[36:39]
	v_mfma_f32_16x16x32_bf16 v[32:35], v[188:191], v[204:207], v[32:35]
	v_mfma_f32_16x16x32_bf16 v[20:23], v[180:183], v[212:215], v[20:23]
	v_mfma_f32_16x16x32_bf16 v[16:19], v[188:191], v[212:215], v[16:19]
	v_mfma_f32_16x16x32_bf16 v[4:7], v[180:183], v[220:223], v[4:7]
	v_mfma_f32_16x16x32_bf16 v[0:3], v[188:191], v[220:223], v[0:3]
	s_barrier
	s_add_i32 s55, 0, 0x18000
	s_add_i32 s56, 0, 0x1c000
	ds_read_b128 v[160:163], v224
	ds_read_b128 v[164:167], v224 offset:1024
	ds_read_b128 v[168:171], v224 offset:2048
	ds_read_b128 v[172:175], v224 offset:3072
	ds_read_b128 v[176:179], v225
	ds_read_b128 v[180:183], v225 offset:1024
	ds_read_b128 v[184:187], v225 offset:2048
	ds_read_b128 v[188:191], v225 offset:3072
	s_add_u32 s30, s30, 0x80000
	s_addc_u32 s31, s31, 0
	s_mov_b32 m0, s37
	ds_read_b128 v[192:195], v158 offset:32768
	ds_read_b128 v[196:199], v158 offset:33792
	ds_read_b128 v[200:203], v158 offset:34816
	ds_read_b128 v[204:207], v158 offset:35840
	ds_read_b128 v[208:211], v158 offset:36864
	ds_read_b128 v[212:215], v158 offset:37888
	ds_read_b128 v[216:219], v158 offset:38912
	ds_read_b128 v[220:223], v158 offset:39936
	global_load_lds_dwordx4 v128, s[30:31]
	s_mov_b32 m0, s38
	s_nop 0
	global_load_lds_dwordx4 v132, s[30:31]
	s_waitcnt vmcnt(8)
	s_waitcnt lgkmcnt(0)
	s_barrier
	s_waitcnt lgkmcnt(0)
	v_mfma_f32_16x16x32_bf16 v[124:127], v[160:163], v[192:195], v[124:127]
	v_mfma_f32_16x16x32_bf16 v[120:123], v[168:171], v[192:195], v[120:123]
	v_mfma_f32_16x16x32_bf16 v[108:111], v[160:163], v[200:203], v[108:111]
	v_mfma_f32_16x16x32_bf16 v[104:107], v[168:171], v[200:203], v[104:107]
	v_mfma_f32_16x16x32_bf16 v[92:95], v[160:163], v[208:211], v[92:95]
	v_mfma_f32_16x16x32_bf16 v[88:91], v[168:171], v[208:211], v[88:91]
	v_mfma_f32_16x16x32_bf16 v[76:79], v[160:163], v[216:219], v[76:79]
	v_mfma_f32_16x16x32_bf16 v[72:75], v[168:171], v[216:219], v[72:75]
	v_mfma_f32_16x16x32_bf16 v[124:127], v[164:167], v[196:199], v[124:127]
	v_mfma_f32_16x16x32_bf16 v[120:123], v[172:175], v[196:199], v[120:123]
	v_mfma_f32_16x16x32_bf16 v[108:111], v[164:167], v[204:207], v[108:111]
	v_mfma_f32_16x16x32_bf16 v[104:107], v[172:175], v[204:207], v[104:107]
	v_mfma_f32_16x16x32_bf16 v[92:95], v[164:167], v[212:215], v[92:95]
	v_mfma_f32_16x16x32_bf16 v[88:91], v[172:175], v[212:215], v[88:91]
	v_mfma_f32_16x16x32_bf16 v[76:79], v[164:167], v[220:223], v[76:79]
	v_mfma_f32_16x16x32_bf16 v[72:75], v[172:175], v[220:223], v[72:75]
	v_mfma_f32_16x16x32_bf16 v[116:119], v[176:179], v[192:195], v[116:119]
	v_mfma_f32_16x16x32_bf16 v[112:115], v[184:187], v[192:195], v[112:115]
	v_mfma_f32_16x16x32_bf16 v[100:103], v[176:179], v[200:203], v[100:103]
	v_mfma_f32_16x16x32_bf16 v[96:99], v[184:187], v[200:203], v[96:99]
	v_mfma_f32_16x16x32_bf16 v[84:87], v[176:179], v[208:211], v[84:87]
	v_mfma_f32_16x16x32_bf16 v[80:83], v[184:187], v[208:211], v[80:83]
	v_mfma_f32_16x16x32_bf16 v[68:71], v[176:179], v[216:219], v[68:71]
	v_mfma_f32_16x16x32_bf16 v[64:67], v[184:187], v[216:219], v[64:67]
	v_mfma_f32_16x16x32_bf16 v[116:119], v[180:183], v[196:199], v[116:119]
	v_mfma_f32_16x16x32_bf16 v[112:115], v[188:191], v[196:199], v[112:115]
	v_mfma_f32_16x16x32_bf16 v[100:103], v[180:183], v[204:207], v[100:103]
	v_mfma_f32_16x16x32_bf16 v[96:99], v[188:191], v[204:207], v[96:99]
	v_mfma_f32_16x16x32_bf16 v[84:87], v[180:183], v[212:215], v[84:87]
	v_mfma_f32_16x16x32_bf16 v[80:83], v[188:191], v[212:215], v[80:83]
	v_mfma_f32_16x16x32_bf16 v[68:71], v[180:183], v[220:223], v[68:71]
	v_mfma_f32_16x16x32_bf16 v[64:67], v[188:191], v[220:223], v[64:67]
	s_barrier
; #define PG8_STAGE(bufoff, gbase, voff) do { _Pragma("unroll") for (int _i = 0; _i < 2; ++_i) \
;         __builtin_amdgcn_global_load_lds((const unsigned*)((const char*)(gbase) + (voff)[_i]), (LAS unsigned*)(lds + (bufoff) + ldsw + _i * 8192), 16, 0, 0); } while (0)
; #define PG8_LDA(dst, b, h) do { _Pragma("unroll") for (int m = 0; m < 4; ++m) _Pragma("unroll") for (int k = 0; k < 2; ++k) dst[m][k] = *(const LAS bf16x8*)(lds + PG8_SA(b, h) + aoff + m * 2048 + k * 1024); } while (0)
; #define PG8_LDB(dst, b, h) do { _Pragma("unroll") for (int n = 0; n < 2; ++n) _Pragma("unroll") for (int k = 0; k < 2; ++k) dst[n][k] = *(const LAS bf16x8*)(lds + PG8_SB(b, h) + boff + n * 2048 + k * 1024); } while (0)
; #define PG8_BAR __builtin_amdgcn_s_barrier()
; __device__ __forceinline__ void gemm_phase(LAS unsigned char* lds, const Params& p, const bf16_t* gA, const bf16_t* gBt, const int gM, const int gN, const int gK, const int epi, const int perm, bf16_t* const Hp, const int goff, const float coef) {
;     ...
;         for (int t = 0; t < nt; t += 2) {
;             const bool last = (t == nt - 2);
;             const char* a1 = cA + (size_t)(t + 1) * kstep;
;             const char* a2 = last ? nA : cA + (size_t)(t + 2) * kstep; const char* b2 = last ? nB : cB + (size_t)(t + 2) * kstep;
;             const char* a3 = a2 + kstep; const char* b3 = b2 + kstep;
;             PG8_LDB(B0, 0, 0); PG8_LDB(B1, 0, 1); PG8_SCHED; PG8_LDA(At, 0, 0); PG8_STAGE(PG8_SA(1, 1), a1 + hstep, voffA);
;             PG8_WAIT_V(8); PG8_WAIT_L(0); PG8_BAR; PG8_MMA(0, 0, At, B0); PG8_MMA(0, 1, At, B1); PG8_BAR; PG8_SCHED;
;             PG8_LDA(At, 0, 1); PG8_STAGE(PG8_SB(0, 0), b2, voffB); PG8_STAGE(PG8_SB(0, 1), b2 + hstep, voffB); PG8_STAGE(PG8_SA(0, 0), a2, voffA);
;             PG8_WAIT_V(8); PG8_WAIT_L(0); PG8_BAR; PG8_MMA(1, 0, At, B0); PG8_MMA(1, 1, At, B1); PG8_BAR; PG8_SCHED;
;             PG8_LDB(B0, 1, 0); PG8_LDB(B1, 1, 1); PG8_SCHED; PG8_LDA(At, 1, 0); PG8_STAGE(PG8_SA(0, 1), a2 + hstep, voffA);
;             PG8_WAIT_V(8); PG8_WAIT_L(0); PG8_BAR; PG8_MMA(0, 0, At, B0); PG8_MMA(0, 1, At, B1); PG8_BAR; PG8_SCHED;
;             PG8_LDA(At, 1, 1); PG8_STAGE(PG8_SB(1, 0), b3, voffB); PG8_STAGE(PG8_SB(1, 1), b3 + hstep, voffB); PG8_STAGE(PG8_SA(1, 0), a3, voffA);
;             PG8_WAIT_V(8); PG8_WAIT_L(0); PG8_BAR; PG8_MMA(1, 0, At, B0); PG8_MMA(1, 1, At, B1); PG8_BAR; PG8_SCHED;
	s_mov_b64 s[98:99], s[30:31]
	s_add_i32 s30, s55, s36
	s_mov_b32 m0, s30
	ds_read_b128 v[192:195], v158 offset:49152
	ds_read_b128 v[196:199], v158 offset:50176
	ds_read_b128 v[200:203], v158 offset:51200
	ds_read_b128 v[204:207], v158 offset:52224
	ds_read_b128 v[208:211], v158 offset:53248
	ds_read_b128 v[212:215], v158 offset:54272
	ds_read_b128 v[216:219], v158 offset:55296
	ds_read_b128 v[220:223], v158 offset:56320
	s_add_u32 s100, s28, 0x80
	s_addc_u32 s101, s29, 0
	global_load_lds_dwordx4 v130, s[100:101]
	s_add_i32 m0, s30, 0x2000
	s_add_u32 s28, s28, 0x80080
	s_addc_u32 s29, s29, 0
	s_add_i32 s30, s56, s36
	global_load_lds_dwordx4 v134, s[100:101]
	s_mov_b32 m0, s30
	s_nop 0
	global_load_lds_dwordx4 v130, s[28:29]
	s_add_i32 m0, s30, 0x2000
	s_nop 0
	global_load_lds_dwordx4 v134, s[28:29]
	s_mov_b32 m0, s40
	s_nop 0
	s_add_u32 s100, s98, 0xfff80080
	s_addc_u32 s101, s99, -1
	global_load_lds_dwordx4 v128, s[100:101]
	s_mov_b32 m0, s41
	s_nop 0
	global_load_lds_dwordx4 v132, s[100:101]
	s_waitcnt vmcnt(8)
	s_waitcnt lgkmcnt(0)
	s_barrier
	s_waitcnt lgkmcnt(0)
	v_mfma_f32_16x16x32_bf16 v[60:63], v[160:163], v[192:195], v[60:63]
	v_mfma_f32_16x16x32_bf16 v[56:59], v[168:171], v[192:195], v[56:59]
	v_mfma_f32_16x16x32_bf16 v[44:47], v[160:163], v[200:203], v[44:47]
	v_mfma_f32_16x16x32_bf16 v[40:43], v[168:171], v[200:203], v[40:43]
	v_mfma_f32_16x16x32_bf16 v[28:31], v[160:163], v[208:211], v[28:31]
	v_mfma_f32_16x16x32_bf16 v[24:27], v[168:171], v[208:211], v[24:27]
	v_mfma_f32_16x16x32_bf16 v[12:15], v[160:163], v[216:219], v[12:15]
	v_mfma_f32_16x16x32_bf16 v[8:11], v[168:171], v[216:219], v[8:11]
	v_mfma_f32_16x16x32_bf16 v[60:63], v[164:167], v[196:199], v[60:63]
	v_mfma_f32_16x16x32_bf16 v[56:59], v[172:175], v[196:199], v[56:59]
	v_mfma_f32_16x16x32_bf16 v[44:47], v[164:167], v[204:207], v[44:47]
	v_mfma_f32_16x16x32_bf16 v[40:43], v[172:175], v[204:207], v[40:43]
	v_mfma_f32_16x16x32_bf16 v[28:31], v[164:167], v[212:215], v[28:31]
	v_mfma_f32_16x16x32_bf16 v[24:27], v[172:175], v[212:215], v[24:27]
	v_mfma_f32_16x16x32_bf16 v[12:15], v[164:167], v[220:223], v[12:15]
	v_mfma_f32_16x16x32_bf16 v[8:11], v[172:175], v[220:223], v[8:11]
	v_mfma_f32_16x16x32_bf16 v[52:55], v[176:179], v[192:195], v[52:55]
	v_mfma_f32_16x16x32_bf16 v[48:51], v[184:187], v[192:195], v[48:51]
	v_mfma_f32_16x16x32_bf16 v[36:39], v[176:179], v[200:203], v[36:39]
	v_mfma_f32_16x16x32_bf16 v[32:35], v[184:187], v[200:203], v[32:35]
	v_mfma_f32_16x16x32_bf16 v[20:23], v[176:179], v[208:211], v[20:23]
	v_mfma_f32_16x16x32_bf16 v[16:19], v[184:187], v[208:211], v[16:19]
	v_mfma_f32_16x16x32_bf16 v[4:7], v[176:179], v[216:219], v[4:7]
	v_mfma_f32_16x16x32_bf16 v[0:3], v[184:187], v[216:219], v[0:3]
	v_mfma_f32_16x16x32_bf16 v[52:55], v[180:183], v[196:199], v[52:55]
	v_mfma_f32_16x16x32_bf16 v[48:51], v[188:191], v[196:199], v[48:51]
	v_mfma_f32_16x16x32_bf16 v[36:39], v[180:183], v[204:207], v[36:39]
	v_mfma_f32_16x16x32_bf16 v[32:35], v[188:191], v[204:207], v[32:35]
	v_mfma_f32_16x16x32_bf16 v[20:23], v[180:183], v[212:215], v[20:23]
	v_mfma_f32_16x16x32_bf16 v[16:19], v[188:191], v[212:215], v[16:19]
	v_mfma_f32_16x16x32_bf16 v[4:7], v[180:183], v[220:223], v[4:7]
	v_mfma_f32_16x16x32_bf16 v[0:3], v[188:191], v[220:223], v[0:3]
	s_barrier
	s_add_u32 s26, s26, 0x100
	s_addc_u32 s27, s27, 0
	s_add_u32 s52, s52, 0x100
	s_addc_u32 s53, s53, 0
	s_cmp_ge_u32 s54, s50
	s_mov_b32 s30, s54
	s_cbranch_scc1 .Lpeel_exit_4
.LBB0_1737:
	ds_read_b128 v[160:163], v156
	ds_read_b128 v[164:167], v156 offset:1024
	ds_read_b128 v[168:171], v156 offset:2048
	ds_read_b128 v[172:175], v156 offset:3072
	ds_read_b128 v[176:179], v157
	ds_read_b128 v[180:183], v157 offset:1024
	ds_read_b128 v[184:187], v157 offset:2048
	ds_read_b128 v[188:191], v157 offset:3072
	s_add_i32 s54, s30, 2
	s_add_u32 s28, s26, 0xfff80080
	s_addc_u32 s29, s27, -1
	s_cmp_eq_u32 s51, s30
	s_cselect_b32 s30, s48, s28
	s_cselect_b32 s31, s13, s29
	s_cselect_b32 s29, s15, s53
	s_cselect_b32 s28, s49, s52
	s_add_i32 m0, s23, 0xc000
	ds_read_b128 v[192:195], v158
	ds_read_b128 v[196:199], v158 offset:1024
	ds_read_b128 v[200:203], v158 offset:2048
	ds_read_b128 v[204:207], v158 offset:3072
	ds_read_b128 v[208:211], v158 offset:4096
	ds_read_b128 v[212:215], v158 offset:5120
	ds_read_b128 v[216:219], v158 offset:6144
	ds_read_b128 v[220:223], v158 offset:7168
	global_load_lds_dwordx4 v136, s[26:27]
	s_add_i32 m0, s23, 0xe000
	s_nop 0
	global_load_lds_dwordx4 v138, s[26:27]
	s_waitcnt vmcnt(8)
	s_waitcnt lgkmcnt(0)
	s_barrier
; #define PG8_STAGE(bufoff, gbase, voff) do { _Pragma("unroll") for (int _i = 0; _i < 2; ++_i) \
;         __builtin_amdgcn_global_load_lds((const unsigned*)((const char*)(gbase) + (voff)[_i]), (LAS unsigned*)(lds + (bufoff) + ldsw + _i * 8192), 16, 0, 0); } while (0)
; #define PG8_LDA(dst, b, h) do { _Pragma("unroll") for (int m = 0; m < 4; ++m) _Pragma("unroll") for (int k = 0; k < 2; ++k) dst[m][k] = *(const LAS bf16x8*)(lds + PG8_SA(b, h) + aoff + m * 2048 + k * 1024); } while (0)
; #define PG8_LDB(dst, b, h) do { _Pragma("unroll") for (int n = 0; n < 2; ++n) _Pragma("unroll") for (int k = 0; k < 2; ++k) dst[n][k] = *(const LAS bf16x8*)(lds + PG8_SB(b, h) + boff + n * 2048 + k * 1024); } while (0)
; #define PG8_MMA(ai, bj, At, Bt) do { __builtin_amdgcn_s_setprio(1); _Pragma("unroll") for (int m = 0; m < 4; ++m) _Pragma("unroll") for (int n = 0; n < 2; ++n) _Pragma("unroll") for (int k = 0; k < 2; ++k) \
;         acc[ai][bj][m][n] = __builtin_amdgcn_mfma_f32_16x16x32_bf16(Bt[n][k], At[m][k], acc[ai][bj][m][n], 0, 0, 0); __builtin_amdgcn_s_setprio(0); } while (0)
; #define PG8_WAIT_V(n) asm volatile("s_waitcnt vmcnt(" #n ")" ::: "memory")
; #define PG8_WAIT_L(n) asm volatile("s_waitcnt lgkmcnt(" #n ")" ::: "memory")
; #define PG8_BAR __builtin_amdgcn_s_barrier()
; #define PG8_SCHED __builtin_amdgcn_sched_barrier(0)
; __device__ __forceinline__ void gemm_phase(LAS unsigned char* lds, const Params& p, const bf16_t* gA, const bf16_t* gBt, const int gM, const int gN, const int gK, const int epi, const int perm, bf16_t* const Hp, const int goff, const float coef) {
;     ...
;             PG8_LDB(B0, 0, 0); PG8_LDB(B1, 0, 1); PG8_SCHED; PG8_LDA(At, 0, 0); PG8_STAGE(PG8_SA(1, 1), a1 + hstep, voffA);
;             PG8_WAIT_V(8); PG8_WAIT_L(0); PG8_BAR; PG8_MMA(0, 0, At, B0); PG8_MMA(0, 1, At, B1); PG8_BAR; PG8_SCHED;
;             PG8_LDA(At, 0, 1); PG8_STAGE(PG8_SB(0, 0), b2, voffB); PG8_STAGE(PG8_SB(0, 1), b2 + hstep, voffB); PG8_STAGE(PG8_SA(0, 0), a2, voffA);
;             PG8_WAIT_V(8); PG8_WAIT_L(0); PG8_BAR; PG8_MMA(1, 0, At, B0); PG8_MMA(1, 1, At, B1); PG8_BAR; PG8_SCHED;
	s_waitcnt lgkmcnt(0)
	v_mfma_f32_16x16x32_bf16 v[124:127], v[160:163], v[192:195], v[124:127]
	v_mfma_f32_16x16x32_bf16 v[120:123], v[168:171], v[192:195], v[120:123]
	v_mfma_f32_16x16x32_bf16 v[108:111], v[160:163], v[200:203], v[108:111]
	v_mfma_f32_16x16x32_bf16 v[104:107], v[168:171], v[200:203], v[104:107]
	v_mfma_f32_16x16x32_bf16 v[92:95], v[160:163], v[208:211], v[92:95]
	v_mfma_f32_16x16x32_bf16 v[88:91], v[168:171], v[208:211], v[88:91]
	v_mfma_f32_16x16x32_bf16 v[76:79], v[160:163], v[216:219], v[76:79]
	v_mfma_f32_16x16x32_bf16 v[72:75], v[168:171], v[216:219], v[72:75]
	v_mfma_f32_16x16x32_bf16 v[124:127], v[164:167], v[196:199], v[124:127]
	v_mfma_f32_16x16x32_bf16 v[120:123], v[172:175], v[196:199], v[120:123]
	v_mfma_f32_16x16x32_bf16 v[108:111], v[164:167], v[204:207], v[108:111]
	v_mfma_f32_16x16x32_bf16 v[104:107], v[172:175], v[204:207], v[104:107]
	v_mfma_f32_16x16x32_bf16 v[92:95], v[164:167], v[212:215], v[92:95]
	v_mfma_f32_16x16x32_bf16 v[88:91], v[172:175], v[212:215], v[88:91]
	v_mfma_f32_16x16x32_bf16 v[76:79], v[164:167], v[220:223], v[76:79]
	v_mfma_f32_16x16x32_bf16 v[72:75], v[172:175], v[220:223], v[72:75]
	v_mfma_f32_16x16x32_bf16 v[116:119], v[176:179], v[192:195], v[116:119]
	v_mfma_f32_16x16x32_bf16 v[112:115], v[184:187], v[192:195], v[112:115]
	v_mfma_f32_16x16x32_bf16 v[100:103], v[176:179], v[200:203], v[100:103]
	v_mfma_f32_16x16x32_bf16 v[96:99], v[184:187], v[200:203], v[96:99]
	v_mfma_f32_16x16x32_bf16 v[84:87], v[176:179], v[208:211], v[84:87]
	v_mfma_f32_16x16x32_bf16 v[80:83], v[184:187], v[208:211], v[80:83]
	v_mfma_f32_16x16x32_bf16 v[68:71], v[176:179], v[216:219], v[68:71]
	v_mfma_f32_16x16x32_bf16 v[64:67], v[184:187], v[216:219], v[64:67]
	v_mfma_f32_16x16x32_bf16 v[116:119], v[180:183], v[196:199], v[116:119]
	v_mfma_f32_16x16x32_bf16 v[112:115], v[188:191], v[196:199], v[112:115]
	v_mfma_f32_16x16x32_bf16 v[100:103], v[180:183], v[204:207], v[100:103]
	v_mfma_f32_16x16x32_bf16 v[96:99], v[188:191], v[204:207], v[96:99]
	v_mfma_f32_16x16x32_bf16 v[84:87], v[180:183], v[212:215], v[84:87]
	v_mfma_f32_16x16x32_bf16 v[80:83], v[188:191], v[212:215], v[80:83]
	v_mfma_f32_16x16x32_bf16 v[68:71], v[180:183], v[220:223], v[68:71]
	v_mfma_f32_16x16x32_bf16 v[64:67], v[188:191], v[220:223], v[64:67]
	s_barrier
	s_add_i32 s55, s44, s36
	s_mov_b32 m0, s55
	ds_read_b128 v[192:195], v158 offset:16384
	ds_read_b128 v[196:199], v158 offset:17408
	ds_read_b128 v[200:203], v158 offset:18432
	ds_read_b128 v[204:207], v158 offset:19456
	ds_read_b128 v[208:211], v158 offset:20480
	ds_read_b128 v[212:215], v158 offset:21504
	ds_read_b128 v[216:219], v158 offset:22528
	ds_read_b128 v[220:223], v158 offset:23552
	global_load_lds_dwordx4 v130, s[28:29]
	s_add_i32 m0, s55, 0x2000
	s_add_u32 s56, s28, 0x80000
	s_addc_u32 s57, s29, 0
	s_add_i32 s55, s45, s36
	global_load_lds_dwordx4 v134, s[28:29]
	s_mov_b32 m0, s55
	s_nop 0
	global_load_lds_dwordx4 v130, s[56:57]
	s_add_i32 m0, s55, 0x2000
	s_nop 0
	global_load_lds_dwordx4 v134, s[56:57]
	s_mov_b32 m0, s23
	s_nop 0
	global_load_lds_dwordx4 v128, s[30:31]
	s_mov_b32 m0, s25
	s_nop 0
	global_load_lds_dwordx4 v132, s[30:31]
	s_waitcnt vmcnt(8)
	s_waitcnt lgkmcnt(0)
	s_barrier
	s_waitcnt lgkmcnt(0)
	v_mfma_f32_16x16x32_bf16 v[60:63], v[160:163], v[192:195], v[60:63]
	v_mfma_f32_16x16x32_bf16 v[56:59], v[168:171], v[192:195], v[56:59]
	v_mfma_f32_16x16x32_bf16 v[44:47], v[160:163], v[200:203], v[44:47]
	v_mfma_f32_16x16x32_bf16 v[40:43], v[168:171], v[200:203], v[40:43]
	v_mfma_f32_16x16x32_bf16 v[28:31], v[160:163], v[208:211], v[28:31]
	v_mfma_f32_16x16x32_bf16 v[24:27], v[168:171], v[208:211], v[24:27]
	v_mfma_f32_16x16x32_bf16 v[12:15], v[160:163], v[216:219], v[12:15]
	v_mfma_f32_16x16x32_bf16 v[8:11], v[168:171], v[216:219], v[8:11]
	v_mfma_f32_16x16x32_bf16 v[60:63], v[164:167], v[196:199], v[60:63]
	v_mfma_f32_16x16x32_bf16 v[56:59], v[172:175], v[196:199], v[56:59]
	v_mfma_f32_16x16x32_bf16 v[44:47], v[164:167], v[204:207], v[44:47]
	v_mfma_f32_16x16x32_bf16 v[40:43], v[172:175], v[204:207], v[40:43]
	v_mfma_f32_16x16x32_bf16 v[28:31], v[164:167], v[212:215], v[28:31]
	v_mfma_f32_16x16x32_bf16 v[24:27], v[172:175], v[212:215], v[24:27]
	v_mfma_f32_16x16x32_bf16 v[12:15], v[164:167], v[220:223], v[12:15]
	v_mfma_f32_16x16x32_bf16 v[8:11], v[172:175], v[220:223], v[8:11]
	v_mfma_f32_16x16x32_bf16 v[52:55], v[176:179], v[192:195], v[52:55]
	v_mfma_f32_16x16x32_bf16 v[48:51], v[184:187], v[192:195], v[48:51]
	v_mfma_f32_16x16x32_bf16 v[36:39], v[176:179], v[200:203], v[36:39]
	v_mfma_f32_16x16x32_bf16 v[32:35], v[184:187], v[200:203], v[32:35]
	v_mfma_f32_16x16x32_bf16 v[20:23], v[176:179], v[208:211], v[20:23]
	v_mfma_f32_16x16x32_bf16 v[16:19], v[184:187], v[208:211], v[16:19]
	v_mfma_f32_16x16x32_bf16 v[4:7], v[176:179], v[216:219], v[4:7]
	v_mfma_f32_16x16x32_bf16 v[0:3], v[184:187], v[216:219], v[0:3]
	v_mfma_f32_16x16x32_bf16 v[52:55], v[180:183], v[196:199], v[52:55]
	v_mfma_f32_16x16x32_bf16 v[48:51], v[188:191], v[196:199], v[48:51]
	v_mfma_f32_16x16x32_bf16 v[36:39], v[180:183], v[204:207], v[36:39]
	v_mfma_f32_16x16x32_bf16 v[32:35], v[188:191], v[204:207], v[32:35]
	v_mfma_f32_16x16x32_bf16 v[20:23], v[180:183], v[212:215], v[20:23]
	v_mfma_f32_16x16x32_bf16 v[16:19], v[188:191], v[212:215], v[16:19]
	v_mfma_f32_16x16x32_bf16 v[4:7], v[180:183], v[220:223], v[4:7]
	v_mfma_f32_16x16x32_bf16 v[0:3], v[188:191], v[220:223], v[0:3]
	s_barrier
; #define PG8_STAGE(bufoff, gbase, voff) do { _Pragma("unroll") for (int _i = 0; _i < 2; ++_i) \
;         __builtin_amdgcn_global_load_lds((const unsigned*)((const char*)(gbase) + (voff)[_i]), (LAS unsigned*)(lds + (bufoff) + ldsw + _i * 8192), 16, 0, 0); } while (0)
; #define PG8_LDA(dst, b, h) do { _Pragma("unroll") for (int m = 0; m < 4; ++m) _Pragma("unroll") for (int k = 0; k < 2; ++k) dst[m][k] = *(const LAS bf16x8*)(lds + PG8_SA(b, h) + aoff + m * 2048 + k * 1024); } while (0)
; #define PG8_LDB(dst, b, h) do { _Pragma("unroll") for (int n = 0; n < 2; ++n) _Pragma("unroll") for (int k = 0; k < 2; ++k) dst[n][k] = *(const LAS bf16x8*)(lds + PG8_SB(b, h) + boff + n * 2048 + k * 1024); } while (0)
; #define PG8_MMA(ai, bj, At, Bt) do { __builtin_amdgcn_s_setprio(1); _Pragma("unroll") for (int m = 0; m < 4; ++m) _Pragma("unroll") for (int n = 0; n < 2; ++n) _Pragma("unroll") for (int k = 0; k < 2; ++k) \
;         acc[ai][bj][m][n] = __builtin_amdgcn_mfma_f32_16x16x32_bf16(Bt[n][k], At[m][k], acc[ai][bj][m][n], 0, 0, 0); __builtin_amdgcn_s_setprio(0); } while (0)
; #define PG8_WAIT_V(n) asm volatile("s_waitcnt vmcnt(" #n ")" ::: "memory")
; #define PG8_WAIT_L(n) asm volatile("s_waitcnt lgkmcnt(" #n ")" ::: "memory")
; #define PG8_BAR __builtin_amdgcn_s_barrier()
; #define PG8_SCHED __builtin_amdgcn_sched_barrier(0)
; __device__ __forceinline__ void gemm_phase(LAS unsigned char* lds, const Params& p, const bf16_t* gA, const bf16_t* gBt, const int gM, const int gN, const int gK, const int epi, const int perm, bf16_t* const Hp, const int goff, const float coef) {
;     ...
;             PG8_LDB(B0, 1, 0); PG8_LDB(B1, 1, 1); PG8_SCHED; PG8_LDA(At, 1, 0); PG8_STAGE(PG8_SA(0, 1), a2 + hstep, voffA);
;             PG8_WAIT_V(8); PG8_WAIT_L(0); PG8_BAR; PG8_MMA(0, 0, At, B0); PG8_MMA(0, 1, At, B1); PG8_BAR; PG8_SCHED;
;             PG8_LDA(At, 1, 1); PG8_STAGE(PG8_SB(1, 0), b3, voffB); PG8_STAGE(PG8_SB(1, 1), b3 + hstep, voffB); PG8_STAGE(PG8_SA(1, 0), a3, voffA);
;             PG8_WAIT_V(8); PG8_WAIT_L(0); PG8_BAR; PG8_MMA(1, 0, At, B0); PG8_MMA(1, 1, At, B1); PG8_BAR; PG8_SCHED;
	s_add_i32 s55, 0, 0x18000
	s_add_i32 s56, 0, 0x1c000
	ds_read_b128 v[160:163], v224
	ds_read_b128 v[164:167], v224 offset:1024
	ds_read_b128 v[168:171], v224 offset:2048
	ds_read_b128 v[172:175], v224 offset:3072
	ds_read_b128 v[176:179], v225
	ds_read_b128 v[180:183], v225 offset:1024
	ds_read_b128 v[184:187], v225 offset:2048
	ds_read_b128 v[188:191], v225 offset:3072
	s_add_u32 s30, s30, 0x80000
	s_addc_u32 s31, s31, 0
	s_mov_b32 m0, s37
	ds_read_b128 v[192:195], v158 offset:32768
	ds_read_b128 v[196:199], v158 offset:33792
	ds_read_b128 v[200:203], v158 offset:34816
	ds_read_b128 v[204:207], v158 offset:35840
	ds_read_b128 v[208:211], v158 offset:36864
	ds_read_b128 v[212:215], v158 offset:37888
	ds_read_b128 v[216:219], v158 offset:38912
	ds_read_b128 v[220:223], v158 offset:39936
	global_load_lds_dwordx4 v128, s[30:31]
	s_mov_b32 m0, s38
	s_nop 0
	global_load_lds_dwordx4 v132, s[30:31]
	s_waitcnt vmcnt(8)
	s_waitcnt lgkmcnt(0)
	s_barrier
	s_waitcnt lgkmcnt(0)
	v_mfma_f32_16x16x32_bf16 v[124:127], v[160:163], v[192:195], v[124:127]
	v_mfma_f32_16x16x32_bf16 v[120:123], v[168:171], v[192:195], v[120:123]
	v_mfma_f32_16x16x32_bf16 v[108:111], v[160:163], v[200:203], v[108:111]
	v_mfma_f32_16x16x32_bf16 v[104:107], v[168:171], v[200:203], v[104:107]
	v_mfma_f32_16x16x32_bf16 v[92:95], v[160:163], v[208:211], v[92:95]
	v_mfma_f32_16x16x32_bf16 v[88:91], v[168:171], v[208:211], v[88:91]
	v_mfma_f32_16x16x32_bf16 v[76:79], v[160:163], v[216:219], v[76:79]
	v_mfma_f32_16x16x32_bf16 v[72:75], v[168:171], v[216:219], v[72:75]
	v_mfma_f32_16x16x32_bf16 v[124:127], v[164:167], v[196:199], v[124:127]
	v_mfma_f32_16x16x32_bf16 v[120:123], v[172:175], v[196:199], v[120:123]
	v_mfma_f32_16x16x32_bf16 v[108:111], v[164:167], v[204:207], v[108:111]
	v_mfma_f32_16x16x32_bf16 v[104:107], v[172:175], v[204:207], v[104:107]
	v_mfma_f32_16x16x32_bf16 v[92:95], v[164:167], v[212:215], v[92:95]
	v_mfma_f32_16x16x32_bf16 v[88:91], v[172:175], v[212:215], v[88:91]
	v_mfma_f32_16x16x32_bf16 v[76:79], v[164:167], v[220:223], v[76:79]
	v_mfma_f32_16x16x32_bf16 v[72:75], v[172:175], v[220:223], v[72:75]
	v_mfma_f32_16x16x32_bf16 v[116:119], v[176:179], v[192:195], v[116:119]
	v_mfma_f32_16x16x32_bf16 v[112:115], v[184:187], v[192:195], v[112:115]
	v_mfma_f32_16x16x32_bf16 v[100:103], v[176:179], v[200:203], v[100:103]
	v_mfma_f32_16x16x32_bf16 v[96:99], v[184:187], v[200:203], v[96:99]
	v_mfma_f32_16x16x32_bf16 v[84:87], v[176:179], v[208:211], v[84:87]
	v_mfma_f32_16x16x32_bf16 v[80:83], v[184:187], v[208:211], v[80:83]
	v_mfma_f32_16x16x32_bf16 v[68:71], v[176:179], v[216:219], v[68:71]
	v_mfma_f32_16x16x32_bf16 v[64:67], v[184:187], v[216:219], v[64:67]
	v_mfma_f32_16x16x32_bf16 v[116:119], v[180:183], v[196:199], v[116:119]
	v_mfma_f32_16x16x32_bf16 v[112:115], v[188:191], v[196:199], v[112:115]
	v_mfma_f32_16x16x32_bf16 v[100:103], v[180:183], v[204:207], v[100:103]
	v_mfma_f32_16x16x32_bf16 v[96:99], v[188:191], v[204:207], v[96:99]
	v_mfma_f32_16x16x32_bf16 v[84:87], v[180:183], v[212:215], v[84:87]
	v_mfma_f32_16x16x32_bf16 v[80:83], v[188:191], v[212:215], v[80:83]
	v_mfma_f32_16x16x32_bf16 v[68:71], v[180:183], v[220:223], v[68:71]
	v_mfma_f32_16x16x32_bf16 v[64:67], v[188:191], v[220:223], v[64:67]
	s_barrier
	s_mov_b64 s[98:99], s[30:31]
	s_add_i32 s30, s55, s36
	s_mov_b32 m0, s30
	ds_read_b128 v[192:195], v158 offset:49152
	ds_read_b128 v[196:199], v158 offset:50176
	ds_read_b128 v[200:203], v158 offset:51200
	ds_read_b128 v[204:207], v158 offset:52224
	ds_read_b128 v[208:211], v158 offset:53248
	ds_read_b128 v[212:215], v158 offset:54272
	ds_read_b128 v[216:219], v158 offset:55296
	ds_read_b128 v[220:223], v158 offset:56320
	s_add_u32 s100, s28, 0x80
	s_addc_u32 s101, s29, 0
	global_load_lds_dwordx4 v130, s[100:101]
	s_add_i32 m0, s30, 0x2000
	s_add_u32 s28, s28, 0x80080
	s_addc_u32 s29, s29, 0
	s_add_i32 s30, s56, s36
	global_load_lds_dwordx4 v134, s[100:101]
	s_mov_b32 m0, s30
	s_nop 0
	global_load_lds_dwordx4 v130, s[28:29]
	s_add_i32 m0, s30, 0x2000
	s_nop 0
	global_load_lds_dwordx4 v134, s[28:29]
	s_mov_b32 m0, s40
	s_nop 0
	s_add_u32 s100, s98, 0xfff80080
	s_addc_u32 s101, s99, -1
	global_load_lds_dwordx4 v128, s[100:101]
	s_mov_b32 m0, s41
	s_nop 0
	global_load_lds_dwordx4 v132, s[100:101]
	s_waitcnt vmcnt(8)
	s_waitcnt lgkmcnt(0)
	s_barrier
	s_waitcnt lgkmcnt(0)
	v_mfma_f32_16x16x32_bf16 v[60:63], v[160:163], v[192:195], v[60:63]
	v_mfma_f32_16x16x32_bf16 v[56:59], v[168:171], v[192:195], v[56:59]
	v_mfma_f32_16x16x32_bf16 v[44:47], v[160:163], v[200:203], v[44:47]
	v_mfma_f32_16x16x32_bf16 v[40:43], v[168:171], v[200:203], v[40:43]
	v_mfma_f32_16x16x32_bf16 v[28:31], v[160:163], v[208:211], v[28:31]
	v_mfma_f32_16x16x32_bf16 v[24:27], v[168:171], v[208:211], v[24:27]
	v_mfma_f32_16x16x32_bf16 v[12:15], v[160:163], v[216:219], v[12:15]
	v_mfma_f32_16x16x32_bf16 v[8:11], v[168:171], v[216:219], v[8:11]
	v_mfma_f32_16x16x32_bf16 v[60:63], v[164:167], v[196:199], v[60:63]
	v_mfma_f32_16x16x32_bf16 v[56:59], v[172:175], v[196:199], v[56:59]
	v_mfma_f32_16x16x32_bf16 v[44:47], v[164:167], v[204:207], v[44:47]
	v_mfma_f32_16x16x32_bf16 v[40:43], v[172:175], v[204:207], v[40:43]
	v_mfma_f32_16x16x32_bf16 v[28:31], v[164:167], v[212:215], v[28:31]
	v_mfma_f32_16x16x32_bf16 v[24:27], v[172:175], v[212:215], v[24:27]
	v_mfma_f32_16x16x32_bf16 v[12:15], v[164:167], v[220:223], v[12:15]
	v_mfma_f32_16x16x32_bf16 v[8:11], v[172:175], v[220:223], v[8:11]
	v_mfma_f32_16x16x32_bf16 v[52:55], v[176:179], v[192:195], v[52:55]
	v_mfma_f32_16x16x32_bf16 v[48:51], v[184:187], v[192:195], v[48:51]
	v_mfma_f32_16x16x32_bf16 v[36:39], v[176:179], v[200:203], v[36:39]
	v_mfma_f32_16x16x32_bf16 v[32:35], v[184:187], v[200:203], v[32:35]
	v_mfma_f32_16x16x32_bf16 v[20:23], v[176:179], v[208:211], v[20:23]
	v_mfma_f32_16x16x32_bf16 v[16:19], v[184:187], v[208:211], v[16:19]
	v_mfma_f32_16x16x32_bf16 v[4:7], v[176:179], v[216:219], v[4:7]
	v_mfma_f32_16x16x32_bf16 v[0:3], v[184:187], v[216:219], v[0:3]
	v_mfma_f32_16x16x32_bf16 v[52:55], v[180:183], v[196:199], v[52:55]
	v_mfma_f32_16x16x32_bf16 v[48:51], v[188:191], v[196:199], v[48:51]
	v_mfma_f32_16x16x32_bf16 v[36:39], v[180:183], v[204:207], v[36:39]
	v_mfma_f32_16x16x32_bf16 v[32:35], v[188:191], v[204:207], v[32:35]
	v_mfma_f32_16x16x32_bf16 v[20:23], v[180:183], v[212:215], v[20:23]
	v_mfma_f32_16x16x32_bf16 v[16:19], v[188:191], v[212:215], v[16:19]
	v_mfma_f32_16x16x32_bf16 v[4:7], v[180:183], v[220:223], v[4:7]
	v_mfma_f32_16x16x32_bf16 v[0:3], v[188:191], v[220:223], v[0:3]
	s_barrier
	s_add_u32 s26, s26, 0x100
	s_addc_u32 s27, s27, 0
	s_add_u32 s52, s52, 0x100
	s_addc_u32 s53, s53, 0
	s_cmp_ge_u32 s54, s50
	s_mov_b32 s30, s54
	s_cbranch_scc0 .LBB0_1737

; #define PG8_STAGE(bufoff, gbase, voff) do { _Pragma("unroll") for (int _i = 0; _i < 2; ++_i) \
;         __builtin_amdgcn_global_load_lds((const unsigned*)((const char*)(gbase) + (voff)[_i]), (LAS unsigned*)(lds + (bufoff) + ldsw + _i * 8192), 16, 0, 0); } while (0)
; #define PG8_LDA(dst, b, h) do { _Pragma("unroll") for (int m = 0; m < 4; ++m) _Pragma("unroll") for (int k = 0; k < 2; ++k) dst[m][k] = *(const LAS bf16x8*)(lds + PG8_SA(b, h) + aoff + m * 2048 + k * 1024); } while (0)
; #define PG8_LDB(dst, b, h) do { _Pragma("unroll") for (int n = 0; n < 2; ++n) _Pragma("unroll") for (int k = 0; k < 2; ++k) dst[n][k] = *(const LAS bf16x8*)(lds + PG8_SB(b, h) + boff + n * 2048 + k * 1024); } while (0)
; #define PG8_WAIT_V(n) asm volatile("s_waitcnt vmcnt(" #n ")" ::: "memory")
; #define PG8_WAIT_L(n) asm volatile("s_waitcnt lgkmcnt(" #n ")" ::: "memory")
; #define PG8_BAR __builtin_amdgcn_s_barrier()
; __device__ __forceinline__ void gemm_phase(LAS unsigned char* lds, const Params& p, const bf16_t* gA, const bf16_t* gBt, const int gM, const int gN, const int gK, const int epi, const int perm, bf16_t* const Hp, const int goff, const float coef) {
;     ...
;         const bool has_next = S.next(ui + 1, nxt);
;         const char* nA = has_next ? (const char*)gA + (size_t)nxt.pm * tstep + (nxt.ks > 0 ? nxt.ks * ksl : 0) : cA; const char* nB = has_next ? (const char*)gBt + (size_t)nxt.pn * tstep + (nxt.ks > 0 ? nxt.ks * ksl : 0) : cB;
;         const int nt = cur.ks >= 0 ? ntf / 4 : ntf;
;         for (int t = 0; t < nt; t += 2) {
;             const bool last = (t == nt - 2);
;             const char* a1 = cA + (size_t)(t + 1) * kstep;
;             const char* a2 = last ? nA : cA + (size_t)(t + 2) * kstep; const char* b2 = last ? nB : cB + (size_t)(t + 2) * kstep;
;             const char* a3 = a2 + kstep; const char* b3 = b2 + kstep;
;             PG8_LDB(B0, 0, 0); PG8_LDB(B1, 0, 1); PG8_SCHED; PG8_LDA(At, 0, 0); PG8_STAGE(PG8_SA(1, 1), a1 + hstep, voffA);
;             PG8_WAIT_V(8); PG8_WAIT_L(0); PG8_BAR; PG8_MMA(0, 0, At, B0); PG8_MMA(0, 1, At, B1); PG8_BAR; PG8_SCHED;
;             PG8_LDA(At, 0, 1); PG8_STAGE(PG8_SB(0, 0), b2, voffB); PG8_STAGE(PG8_SB(0, 1), b2 + hstep, voffB); PG8_STAGE(PG8_SA(0, 0), a2, voffA);
;             PG8_WAIT_V(8); PG8_WAIT_L(0); PG8_BAR; PG8_MMA(1, 0, At, B0); PG8_MMA(1, 1, At, B1); PG8_BAR; PG8_SCHED;
.LBB0_1826:
	s_cmp_gt_i32 s6, -1
	s_cselect_b64 s[4:5], -1, 0
	s_and_b64 s[22:23], s[4:5], exec
	s_cselect_b32 s50, 22, 0x58
	s_add_i32 s51, s50, -2
	s_add_u32 s18, s18, 0x160080
	s_addc_u32 s19, s19, 0
	s_add_u32 s52, s20, 0x100
	s_addc_u32 s53, s21, 0
	s_mov_b32 s20, 0
	v_add_u32_e32 v222, 0x18000, v157
	v_add_u32_e32 v223, 0x1c000, v157
	ds_read_b128 v[144:147], v166
	ds_read_b128 v[148:151], v166 offset:1024
	ds_read_b128 v[152:155], v166 offset:2048
	ds_read_b128 v[170:173], v166 offset:3072
	ds_read_b128 v[174:177], v167
	ds_read_b128 v[178:181], v167 offset:1024
	ds_read_b128 v[182:185], v167 offset:2048
	ds_read_b128 v[186:189], v167 offset:3072
	s_add_i32 s54, s20, 2
	s_add_u32 s21, s18, 0xffea0080
	s_addc_u32 s22, s19, -1
	s_cmp_eq_u32 s51, s20
	s_cselect_b32 s20, s16, s52
	s_cselect_b32 s23, s15, s22
	s_cselect_b32 s22, s14, s21
	s_cselect_b32 s21, s17, s53
	s_add_i32 m0, s28, 0xc000
	ds_read_b128 v[190:193], v168
	ds_read_b128 v[194:197], v168 offset:1024
	ds_read_b128 v[198:201], v168 offset:2048
	ds_read_b128 v[202:205], v168 offset:3072
	ds_read_b128 v[206:209], v168 offset:4096
	ds_read_b128 v[210:213], v168 offset:5120
	ds_read_b128 v[214:217], v168 offset:6144
	ds_read_b128 v[218:221], v168 offset:7168
	global_load_lds_dwordx4 v136, s[18:19]
	s_add_i32 m0, s28, 0xe000
	s_nop 0
	global_load_lds_dwordx4 v138, s[18:19]
	s_waitcnt vmcnt(8)
	s_waitcnt lgkmcnt(0)
	s_barrier
	s_waitcnt lgkmcnt(0)
	v_mfma_f32_16x16x32_bf16 v[124:127], v[144:147], v[190:193], 0
	v_mfma_f32_16x16x32_bf16 v[120:123], v[152:155], v[190:193], 0
	v_mfma_f32_16x16x32_bf16 v[116:119], v[144:147], v[198:201], 0
	v_mfma_f32_16x16x32_bf16 v[112:115], v[152:155], v[198:201], 0
	v_mfma_f32_16x16x32_bf16 v[108:111], v[144:147], v[206:209], 0
	v_mfma_f32_16x16x32_bf16 v[104:107], v[152:155], v[206:209], 0
	v_mfma_f32_16x16x32_bf16 v[100:103], v[144:147], v[214:217], 0
	v_mfma_f32_16x16x32_bf16 v[96:99], v[152:155], v[214:217], 0
	v_mfma_f32_16x16x32_bf16 v[124:127], v[148:151], v[194:197], v[124:127]
	v_mfma_f32_16x16x32_bf16 v[120:123], v[170:173], v[194:197], v[120:123]
	v_mfma_f32_16x16x32_bf16 v[116:119], v[148:151], v[202:205], v[116:119]
	v_mfma_f32_16x16x32_bf16 v[112:115], v[170:173], v[202:205], v[112:115]
	v_mfma_f32_16x16x32_bf16 v[108:111], v[148:151], v[210:213], v[108:111]
	v_mfma_f32_16x16x32_bf16 v[104:107], v[170:173], v[210:213], v[104:107]
	v_mfma_f32_16x16x32_bf16 v[100:103], v[148:151], v[218:221], v[100:103]
	v_mfma_f32_16x16x32_bf16 v[96:99], v[170:173], v[218:221], v[96:99]
	v_mfma_f32_16x16x32_bf16 v[68:71], v[174:177], v[190:193], 0
	v_mfma_f32_16x16x32_bf16 v[60:63], v[182:185], v[190:193], 0
	v_mfma_f32_16x16x32_bf16 v[52:55], v[174:177], v[198:201], 0
	v_mfma_f32_16x16x32_bf16 v[48:51], v[182:185], v[198:201], 0
	v_mfma_f32_16x16x32_bf16 v[44:47], v[174:177], v[206:209], 0
	v_mfma_f32_16x16x32_bf16 v[40:43], v[182:185], v[206:209], 0
	v_mfma_f32_16x16x32_bf16 v[36:39], v[174:177], v[214:217], 0
	v_mfma_f32_16x16x32_bf16 v[32:35], v[182:185], v[214:217], 0
	v_mfma_f32_16x16x32_bf16 v[68:71], v[178:181], v[194:197], v[68:71]
	v_mfma_f32_16x16x32_bf16 v[60:63], v[186:189], v[194:197], v[60:63]
	v_mfma_f32_16x16x32_bf16 v[52:55], v[178:181], v[202:205], v[52:55]
	v_mfma_f32_16x16x32_bf16 v[48:51], v[186:189], v[202:205], v[48:51]
	v_mfma_f32_16x16x32_bf16 v[44:47], v[178:181], v[210:213], v[44:47]
	v_mfma_f32_16x16x32_bf16 v[40:43], v[186:189], v[210:213], v[40:43]
	v_mfma_f32_16x16x32_bf16 v[36:39], v[178:181], v[218:221], v[36:39]
	v_mfma_f32_16x16x32_bf16 v[32:35], v[186:189], v[218:221], v[32:35]
	s_barrier
	s_add_i32 s55, s42, s27
	s_mov_b32 m0, s55
	ds_read_b128 v[190:193], v168 offset:16384
	ds_read_b128 v[194:197], v168 offset:17408
	ds_read_b128 v[198:201], v168 offset:18432
	ds_read_b128 v[202:205], v168 offset:19456
	ds_read_b128 v[206:209], v168 offset:20480
	ds_read_b128 v[210:213], v168 offset:21504
	ds_read_b128 v[214:217], v168 offset:22528
	ds_read_b128 v[218:221], v168 offset:23552
	global_load_lds_dwordx4 v130, s[20:21]
	s_add_i32 m0, s55, 0x2000
	s_add_u32 s56, s20, 0x160000
	s_addc_u32 s57, s21, 0
	s_add_i32 s55, s43, s27
	global_load_lds_dwordx4 v134, s[20:21]
	s_mov_b32 m0, s55
	s_nop 0
	global_load_lds_dwordx4 v130, s[56:57]
	s_add_i32 m0, s55, 0x2000
	s_nop 0
	global_load_lds_dwordx4 v134, s[56:57]
	s_mov_b32 m0, s28
	s_nop 0
	global_load_lds_dwordx4 v128, s[22:23]
	s_mov_b32 m0, s29
	s_nop 0
	global_load_lds_dwordx4 v132, s[22:23]
	s_waitcnt vmcnt(8)
	s_waitcnt lgkmcnt(0)
	s_barrier
	s_waitcnt lgkmcnt(0)
	v_mfma_f32_16x16x32_bf16 v[92:95], v[144:147], v[190:193], 0
	v_mfma_f32_16x16x32_bf16 v[88:91], v[152:155], v[190:193], 0
	v_mfma_f32_16x16x32_bf16 v[84:87], v[144:147], v[198:201], 0
	v_mfma_f32_16x16x32_bf16 v[80:83], v[152:155], v[198:201], 0
	v_mfma_f32_16x16x32_bf16 v[76:79], v[144:147], v[206:209], 0
	v_mfma_f32_16x16x32_bf16 v[72:75], v[152:155], v[206:209], 0
	v_mfma_f32_16x16x32_bf16 v[64:67], v[144:147], v[214:217], 0
	v_mfma_f32_16x16x32_bf16 v[56:59], v[152:155], v[214:217], 0
	v_mfma_f32_16x16x32_bf16 v[92:95], v[148:151], v[194:197], v[92:95]
	v_mfma_f32_16x16x32_bf16 v[88:91], v[170:173], v[194:197], v[88:91]
	v_mfma_f32_16x16x32_bf16 v[84:87], v[148:151], v[202:205], v[84:87]
	v_mfma_f32_16x16x32_bf16 v[80:83], v[170:173], v[202:205], v[80:83]
	v_mfma_f32_16x16x32_bf16 v[76:79], v[148:151], v[210:213], v[76:79]
	v_mfma_f32_16x16x32_bf16 v[72:75], v[170:173], v[210:213], v[72:75]
	v_mfma_f32_16x16x32_bf16 v[64:67], v[148:151], v[218:221], v[64:67]
	v_mfma_f32_16x16x32_bf16 v[56:59], v[170:173], v[218:221], v[56:59]
	v_mfma_f32_16x16x32_bf16 v[28:31], v[174:177], v[190:193], 0
	v_mfma_f32_16x16x32_bf16 v[24:27], v[182:185], v[190:193], 0
	v_mfma_f32_16x16x32_bf16 v[20:23], v[174:177], v[198:201], 0
	v_mfma_f32_16x16x32_bf16 v[16:19], v[182:185], v[198:201], 0
	v_mfma_f32_16x16x32_bf16 v[12:15], v[174:177], v[206:209], 0
	v_mfma_f32_16x16x32_bf16 v[8:11], v[182:185], v[206:209], 0
	v_mfma_f32_16x16x32_bf16 v[4:7], v[174:177], v[214:217], 0
	v_mfma_f32_16x16x32_bf16 v[0:3], v[182:185], v[214:217], 0
	v_mfma_f32_16x16x32_bf16 v[28:31], v[178:181], v[194:197], v[28:31]
	v_mfma_f32_16x16x32_bf16 v[24:27], v[186:189], v[194:197], v[24:27]
	v_mfma_f32_16x16x32_bf16 v[20:23], v[178:181], v[202:205], v[20:23]
	v_mfma_f32_16x16x32_bf16 v[16:19], v[186:189], v[202:205], v[16:19]
	v_mfma_f32_16x16x32_bf16 v[12:15], v[178:181], v[210:213], v[12:15]
	v_mfma_f32_16x16x32_bf16 v[8:11], v[186:189], v[210:213], v[8:11]
	v_mfma_f32_16x16x32_bf16 v[4:7], v[178:181], v[218:221], v[4:7]
	v_mfma_f32_16x16x32_bf16 v[0:3], v[186:189], v[218:221], v[0:3]
	s_barrier
; #define PG8_STAGE(bufoff, gbase, voff) do { _Pragma("unroll") for (int _i = 0; _i < 2; ++_i) \
;         __builtin_amdgcn_global_load_lds((const unsigned*)((const char*)(gbase) + (voff)[_i]), (LAS unsigned*)(lds + (bufoff) + ldsw + _i * 8192), 16, 0, 0); } while (0)
; #define PG8_LDA(dst, b, h) do { _Pragma("unroll") for (int m = 0; m < 4; ++m) _Pragma("unroll") for (int k = 0; k < 2; ++k) dst[m][k] = *(const LAS bf16x8*)(lds + PG8_SA(b, h) + aoff + m * 2048 + k * 1024); } while (0)
; #define PG8_LDB(dst, b, h) do { _Pragma("unroll") for (int n = 0; n < 2; ++n) _Pragma("unroll") for (int k = 0; k < 2; ++k) dst[n][k] = *(const LAS bf16x8*)(lds + PG8_SB(b, h) + boff + n * 2048 + k * 1024); } while (0)
; #define PG8_MMA(ai, bj, At, Bt) do { __builtin_amdgcn_s_setprio(1); _Pragma("unroll") for (int m = 0; m < 4; ++m) _Pragma("unroll") for (int n = 0; n < 2; ++n) _Pragma("unroll") for (int k = 0; k < 2; ++k) \
;         acc[ai][bj][m][n] = __builtin_amdgcn_mfma_f32_16x16x32_bf16(Bt[n][k], At[m][k], acc[ai][bj][m][n], 0, 0, 0); __builtin_amdgcn_s_setprio(0); } while (0)
; #define PG8_WAIT_V(n) asm volatile("s_waitcnt vmcnt(" #n ")" ::: "memory")
; #define PG8_WAIT_L(n) asm volatile("s_waitcnt lgkmcnt(" #n ")" ::: "memory")
; #define PG8_BAR __builtin_amdgcn_s_barrier()
; #define PG8_SCHED __builtin_amdgcn_sched_barrier(0)
; __device__ __forceinline__ void gemm_phase(LAS unsigned char* lds, const Params& p, const bf16_t* gA, const bf16_t* gBt, const int gM, const int gN, const int gK, const int epi, const int perm, bf16_t* const Hp, const int goff, const float coef) {
;     ...
;             PG8_LDB(B0, 1, 0); PG8_LDB(B1, 1, 1); PG8_SCHED; PG8_LDA(At, 1, 0); PG8_STAGE(PG8_SA(0, 1), a2 + hstep, voffA);
;             PG8_WAIT_V(8); PG8_WAIT_L(0); PG8_BAR; PG8_MMA(0, 0, At, B0); PG8_MMA(0, 1, At, B1); PG8_BAR; PG8_SCHED;
;             PG8_LDA(At, 1, 1); PG8_STAGE(PG8_SB(1, 0), b3, voffB); PG8_STAGE(PG8_SB(1, 1), b3 + hstep, voffB); PG8_STAGE(PG8_SA(1, 0), a3, voffA);
;             PG8_WAIT_V(8); PG8_WAIT_L(0); PG8_BAR; PG8_MMA(1, 0, At, B0); PG8_MMA(1, 1, At, B1); PG8_BAR; PG8_SCHED;
;         }
	s_add_i32 s55, 0, 0x18000
	s_add_i32 s56, 0, 0x1c000
	ds_read_b128 v[144:147], v222
	ds_read_b128 v[148:151], v222 offset:1024
	ds_read_b128 v[152:155], v222 offset:2048
	ds_read_b128 v[170:173], v222 offset:3072
	ds_read_b128 v[174:177], v223
	ds_read_b128 v[178:181], v223 offset:1024
	ds_read_b128 v[182:185], v223 offset:2048
	ds_read_b128 v[186:189], v223 offset:3072
	s_add_u32 s22, s22, 0x160000
	s_addc_u32 s23, s23, 0
	s_mov_b32 m0, s30
	ds_read_b128 v[190:193], v168 offset:32768
	ds_read_b128 v[194:197], v168 offset:33792
	ds_read_b128 v[198:201], v168 offset:34816
	ds_read_b128 v[202:205], v168 offset:35840
	ds_read_b128 v[206:209], v168 offset:36864
	ds_read_b128 v[210:213], v168 offset:37888
	ds_read_b128 v[214:217], v168 offset:38912
	ds_read_b128 v[218:221], v168 offset:39936
	global_load_lds_dwordx4 v128, s[22:23]
	s_mov_b32 m0, s31
	s_nop 0
	global_load_lds_dwordx4 v132, s[22:23]
	s_waitcnt vmcnt(8)
	s_waitcnt lgkmcnt(0)
	s_barrier
	s_waitcnt lgkmcnt(0)
	v_mfma_f32_16x16x32_bf16 v[124:127], v[144:147], v[190:193], v[124:127]
	v_mfma_f32_16x16x32_bf16 v[120:123], v[152:155], v[190:193], v[120:123]
	v_mfma_f32_16x16x32_bf16 v[116:119], v[144:147], v[198:201], v[116:119]
	v_mfma_f32_16x16x32_bf16 v[112:115], v[152:155], v[198:201], v[112:115]
	v_mfma_f32_16x16x32_bf16 v[108:111], v[144:147], v[206:209], v[108:111]
	v_mfma_f32_16x16x32_bf16 v[104:107], v[152:155], v[206:209], v[104:107]
	v_mfma_f32_16x16x32_bf16 v[100:103], v[144:147], v[214:217], v[100:103]
	v_mfma_f32_16x16x32_bf16 v[96:99], v[152:155], v[214:217], v[96:99]
	v_mfma_f32_16x16x32_bf16 v[124:127], v[148:151], v[194:197], v[124:127]
	v_mfma_f32_16x16x32_bf16 v[120:123], v[170:173], v[194:197], v[120:123]
	v_mfma_f32_16x16x32_bf16 v[116:119], v[148:151], v[202:205], v[116:119]
	v_mfma_f32_16x16x32_bf16 v[112:115], v[170:173], v[202:205], v[112:115]
	v_mfma_f32_16x16x32_bf16 v[108:111], v[148:151], v[210:213], v[108:111]
	v_mfma_f32_16x16x32_bf16 v[104:107], v[170:173], v[210:213], v[104:107]
	v_mfma_f32_16x16x32_bf16 v[100:103], v[148:151], v[218:221], v[100:103]
	v_mfma_f32_16x16x32_bf16 v[96:99], v[170:173], v[218:221], v[96:99]
	v_mfma_f32_16x16x32_bf16 v[68:71], v[174:177], v[190:193], v[68:71]
	v_mfma_f32_16x16x32_bf16 v[60:63], v[182:185], v[190:193], v[60:63]
	v_mfma_f32_16x16x32_bf16 v[52:55], v[174:177], v[198:201], v[52:55]
	v_mfma_f32_16x16x32_bf16 v[48:51], v[182:185], v[198:201], v[48:51]
	v_mfma_f32_16x16x32_bf16 v[44:47], v[174:177], v[206:209], v[44:47]
	v_mfma_f32_16x16x32_bf16 v[40:43], v[182:185], v[206:209], v[40:43]
	v_mfma_f32_16x16x32_bf16 v[36:39], v[174:177], v[214:217], v[36:39]
	v_mfma_f32_16x16x32_bf16 v[32:35], v[182:185], v[214:217], v[32:35]
	v_mfma_f32_16x16x32_bf16 v[68:71], v[178:181], v[194:197], v[68:71]
	v_mfma_f32_16x16x32_bf16 v[60:63], v[186:189], v[194:197], v[60:63]
	v_mfma_f32_16x16x32_bf16 v[52:55], v[178:181], v[202:205], v[52:55]
	v_mfma_f32_16x16x32_bf16 v[48:51], v[186:189], v[202:205], v[48:51]
	v_mfma_f32_16x16x32_bf16 v[44:47], v[178:181], v[210:213], v[44:47]
	v_mfma_f32_16x16x32_bf16 v[40:43], v[186:189], v[210:213], v[40:43]
	v_mfma_f32_16x16x32_bf16 v[36:39], v[178:181], v[218:221], v[36:39]
	v_mfma_f32_16x16x32_bf16 v[32:35], v[186:189], v[218:221], v[32:35]
	s_barrier
	s_mov_b64 s[98:99], s[22:23]
	s_add_i32 s22, s55, s27
	s_mov_b32 m0, s22
	ds_read_b128 v[190:193], v168 offset:49152
	ds_read_b128 v[194:197], v168 offset:50176
	ds_read_b128 v[198:201], v168 offset:51200
	ds_read_b128 v[202:205], v168 offset:52224
	ds_read_b128 v[206:209], v168 offset:53248
	ds_read_b128 v[210:213], v168 offset:54272
	ds_read_b128 v[214:217], v168 offset:55296
	ds_read_b128 v[218:221], v168 offset:56320
	s_add_u32 s100, s20, 0x80
	s_addc_u32 s101, s21, 0
	global_load_lds_dwordx4 v130, s[100:101]
	s_add_i32 m0, s22, 0x2000
	s_add_u32 s20, s20, 0x160080
	s_addc_u32 s21, s21, 0
	s_add_i32 s22, s56, s27
	global_load_lds_dwordx4 v134, s[100:101]
	s_mov_b32 m0, s22
	s_nop 0
	global_load_lds_dwordx4 v130, s[20:21]
	s_add_i32 m0, s22, 0x2000
	s_nop 0
	global_load_lds_dwordx4 v134, s[20:21]
	s_mov_b32 m0, s36
	s_nop 0
	s_add_u32 s100, s98, 0xffea0080
	s_addc_u32 s101, s99, -1
	global_load_lds_dwordx4 v128, s[100:101]
	s_mov_b32 m0, s37
	s_nop 0
	global_load_lds_dwordx4 v132, s[100:101]
	s_waitcnt vmcnt(8)
	s_waitcnt lgkmcnt(0)
	s_barrier
	s_waitcnt lgkmcnt(0)
	v_mfma_f32_16x16x32_bf16 v[92:95], v[144:147], v[190:193], v[92:95]
	v_mfma_f32_16x16x32_bf16 v[88:91], v[152:155], v[190:193], v[88:91]
	v_mfma_f32_16x16x32_bf16 v[84:87], v[144:147], v[198:201], v[84:87]
	v_mfma_f32_16x16x32_bf16 v[80:83], v[152:155], v[198:201], v[80:83]
	v_mfma_f32_16x16x32_bf16 v[76:79], v[144:147], v[206:209], v[76:79]
	v_mfma_f32_16x16x32_bf16 v[72:75], v[152:155], v[206:209], v[72:75]
	v_mfma_f32_16x16x32_bf16 v[64:67], v[144:147], v[214:217], v[64:67]
	v_mfma_f32_16x16x32_bf16 v[56:59], v[152:155], v[214:217], v[56:59]
	v_mfma_f32_16x16x32_bf16 v[92:95], v[148:151], v[194:197], v[92:95]
	v_mfma_f32_16x16x32_bf16 v[88:91], v[170:173], v[194:197], v[88:91]
	v_mfma_f32_16x16x32_bf16 v[84:87], v[148:151], v[202:205], v[84:87]
	v_mfma_f32_16x16x32_bf16 v[80:83], v[170:173], v[202:205], v[80:83]
	v_mfma_f32_16x16x32_bf16 v[76:79], v[148:151], v[210:213], v[76:79]
	v_mfma_f32_16x16x32_bf16 v[72:75], v[170:173], v[210:213], v[72:75]
	v_mfma_f32_16x16x32_bf16 v[64:67], v[148:151], v[218:221], v[64:67]
	v_mfma_f32_16x16x32_bf16 v[56:59], v[170:173], v[218:221], v[56:59]
	v_mfma_f32_16x16x32_bf16 v[28:31], v[174:177], v[190:193], v[28:31]
	v_mfma_f32_16x16x32_bf16 v[24:27], v[182:185], v[190:193], v[24:27]
	v_mfma_f32_16x16x32_bf16 v[20:23], v[174:177], v[198:201], v[20:23]
	v_mfma_f32_16x16x32_bf16 v[16:19], v[182:185], v[198:201], v[16:19]
	v_mfma_f32_16x16x32_bf16 v[12:15], v[174:177], v[206:209], v[12:15]
	v_mfma_f32_16x16x32_bf16 v[8:11], v[182:185], v[206:209], v[8:11]
	v_mfma_f32_16x16x32_bf16 v[4:7], v[174:177], v[214:217], v[4:7]
	v_mfma_f32_16x16x32_bf16 v[0:3], v[182:185], v[214:217], v[0:3]
	v_mfma_f32_16x16x32_bf16 v[28:31], v[178:181], v[194:197], v[28:31]
	v_mfma_f32_16x16x32_bf16 v[24:27], v[186:189], v[194:197], v[24:27]
	v_mfma_f32_16x16x32_bf16 v[20:23], v[178:181], v[202:205], v[20:23]
	v_mfma_f32_16x16x32_bf16 v[16:19], v[186:189], v[202:205], v[16:19]
	v_mfma_f32_16x16x32_bf16 v[12:15], v[178:181], v[210:213], v[12:15]
	v_mfma_f32_16x16x32_bf16 v[8:11], v[186:189], v[210:213], v[8:11]
	v_mfma_f32_16x16x32_bf16 v[4:7], v[178:181], v[218:221], v[4:7]
	v_mfma_f32_16x16x32_bf16 v[0:3], v[186:189], v[218:221], v[0:3]
	s_barrier
	s_add_u32 s18, s18, 0x100
	s_addc_u32 s19, s19, 0
	s_add_u32 s52, s52, 0x100
	s_addc_u32 s53, s53, 0
	s_cmp_ge_u32 s54, s50
	s_mov_b64 s[98:99], s[20:21]
	s_mov_b32 s20, s54
	s_cbranch_scc1 .Lpeel_exit_5
; #define PG8_STAGE(bufoff, gbase, voff) do { _Pragma("unroll") for (int _i = 0; _i < 2; ++_i) \
;         __builtin_amdgcn_global_load_lds((const unsigned*)((const char*)(gbase) + (voff)[_i]), (LAS unsigned*)(lds + (bufoff) + ldsw + _i * 8192), 16, 0, 0); } while (0)
; #define PG8_LDA(dst, b, h) do { _Pragma("unroll") for (int m = 0; m < 4; ++m) _Pragma("unroll") for (int k = 0; k < 2; ++k) dst[m][k] = *(const LAS bf16x8*)(lds + PG8_SA(b, h) + aoff + m * 2048 + k * 1024); } while (0)
; #define PG8_LDB(dst, b, h) do { _Pragma("unroll") for (int n = 0; n < 2; ++n) _Pragma("unroll") for (int k = 0; k < 2; ++k) dst[n][k] = *(const LAS bf16x8*)(lds + PG8_SB(b, h) + boff + n * 2048 + k * 1024); } while (0)
; #define PG8_MMA(ai, bj, At, Bt) do { __builtin_amdgcn_s_setprio(1); _Pragma("unroll") for (int m = 0; m < 4; ++m) _Pragma("unroll") for (int n = 0; n < 2; ++n) _Pragma("unroll") for (int k = 0; k < 2; ++k) \
;         acc[ai][bj][m][n] = __builtin_amdgcn_mfma_f32_16x16x32_bf16(Bt[n][k], At[m][k], acc[ai][bj][m][n], 0, 0, 0); __builtin_amdgcn_s_setprio(0); } while (0)
; #define PG8_WAIT_V(n) asm volatile("s_waitcnt vmcnt(" #n ")" ::: "memory")
; #define PG8_WAIT_L(n) asm volatile("s_waitcnt lgkmcnt(" #n ")" ::: "memory")
; __device__ __forceinline__ void gemm_phase(LAS unsigned char* lds, const Params& p, const bf16_t* gA, const bf16_t* gBt, const int gM, const int gN, const int gK, const int epi, const int perm, bf16_t* const Hp, const int goff, const float coef) {
;     ...
;         for (int t = 0; t < nt; t += 2) {
;             const bool last = (t == nt - 2);
;             const char* a1 = cA + (size_t)(t + 1) * kstep;
;             const char* a2 = last ? nA : cA + (size_t)(t + 2) * kstep; const char* b2 = last ? nB : cB + (size_t)(t + 2) * kstep;
;             const char* a3 = a2 + kstep; const char* b3 = b2 + kstep;
;             PG8_LDB(B0, 0, 0); PG8_LDB(B1, 0, 1); PG8_SCHED; PG8_LDA(At, 0, 0); PG8_STAGE(PG8_SA(1, 1), a1 + hstep, voffA);
;             PG8_WAIT_V(8); PG8_WAIT_L(0); PG8_BAR; PG8_MMA(0, 0, At, B0); PG8_MMA(0, 1, At, B1); PG8_BAR; PG8_SCHED;
;             PG8_LDA(At, 0, 1); PG8_STAGE(PG8_SB(0, 0), b2, voffB); PG8_STAGE(PG8_SB(0, 1), b2 + hstep, voffB); PG8_STAGE(PG8_SA(0, 0), a2, voffA);
;             PG8_WAIT_V(8); PG8_WAIT_L(0); PG8_BAR; PG8_MMA(1, 0, At, B0); PG8_MMA(1, 1, At, B1); PG8_BAR; PG8_SCHED;
.LBB0_1827:
	ds_read_b128 v[144:147], v166
	ds_read_b128 v[148:151], v166 offset:1024
	ds_read_b128 v[152:155], v166 offset:2048
	ds_read_b128 v[170:173], v166 offset:3072
	ds_read_b128 v[174:177], v167
	ds_read_b128 v[178:181], v167 offset:1024
	ds_read_b128 v[182:185], v167 offset:2048
	ds_read_b128 v[186:189], v167 offset:3072
	s_add_i32 s54, s20, 2
	s_add_u32 s21, s18, 0xffea0080
	s_addc_u32 s22, s19, -1
	s_cmp_eq_u32 s51, s20
	s_cselect_b32 s20, s16, s52
	s_cselect_b32 s23, s15, s22
	s_cselect_b32 s22, s14, s21
	s_cselect_b32 s21, s17, s53
	s_add_i32 m0, s28, 0xc000
	ds_read_b128 v[190:193], v168
	ds_read_b128 v[194:197], v168 offset:1024
	ds_read_b128 v[198:201], v168 offset:2048
	ds_read_b128 v[202:205], v168 offset:3072
	ds_read_b128 v[206:209], v168 offset:4096
	ds_read_b128 v[210:213], v168 offset:5120
	ds_read_b128 v[214:217], v168 offset:6144
	ds_read_b128 v[218:221], v168 offset:7168
	global_load_lds_dwordx4 v136, s[18:19]
	s_add_i32 m0, s28, 0xe000
	s_nop 0
	global_load_lds_dwordx4 v138, s[18:19]
	s_waitcnt vmcnt(8)
	s_waitcnt lgkmcnt(0)
	s_barrier
	s_waitcnt lgkmcnt(0)
	v_mfma_f32_16x16x32_bf16 v[124:127], v[144:147], v[190:193], v[124:127]
	v_mfma_f32_16x16x32_bf16 v[120:123], v[152:155], v[190:193], v[120:123]
	v_mfma_f32_16x16x32_bf16 v[116:119], v[144:147], v[198:201], v[116:119]
	v_mfma_f32_16x16x32_bf16 v[112:115], v[152:155], v[198:201], v[112:115]
	v_mfma_f32_16x16x32_bf16 v[108:111], v[144:147], v[206:209], v[108:111]
	v_mfma_f32_16x16x32_bf16 v[104:107], v[152:155], v[206:209], v[104:107]
	v_mfma_f32_16x16x32_bf16 v[100:103], v[144:147], v[214:217], v[100:103]
	v_mfma_f32_16x16x32_bf16 v[96:99], v[152:155], v[214:217], v[96:99]
	v_mfma_f32_16x16x32_bf16 v[124:127], v[148:151], v[194:197], v[124:127]
	v_mfma_f32_16x16x32_bf16 v[120:123], v[170:173], v[194:197], v[120:123]
	v_mfma_f32_16x16x32_bf16 v[116:119], v[148:151], v[202:205], v[116:119]
	v_mfma_f32_16x16x32_bf16 v[112:115], v[170:173], v[202:205], v[112:115]
	v_mfma_f32_16x16x32_bf16 v[108:111], v[148:151], v[210:213], v[108:111]
	v_mfma_f32_16x16x32_bf16 v[104:107], v[170:173], v[210:213], v[104:107]
	v_mfma_f32_16x16x32_bf16 v[100:103], v[148:151], v[218:221], v[100:103]
	v_mfma_f32_16x16x32_bf16 v[96:99], v[170:173], v[218:221], v[96:99]
	v_mfma_f32_16x16x32_bf16 v[68:71], v[174:177], v[190:193], v[68:71]
	v_mfma_f32_16x16x32_bf16 v[60:63], v[182:185], v[190:193], v[60:63]
	v_mfma_f32_16x16x32_bf16 v[52:55], v[174:177], v[198:201], v[52:55]
	v_mfma_f32_16x16x32_bf16 v[48:51], v[182:185], v[198:201], v[48:51]
	v_mfma_f32_16x16x32_bf16 v[44:47], v[174:177], v[206:209], v[44:47]
	v_mfma_f32_16x16x32_bf16 v[40:43], v[182:185], v[206:209], v[40:43]
	v_mfma_f32_16x16x32_bf16 v[36:39], v[174:177], v[214:217], v[36:39]
	v_mfma_f32_16x16x32_bf16 v[32:35], v[182:185], v[214:217], v[32:35]
	v_mfma_f32_16x16x32_bf16 v[68:71], v[178:181], v[194:197], v[68:71]
	v_mfma_f32_16x16x32_bf16 v[60:63], v[186:189], v[194:197], v[60:63]
	v_mfma_f32_16x16x32_bf16 v[52:55], v[178:181], v[202:205], v[52:55]
	v_mfma_f32_16x16x32_bf16 v[48:51], v[186:189], v[202:205], v[48:51]
	v_mfma_f32_16x16x32_bf16 v[44:47], v[178:181], v[210:213], v[44:47]
	v_mfma_f32_16x16x32_bf16 v[40:43], v[186:189], v[210:213], v[40:43]
	v_mfma_f32_16x16x32_bf16 v[36:39], v[178:181], v[218:221], v[36:39]
	v_mfma_f32_16x16x32_bf16 v[32:35], v[186:189], v[218:221], v[32:35]
	s_barrier
	s_add_i32 s55, s42, s27
	s_mov_b32 m0, s55
	ds_read_b128 v[190:193], v168 offset:16384
	ds_read_b128 v[194:197], v168 offset:17408
	ds_read_b128 v[198:201], v168 offset:18432
	ds_read_b128 v[202:205], v168 offset:19456
	ds_read_b128 v[206:209], v168 offset:20480
	ds_read_b128 v[210:213], v168 offset:21504
	ds_read_b128 v[214:217], v168 offset:22528
	ds_read_b128 v[218:221], v168 offset:23552
	global_load_lds_dwordx4 v130, s[20:21]
	s_add_i32 m0, s55, 0x2000
	s_add_u32 s56, s20, 0x160000
	s_addc_u32 s57, s21, 0
	s_add_i32 s55, s43, s27
	global_load_lds_dwordx4 v134, s[20:21]
	s_mov_b32 m0, s55
	s_nop 0
	global_load_lds_dwordx4 v130, s[56:57]
	s_add_i32 m0, s55, 0x2000
	s_nop 0
	global_load_lds_dwordx4 v134, s[56:57]
	s_mov_b32 m0, s28
	s_nop 0
	global_load_lds_dwordx4 v128, s[22:23]
	s_mov_b32 m0, s29
	s_nop 0
	global_load_lds_dwordx4 v132, s[22:23]
	s_waitcnt vmcnt(8)
	s_waitcnt lgkmcnt(0)
	s_barrier
	s_waitcnt lgkmcnt(0)
	v_mfma_f32_16x16x32_bf16 v[92:95], v[144:147], v[190:193], v[92:95]
	v_mfma_f32_16x16x32_bf16 v[88:91], v[152:155], v[190:193], v[88:91]
	v_mfma_f32_16x16x32_bf16 v[84:87], v[144:147], v[198:201], v[84:87]
	v_mfma_f32_16x16x32_bf16 v[80:83], v[152:155], v[198:201], v[80:83]
	v_mfma_f32_16x16x32_bf16 v[76:79], v[144:147], v[206:209], v[76:79]
	v_mfma_f32_16x16x32_bf16 v[72:75], v[152:155], v[206:209], v[72:75]
	v_mfma_f32_16x16x32_bf16 v[64:67], v[144:147], v[214:217], v[64:67]
	v_mfma_f32_16x16x32_bf16 v[56:59], v[152:155], v[214:217], v[56:59]
	v_mfma_f32_16x16x32_bf16 v[92:95], v[148:151], v[194:197], v[92:95]
	v_mfma_f32_16x16x32_bf16 v[88:91], v[170:173], v[194:197], v[88:91]
	v_mfma_f32_16x16x32_bf16 v[84:87], v[148:151], v[202:205], v[84:87]
	v_mfma_f32_16x16x32_bf16 v[80:83], v[170:173], v[202:205], v[80:83]
	v_mfma_f32_16x16x32_bf16 v[76:79], v[148:151], v[210:213], v[76:79]
	v_mfma_f32_16x16x32_bf16 v[72:75], v[170:173], v[210:213], v[72:75]
	v_mfma_f32_16x16x32_bf16 v[64:67], v[148:151], v[218:221], v[64:67]
	v_mfma_f32_16x16x32_bf16 v[56:59], v[170:173], v[218:221], v[56:59]
	v_mfma_f32_16x16x32_bf16 v[28:31], v[174:177], v[190:193], v[28:31]
	v_mfma_f32_16x16x32_bf16 v[24:27], v[182:185], v[190:193], v[24:27]
	v_mfma_f32_16x16x32_bf16 v[20:23], v[174:177], v[198:201], v[20:23]
	v_mfma_f32_16x16x32_bf16 v[16:19], v[182:185], v[198:201], v[16:19]
	v_mfma_f32_16x16x32_bf16 v[12:15], v[174:177], v[206:209], v[12:15]
	v_mfma_f32_16x16x32_bf16 v[8:11], v[182:185], v[206:209], v[8:11]
	v_mfma_f32_16x16x32_bf16 v[4:7], v[174:177], v[214:217], v[4:7]
	v_mfma_f32_16x16x32_bf16 v[0:3], v[182:185], v[214:217], v[0:3]
	v_mfma_f32_16x16x32_bf16 v[28:31], v[178:181], v[194:197], v[28:31]
	v_mfma_f32_16x16x32_bf16 v[24:27], v[186:189], v[194:197], v[24:27]
	v_mfma_f32_16x16x32_bf16 v[20:23], v[178:181], v[202:205], v[20:23]
	v_mfma_f32_16x16x32_bf16 v[16:19], v[186:189], v[202:205], v[16:19]
	v_mfma_f32_16x16x32_bf16 v[12:15], v[178:181], v[210:213], v[12:15]
	v_mfma_f32_16x16x32_bf16 v[8:11], v[186:189], v[210:213], v[8:11]
	v_mfma_f32_16x16x32_bf16 v[4:7], v[178:181], v[218:221], v[4:7]
	v_mfma_f32_16x16x32_bf16 v[0:3], v[186:189], v[218:221], v[0:3]
	s_barrier
; #define PG8_STAGE(bufoff, gbase, voff) do { _Pragma("unroll") for (int _i = 0; _i < 2; ++_i) \
;         __builtin_amdgcn_global_load_lds((const unsigned*)((const char*)(gbase) + (voff)[_i]), (LAS unsigned*)(lds + (bufoff) + ldsw + _i * 8192), 16, 0, 0); } while (0)
; #define PG8_LDA(dst, b, h) do { _Pragma("unroll") for (int m = 0; m < 4; ++m) _Pragma("unroll") for (int k = 0; k < 2; ++k) dst[m][k] = *(const LAS bf16x8*)(lds + PG8_SA(b, h) + aoff + m * 2048 + k * 1024); } while (0)
; #define PG8_LDB(dst, b, h) do { _Pragma("unroll") for (int n = 0; n < 2; ++n) _Pragma("unroll") for (int k = 0; k < 2; ++k) dst[n][k] = *(const LAS bf16x8*)(lds + PG8_SB(b, h) + boff + n * 2048 + k * 1024); } while (0)
; #define PG8_MMA(ai, bj, At, Bt) do { __builtin_amdgcn_s_setprio(1); _Pragma("unroll") for (int m = 0; m < 4; ++m) _Pragma("unroll") for (int n = 0; n < 2; ++n) _Pragma("unroll") for (int k = 0; k < 2; ++k) \
;         acc[ai][bj][m][n] = __builtin_amdgcn_mfma_f32_16x16x32_bf16(Bt[n][k], At[m][k], acc[ai][bj][m][n], 0, 0, 0); __builtin_amdgcn_s_setprio(0); } while (0)
; #define PG8_WAIT_V(n) asm volatile("s_waitcnt vmcnt(" #n ")" ::: "memory")
; #define PG8_WAIT_L(n) asm volatile("s_waitcnt lgkmcnt(" #n ")" ::: "memory")
; #define PG8_BAR __builtin_amdgcn_s_barrier()
; #define PG8_SCHED __builtin_amdgcn_sched_barrier(0)
; __device__ __forceinline__ void gemm_phase(LAS unsigned char* lds, const Params& p, const bf16_t* gA, const bf16_t* gBt, const int gM, const int gN, const int gK, const int epi, const int perm, bf16_t* const Hp, const int goff, const float coef) {
;     ...
;             PG8_LDB(B0, 1, 0); PG8_LDB(B1, 1, 1); PG8_SCHED; PG8_LDA(At, 1, 0); PG8_STAGE(PG8_SA(0, 1), a2 + hstep, voffA);
;             PG8_WAIT_V(8); PG8_WAIT_L(0); PG8_BAR; PG8_MMA(0, 0, At, B0); PG8_MMA(0, 1, At, B1); PG8_BAR; PG8_SCHED;
;             PG8_LDA(At, 1, 1); PG8_STAGE(PG8_SB(1, 0), b3, voffB); PG8_STAGE(PG8_SB(1, 1), b3 + hstep, voffB); PG8_STAGE(PG8_SA(1, 0), a3, voffA);
;             PG8_WAIT_V(8); PG8_WAIT_L(0); PG8_BAR; PG8_MMA(1, 0, At, B0); PG8_MMA(1, 1, At, B1); PG8_BAR; PG8_SCHED;
;         }
	s_add_i32 s55, 0, 0x18000
	s_add_i32 s56, 0, 0x1c000
	ds_read_b128 v[144:147], v222
	ds_read_b128 v[148:151], v222 offset:1024
	ds_read_b128 v[152:155], v222 offset:2048
	ds_read_b128 v[170:173], v222 offset:3072
	ds_read_b128 v[174:177], v223
	ds_read_b128 v[178:181], v223 offset:1024
	ds_read_b128 v[182:185], v223 offset:2048
	ds_read_b128 v[186:189], v223 offset:3072
	s_add_u32 s22, s22, 0x160000
	s_addc_u32 s23, s23, 0
	s_mov_b32 m0, s30
	ds_read_b128 v[190:193], v168 offset:32768
	ds_read_b128 v[194:197], v168 offset:33792
	ds_read_b128 v[198:201], v168 offset:34816
	ds_read_b128 v[202:205], v168 offset:35840
	ds_read_b128 v[206:209], v168 offset:36864
	ds_read_b128 v[210:213], v168 offset:37888
	ds_read_b128 v[214:217], v168 offset:38912
	ds_read_b128 v[218:221], v168 offset:39936
	global_load_lds_dwordx4 v128, s[22:23]
	s_mov_b32 m0, s31
	s_nop 0
	global_load_lds_dwordx4 v132, s[22:23]
	s_waitcnt vmcnt(8)
	s_waitcnt lgkmcnt(0)
	s_barrier
	s_waitcnt lgkmcnt(0)
	v_mfma_f32_16x16x32_bf16 v[124:127], v[144:147], v[190:193], v[124:127]
	v_mfma_f32_16x16x32_bf16 v[120:123], v[152:155], v[190:193], v[120:123]
	v_mfma_f32_16x16x32_bf16 v[116:119], v[144:147], v[198:201], v[116:119]
	v_mfma_f32_16x16x32_bf16 v[112:115], v[152:155], v[198:201], v[112:115]
	v_mfma_f32_16x16x32_bf16 v[108:111], v[144:147], v[206:209], v[108:111]
	v_mfma_f32_16x16x32_bf16 v[104:107], v[152:155], v[206:209], v[104:107]
	v_mfma_f32_16x16x32_bf16 v[100:103], v[144:147], v[214:217], v[100:103]
	v_mfma_f32_16x16x32_bf16 v[96:99], v[152:155], v[214:217], v[96:99]
	v_mfma_f32_16x16x32_bf16 v[124:127], v[148:151], v[194:197], v[124:127]
	v_mfma_f32_16x16x32_bf16 v[120:123], v[170:173], v[194:197], v[120:123]
	v_mfma_f32_16x16x32_bf16 v[116:119], v[148:151], v[202:205], v[116:119]
	v_mfma_f32_16x16x32_bf16 v[112:115], v[170:173], v[202:205], v[112:115]
	v_mfma_f32_16x16x32_bf16 v[108:111], v[148:151], v[210:213], v[108:111]
	v_mfma_f32_16x16x32_bf16 v[104:107], v[170:173], v[210:213], v[104:107]
	v_mfma_f32_16x16x32_bf16 v[100:103], v[148:151], v[218:221], v[100:103]
	v_mfma_f32_16x16x32_bf16 v[96:99], v[170:173], v[218:221], v[96:99]
	v_mfma_f32_16x16x32_bf16 v[68:71], v[174:177], v[190:193], v[68:71]
	v_mfma_f32_16x16x32_bf16 v[60:63], v[182:185], v[190:193], v[60:63]
	v_mfma_f32_16x16x32_bf16 v[52:55], v[174:177], v[198:201], v[52:55]
	v_mfma_f32_16x16x32_bf16 v[48:51], v[182:185], v[198:201], v[48:51]
	v_mfma_f32_16x16x32_bf16 v[44:47], v[174:177], v[206:209], v[44:47]
	v_mfma_f32_16x16x32_bf16 v[40:43], v[182:185], v[206:209], v[40:43]
	v_mfma_f32_16x16x32_bf16 v[36:39], v[174:177], v[214:217], v[36:39]
	v_mfma_f32_16x16x32_bf16 v[32:35], v[182:185], v[214:217], v[32:35]
	v_mfma_f32_16x16x32_bf16 v[68:71], v[178:181], v[194:197], v[68:71]
	v_mfma_f32_16x16x32_bf16 v[60:63], v[186:189], v[194:197], v[60:63]
	v_mfma_f32_16x16x32_bf16 v[52:55], v[178:181], v[202:205], v[52:55]
	v_mfma_f32_16x16x32_bf16 v[48:51], v[186:189], v[202:205], v[48:51]
	v_mfma_f32_16x16x32_bf16 v[44:47], v[178:181], v[210:213], v[44:47]
	v_mfma_f32_16x16x32_bf16 v[40:43], v[186:189], v[210:213], v[40:43]
	v_mfma_f32_16x16x32_bf16 v[36:39], v[178:181], v[218:221], v[36:39]
	v_mfma_f32_16x16x32_bf16 v[32:35], v[186:189], v[218:221], v[32:35]
	s_barrier
	s_mov_b64 s[98:99], s[22:23]
	s_add_i32 s22, s55, s27
	s_mov_b32 m0, s22
	ds_read_b128 v[190:193], v168 offset:49152
	ds_read_b128 v[194:197], v168 offset:50176
	ds_read_b128 v[198:201], v168 offset:51200
	ds_read_b128 v[202:205], v168 offset:52224
	ds_read_b128 v[206:209], v168 offset:53248
	ds_read_b128 v[210:213], v168 offset:54272
	ds_read_b128 v[214:217], v168 offset:55296
	ds_read_b128 v[218:221], v168 offset:56320
	s_add_u32 s100, s20, 0x80
	s_addc_u32 s101, s21, 0
	global_load_lds_dwordx4 v130, s[100:101]
	s_add_i32 m0, s22, 0x2000
	s_add_u32 s20, s20, 0x160080
	s_addc_u32 s21, s21, 0
	s_add_i32 s22, s56, s27
	global_load_lds_dwordx4 v134, s[100:101]
	s_mov_b32 m0, s22
	s_nop 0
	global_load_lds_dwordx4 v130, s[20:21]
	s_add_i32 m0, s22, 0x2000
	s_nop 0
	global_load_lds_dwordx4 v134, s[20:21]
	s_mov_b32 m0, s36
	s_nop 0
	s_add_u32 s100, s98, 0xffea0080
	s_addc_u32 s101, s99, -1
	global_load_lds_dwordx4 v128, s[100:101]
	s_mov_b32 m0, s37
	s_nop 0
	global_load_lds_dwordx4 v132, s[100:101]
	s_waitcnt vmcnt(8)
	s_waitcnt lgkmcnt(0)
	s_barrier
	s_waitcnt lgkmcnt(0)
	v_mfma_f32_16x16x32_bf16 v[92:95], v[144:147], v[190:193], v[92:95]
	v_mfma_f32_16x16x32_bf16 v[88:91], v[152:155], v[190:193], v[88:91]
	v_mfma_f32_16x16x32_bf16 v[84:87], v[144:147], v[198:201], v[84:87]
	v_mfma_f32_16x16x32_bf16 v[80:83], v[152:155], v[198:201], v[80:83]
	v_mfma_f32_16x16x32_bf16 v[76:79], v[144:147], v[206:209], v[76:79]
	v_mfma_f32_16x16x32_bf16 v[72:75], v[152:155], v[206:209], v[72:75]
	v_mfma_f32_16x16x32_bf16 v[64:67], v[144:147], v[214:217], v[64:67]
	v_mfma_f32_16x16x32_bf16 v[56:59], v[152:155], v[214:217], v[56:59]
	v_mfma_f32_16x16x32_bf16 v[92:95], v[148:151], v[194:197], v[92:95]
	v_mfma_f32_16x16x32_bf16 v[88:91], v[170:173], v[194:197], v[88:91]
	v_mfma_f32_16x16x32_bf16 v[84:87], v[148:151], v[202:205], v[84:87]
	v_mfma_f32_16x16x32_bf16 v[80:83], v[170:173], v[202:205], v[80:83]
	v_mfma_f32_16x16x32_bf16 v[76:79], v[148:151], v[210:213], v[76:79]
	v_mfma_f32_16x16x32_bf16 v[72:75], v[170:173], v[210:213], v[72:75]
	v_mfma_f32_16x16x32_bf16 v[64:67], v[148:151], v[218:221], v[64:67]
	v_mfma_f32_16x16x32_bf16 v[56:59], v[170:173], v[218:221], v[56:59]
	v_mfma_f32_16x16x32_bf16 v[28:31], v[174:177], v[190:193], v[28:31]
	v_mfma_f32_16x16x32_bf16 v[24:27], v[182:185], v[190:193], v[24:27]
	v_mfma_f32_16x16x32_bf16 v[20:23], v[174:177], v[198:201], v[20:23]
	v_mfma_f32_16x16x32_bf16 v[16:19], v[182:185], v[198:201], v[16:19]
	v_mfma_f32_16x16x32_bf16 v[12:15], v[174:177], v[206:209], v[12:15]
	v_mfma_f32_16x16x32_bf16 v[8:11], v[182:185], v[206:209], v[8:11]
	v_mfma_f32_16x16x32_bf16 v[4:7], v[174:177], v[214:217], v[4:7]
	v_mfma_f32_16x16x32_bf16 v[0:3], v[182:185], v[214:217], v[0:3]
	v_mfma_f32_16x16x32_bf16 v[28:31], v[178:181], v[194:197], v[28:31]
	v_mfma_f32_16x16x32_bf16 v[24:27], v[186:189], v[194:197], v[24:27]
	v_mfma_f32_16x16x32_bf16 v[20:23], v[178:181], v[202:205], v[20:23]
	v_mfma_f32_16x16x32_bf16 v[16:19], v[186:189], v[202:205], v[16:19]
	v_mfma_f32_16x16x32_bf16 v[12:15], v[178:181], v[210:213], v[12:15]
	v_mfma_f32_16x16x32_bf16 v[8:11], v[186:189], v[210:213], v[8:11]
	v_mfma_f32_16x16x32_bf16 v[4:7], v[178:181], v[218:221], v[4:7]
	v_mfma_f32_16x16x32_bf16 v[0:3], v[186:189], v[218:221], v[0:3]
	s_barrier
	s_add_u32 s18, s18, 0x100
	s_addc_u32 s19, s19, 0
	s_add_u32 s52, s52, 0x100
	s_addc_u32 s53, s53, 0
	s_cmp_ge_u32 s54, s50
	s_mov_b64 s[98:99], s[20:21]
	s_mov_b32 s20, s54
	s_cbranch_scc0 .LBB0_1827
